# LRU: hoisted constants + double-buffered uc LDS tile (one barrier per tile instead of two)
# speedup vs baseline: 1.0049x; 1.0041x over previous
; __device__ __forceinline__ void lru_tile(const Params& P, int chunk, int head, int pass, char* smem_raw) {
;     ...
;   const int tid = VTID, lane = tid & 63, wid = tid >> 6;
;   const int q = tid >> 6, ch = tid & 63;
;   const int row0 = chunk * 128;
;   int seq_lo, seq_hi;
;   if (chunk < 256) { seq_lo = (chunk >> 6) << 13; seq_hi = seq_lo + 8192; }
;   else { const int b = (chunk - 256) >> 1; seq_lo = N_X + b * 256; seq_hi = seq_lo + 256; }
;   const int gch = head * 64 + ch;
;   const float* hfbuf = reinterpret_cast<const float*>(P.hy);
;   float* hfw = reinterpret_cast<float*>(P.hy);
;   {
;     const float w0 = P.conv_w[gch], w1 = P.conv_w[512 + gch], w2 = P.conv_w[1024 + gch], w3 = P.conv_w[1536 + gch];
;     const float cb = P.conv_b[gch];
;     const u16* zu = P.zq + gch;
.LBB0_287:
	v_readlane_b32 s0, v252, 0
	v_readlane_b32 s1, v252, 1
	v_readfirstlane_b32 s68, v153
	s_nop 3
	s_sub_u32 s0, s0, 0x170
	s_subb_u32 s1, s1, 0
	s_load_dwordx2 s[10:11], s[0:1], 0x148
	s_load_dwordx2 s[12:13], s[0:1], 0x158
	s_load_dwordx2 s[18:19], s[0:1], 0x130
	s_load_dwordx2 s[20:21], s[0:1], 0x128
	s_load_dwordx4 s[24:27], s[0:1], 0x70
	s_load_dwordx2 s[28:29], s[0:1], 0x88
	s_load_dwordx2 s[30:31], s[0:1], 0x98
	s_load_dwordx2 s[36:37], s[0:1], 0xa0
	s_lshl_b32 s4, s2, 1
	s_add_u32 s68, s4, s68
	s_mov_b32 s69, 0
	s_mov_b32 s70, 4
	s_cmp_lt_u32 s68, 64
	s_cselect_b32 s70, 5, 4
	s_mov_b32 s72, 0xffff0000
	s_mov_b32 s73, -1
	s_mov_b32 s74, 0
	s_mov_b32 s75, -1
	s_mov_b32 s76, 0
	s_mov_b32 s77, 0xffff0000
	s_mov_b32 s78, -1
	s_mov_b32 s79, 0x0000ffff
	s_mov_b32 s80, -1
	s_mov_b32 s81, 0
	s_mov_b32 s82, 0x0000ffff
	s_mov_b32 s83, 0
	v_and_b32_e32 v138, 63, v152
	v_lshrrev_b32_e32 v139, 4, v138
	v_and_b32_e32 v140, 15, v138
	v_bfe_u32 v141, v152, 6, 2
	v_lshl_add_u32 v255, v141, 4, v140
	v_mul_u32_u24_e32 v253, 0x12000, v153
	v_add_u32_e32 v253, 16, v253
	v_mul_u32_u24_e32 v134, 0x18000, v139
	v_lshl_add_u32 v134, v255, 1, v134
	v_lshlrev_b32_e32 v237, 16, v139
	v_lshl_add_u32 v237, v255, 1, v237
	v_lshlrev_b32_e32 v250, 3, v255
	v_lshlrev_b32_e32 v251, 7, v255
	v_lshl_add_u32 v251, v139, 4, v251
	v_lshrrev_b32_e32 v254, 3, v140
	v_lshl_add_u32 v254, v141, 1, v254
	v_lshlrev_b32_e32 v202, 1, v139
	v_xor_b32_e32 v89, v254, v202
	v_xor_b32_e32 v130, 1, v89
	v_and_b32_e32 v203, 7, v140
	v_lshl_add_u32 v202, v139, 12, v253
	v_lshl_add_u32 v202, v203, 1, v202
	v_lshl_add_u32 v89, v89, 4, v202
	v_lshl_add_u32 v130, v130, 4, v202
	v_lshrrev_b32_e32 v202, 2, v140
	v_and_b32_e32 v203, 3, v140
	v_lshl_add_u32 v254, v202, 5, v203
	v_lshl_add_u32 v254, v254, 7, v253
	v_lshrrev_b32_e32 v203, 1, v203
	v_lshl_add_u32 v202, v202, 1, v203
	v_xor_b32_e32 v202, v139, v202
	v_lshl_add_u32 v131, v202, 4, v254
	v_xor_b32_e32 v202, 4, v202
	v_lshl_add_u32 v133, v202, 4, v254
	v_cmp_eq_u32_e32 vcc, 0, v139
	s_mov_b64 s[84:85], vcc
	v_cmp_eq_u32_e32 vcc, 3, v139
	s_mov_b64 s[86:87], vcc
	s_waitcnt lgkmcnt(0)
; __device__ __forceinline__ float bf2f(u16 h) { return __uint_as_float(((unsigned)h) << 16); }
; __device__ __forceinline__ void lru_tile(const Params& P, int chunk, int head, int pass, char* smem_raw) {
;     ...
;   const int q = tid >> 6, ch = tid & 63;
;   const int row0 = chunk * 128;
;   int seq_lo, seq_hi;
;   if (chunk < 256) { seq_lo = (chunk >> 6) << 13; seq_hi = seq_lo + 8192; }
;   else { const int b = (chunk - 256) >> 1; seq_lo = N_X + b * 256; seq_hi = seq_lo + 256; }
;   const int gch = head * 64 + ch;
;   const float* hfbuf = reinterpret_cast<const float*>(P.hy);
;   float* hfw = reinterpret_cast<float*>(P.hy);
;   {
;     const float w0 = P.conv_w[gch], w1 = P.conv_w[512 + gch], w2 = P.conv_w[1024 + gch], w3 = P.conv_w[1536 + gch];
;     const float cb = P.conv_b[gch];
;     const u16* zu = P.zq + gch;
;     const int r = row0 + q * 32;
;     float uv[35];
; #pragma unroll
;     for (int i = 0; i < 35; ++i) {
;       const int rr = r - 2 + i;
;       uv[i] = (rr >= seq_lo && rr < seq_hi) ? bf2f(zu[(long)rr * 1536]) : 0.f;
;     ...
;     float ba[4], bi[4], c8[4];
; #pragma unroll
;     for (int tc = 0; tc < 4; ++tc) {
;       const int cidx = d * 512 + head * 64 + 16 * tc + (lane & 15);
;       ba[tc] = P.b_a[cidx] * -1.4426950408889634f; bi[tc] = P.b_i[cidx] * -1.4426950408889634f;
;       const float nl = -P.lam[cidx];
;       const float e_ = __expf(nl);
;       const float sp = (nl > 20.f) ? nl
;                      : (e_ < 0.03f ? e_ * (1.f - e_ * (0.5f - e_ * (0.33333334f - 0.25f * e_))) : __logf(1.f + e_));
;       c8[tc] = 8.f * 1.4426950408889634f * sp;
;     }
	s_and_b32 s56, s68, 7
	s_lshl_b32 s56, s56, 6
	s_lshr_b32 s59, s68, 3
	s_cmp_lt_u32 s59, 256
	s_cselect_b32 s60, 63, 1
	s_and_b32 s57, s59, s60
	s_cmp_eq_u32 s57, 0
	s_cselect_b64 s[0:1], s[84:85], 0
	s_cmp_eq_u32 s57, s60
	s_cselect_b64 s[4:5], s[86:87], 0
	v_mov_b32_e32 v255, 0x1800
	v_cndmask_b32_e64 v150, 0, v255, s[0:1]
	v_lshlrev_b32_e32 v136, 1, v150
	v_add_u32_e32 v136, v134, v136
	v_add_u32_e32 v150, v134, v150
	v_cndmask_b32_e64 v151, 0, v255, s[4:5]
	v_sub_u32_e32 v151, v134, v151
	s_lshl_b32 s61, s59, 7
	s_mul_i32 s0, s61, 0xc00
	s_lshl_b32 s1, s56, 1
	s_add_u32 s0, s0, s1
	s_add_u32 s4, s10, s0
	s_addc_u32 s5, s11, 0
	s_sub_u32 s4, s4, 0x1800
	s_subb_u32 s5, s5, 0
	global_load_ushort v205, v136, s[4:5]
	s_add_u32 s4, s4, 0xc00
	s_addc_u32 s5, s5, 0
	global_load_ushort v206, v150, s[4:5]
	s_add_u32 s4, s4, 0xc00
	s_addc_u32 s5, s5, 0
	global_load_ushort v207, v134, s[4:5]
	s_add_u32 s4, s4, 0xc00
	s_addc_u32 s5, s5, 0
	global_load_ushort v208, v134, s[4:5]
	s_add_u32 s4, s4, 0xc00
	s_addc_u32 s5, s5, 0
	global_load_ushort v209, v134, s[4:5]
	s_add_u32 s4, s4, 0xc00
	s_addc_u32 s5, s5, 0
	global_load_ushort v210, v134, s[4:5]
	s_add_u32 s4, s4, 0xc00
	s_addc_u32 s5, s5, 0
	global_load_ushort v211, v134, s[4:5]
	s_add_u32 s4, s4, 0xc00
	s_addc_u32 s5, s5, 0
	global_load_ushort v212, v134, s[4:5]
	s_add_u32 s4, s4, 0xc00
	s_addc_u32 s5, s5, 0
	global_load_ushort v213, v134, s[4:5]
	s_add_u32 s4, s4, 0xc00
	s_addc_u32 s5, s5, 0
	global_load_ushort v214, v134, s[4:5]
	s_add_u32 s4, s4, 0xc00
	s_addc_u32 s5, s5, 0
	global_load_ushort v215, v134, s[4:5]
	s_add_u32 s4, s4, 0xc00
	s_addc_u32 s5, s5, 0
	global_load_ushort v216, v134, s[4:5]
	s_add_u32 s4, s4, 0xc00
	s_addc_u32 s5, s5, 0
	global_load_ushort v217, v134, s[4:5]
	s_add_u32 s4, s4, 0xc00
	s_addc_u32 s5, s5, 0
	global_load_ushort v218, v134, s[4:5]
	s_add_u32 s4, s4, 0xc00
	s_addc_u32 s5, s5, 0
	global_load_ushort v219, v134, s[4:5]
	s_add_u32 s4, s4, 0xc00
	s_addc_u32 s5, s5, 0
	global_load_ushort v220, v134, s[4:5]
	s_add_u32 s4, s4, 0xc00
	s_addc_u32 s5, s5, 0
	global_load_ushort v221, v134, s[4:5]
	s_add_u32 s4, s4, 0xc00
	s_addc_u32 s5, s5, 0
	global_load_ushort v222, v134, s[4:5]
	s_add_u32 s4, s4, 0xc00
	s_addc_u32 s5, s5, 0
	global_load_ushort v223, v134, s[4:5]
	s_add_u32 s4, s4, 0xc00
	s_addc_u32 s5, s5, 0
	global_load_ushort v224, v134, s[4:5]
	s_add_u32 s4, s4, 0xc00
	s_addc_u32 s5, s5, 0
	global_load_ushort v225, v134, s[4:5]
	s_add_u32 s4, s4, 0xc00
	s_addc_u32 s5, s5, 0
	global_load_ushort v226, v134, s[4:5]
	s_add_u32 s4, s4, 0xc00
	s_addc_u32 s5, s5, 0
	global_load_ushort v227, v134, s[4:5]
	s_add_u32 s4, s4, 0xc00
	s_addc_u32 s5, s5, 0
	global_load_ushort v228, v134, s[4:5]
	s_add_u32 s4, s4, 0xc00
	s_addc_u32 s5, s5, 0
	global_load_ushort v229, v134, s[4:5]
	s_add_u32 s4, s4, 0xc00
	s_addc_u32 s5, s5, 0
	global_load_ushort v230, v134, s[4:5]
	s_add_u32 s4, s4, 0xc00
	s_addc_u32 s5, s5, 0
	global_load_ushort v231, v134, s[4:5]
	s_add_u32 s4, s4, 0xc00
	s_addc_u32 s5, s5, 0
	global_load_ushort v232, v134, s[4:5]
	s_add_u32 s4, s4, 0xc00
	s_addc_u32 s5, s5, 0
	global_load_ushort v233, v134, s[4:5]
	s_add_u32 s4, s4, 0xc00
	s_addc_u32 s5, s5, 0
	global_load_ushort v234, v134, s[4:5]
	s_add_u32 s4, s4, 0xc00
	s_addc_u32 s5, s5, 0
	global_load_ushort v235, v134, s[4:5]
	s_add_u32 s4, s4, 0xc00
	s_addc_u32 s5, s5, 0
	global_load_ushort v236, v134, s[4:5]
	s_add_u32 s4, s4, 0xc00
	s_addc_u32 s5, s5, 0
	global_load_ushort v142, v134, s[4:5]
	s_add_u32 s4, s4, 0xc00
	s_addc_u32 s5, s5, 0
	global_load_ushort v143, v134, s[4:5]
	s_add_u32 s4, s4, 0xc00
	s_addc_u32 s5, s5, 0
	global_load_ushort v144, v151, s[4:5]
	v_bfe_u32 v255, v152, 6, 2
	v_and_b32_e32 v253, 15, v152
	v_lshl_add_u32 v255, v255, 4, v253
	v_add_u32_e32 v255, s56, v255
	v_lshlrev_b32_e32 v255, 2, v255
	global_load_dword v65, v255, s[24:25]
	global_load_dword v67, v255, s[24:25] offset:2048
	s_add_u32 s0, s24, 0x1000
	s_addc_u32 s1, s25, 0
	global_load_dword v68, v255, s[0:1]
	global_load_dword v70, v255, s[0:1] offset:2048
	global_load_dword v73, v255, s[26:27]
	s_add_u32 s0, s28, 0x0
	s_addc_u32 s1, s29, 0
	global_load_dword v75, v255, s[0:1]
	s_add_u32 s0, s30, 0x0
	s_addc_u32 s1, s31, 0
	global_load_dword v84, v255, s[0:1]
	s_add_u32 s0, s36, 0x0
	s_addc_u32 s1, s37, 0
	global_load_dword v85, v255, s[0:1]
	s_add_u32 s0, s28, 0x800
	s_addc_u32 s1, s29, 0
	global_load_dword v145, v255, s[0:1]
	s_add_u32 s0, s30, 0x800
	s_addc_u32 s1, s31, 0
	global_load_dword v146, v255, s[0:1]
	s_add_u32 s0, s36, 0x800
	s_addc_u32 s1, s37, 0
	global_load_dword v147, v255, s[0:1]
	s_lshl_b32 s0, s56, 8
	s_add_u32 s0, s0, 0x0
	s_add_u32 s4, s20, s0
	s_addc_u32 s5, s21, 0
	global_load_dwordx4 v[238:241], v251, s[4:5]
	global_load_dwordx4 v[242:245], v251, s[4:5] offset:64
	s_add_u32 s4, s4, 0x2000
	s_addc_u32 s5, s5, 0
	global_load_dwordx4 v[246:249], v251, s[4:5]
	global_load_dwordx4 v[194:197], v251, s[4:5] offset:64
	s_waitcnt vmcnt(0)
	v_mul_f32_e32 v75, 0xbfb8aa3b, v75
	v_mul_f32_e32 v84, 0xbfb8aa3b, v84
	v_sub_f32_e32 v138, 0, v85
	v_mul_f32_e32 v139, 0x3fb8aa3b, v138
	v_exp_f32_e32 v139, v139
	s_nop 0
	v_mul_f32_e32 v140, 0xbe800000, v139
	v_add_f32_e32 v140, 0x3eaaaaab, v140
	v_fma_f32 v140, -v139, v140, 0.5
	v_fma_f32 v140, -v139, v140, 1.0
	v_mul_f32_e32 v140, v139, v140
	v_add_f32_e32 v141, 1.0, v139
	v_log_f32_e32 v141, v141
	v_mov_b32_e32 v255, 0x3cf5c28f
	v_mul_f32_e32 v141, 0x3f317218, v141
	v_cmp_gt_f32_e32 vcc, v255, v139
	s_nop 1
	v_cndmask_b32_e32 v140, v141, v140, vcc
	v_mov_b32_e32 v255, 0x41a00000
	v_cmp_lt_f32_e32 vcc, v255, v138
	s_nop 1
	v_cndmask_b32_e32 v140, v140, v138, vcc
	v_mul_f32_e32 v85, 0xc138aa3b, v140
	v_mul_f32_e32 v145, 0xbfb8aa3b, v145
	v_mul_f32_e32 v146, 0xbfb8aa3b, v146
	v_sub_f32_e32 v138, 0, v147
	v_mul_f32_e32 v139, 0x3fb8aa3b, v138
	v_exp_f32_e32 v139, v139
	s_nop 0
	v_mul_f32_e32 v140, 0xbe800000, v139
	v_add_f32_e32 v140, 0x3eaaaaab, v140
	v_fma_f32 v140, -v139, v140, 0.5
	v_fma_f32 v140, -v139, v140, 1.0
	v_mul_f32_e32 v140, v139, v140
	v_add_f32_e32 v141, 1.0, v139
	v_log_f32_e32 v141, v141
	v_mov_b32_e32 v255, 0x3cf5c28f
	v_mul_f32_e32 v141, 0x3f317218, v141
	v_cmp_gt_f32_e32 vcc, v255, v139
	s_nop 1
	v_cndmask_b32_e32 v140, v141, v140, vcc
	v_mov_b32_e32 v255, 0x41a00000
	v_cmp_lt_f32_e32 vcc, v255, v138
	s_nop 1
	v_cndmask_b32_e32 v140, v140, v138, vcc
	v_mul_f32_e32 v147, 0xc138aa3b, v140
	s_mov_b32 s62, 0x4000

; __device__ __forceinline__ float bf2f(u16 h) { return __uint_as_float(((unsigned)h) << 16); }
; __device__ __forceinline__ void lru_tile(const Params& P, int chunk, int head, int pass, char* smem_raw) {
;     ...
;     const float w0 = P.conv_w[gch], w1 = P.conv_w[512 + gch], w2 = P.conv_w[1024 + gch], w3 = P.conv_w[1536 + gch];
;     const float cb = P.conv_b[gch];
;     const u16* zu = P.zq + gch;
;     const int r = row0 + q * 32;
;     float uv[35];
; #pragma unroll
;     for (int i = 0; i < 35; ++i) {
;       const int rr = r - 2 + i;
;       uv[i] = (rr >= seq_lo && rr < seq_hi) ? bf2f(zu[(long)rr * 1536]) : 0.f;
;     }
;     __syncthreads();
; #pragma unroll
;     for (int i = 0; i < 32; ++i) {
;       const float v = cb + uv[i] * w0 + uv[i + 1] * w1 + uv[i + 2] * w2 + uv[i + 3] * w3;
;       sm_uc[(q * 32 + i) * LDSS + ch] = f2bf(v);
.Lmy_lrua_fl:
	s_cmp_eq_u32 s57, 0
	s_cselect_b64 s[0:1], s[84:85], 0
	s_cmp_eq_u32 s57, s60
	s_cselect_b64 s[4:5], s[86:87], 0
	v_cndmask_b32_e64 v202, 1.0, 0, s[0:1]
	v_cndmask_b32_e64 v203, 1.0, 0, s[4:5]
	s_waitcnt vmcnt(1)
	v_lshlrev_b32_e32 v90, 16, v205
	v_lshlrev_b32_e32 v91, 16, v206
	v_lshlrev_b32_e32 v92, 16, v207
	v_lshlrev_b32_e32 v93, 16, v208
	v_lshlrev_b32_e32 v94, 16, v209
	v_lshlrev_b32_e32 v95, 16, v210
	v_lshlrev_b32_e32 v96, 16, v211
	v_lshlrev_b32_e32 v97, 16, v212
	v_lshlrev_b32_e32 v98, 16, v213
	v_lshlrev_b32_e32 v99, 16, v214
	v_lshlrev_b32_e32 v100, 16, v215
	v_lshlrev_b32_e32 v101, 16, v216
	v_lshlrev_b32_e32 v102, 16, v217
	v_lshlrev_b32_e32 v103, 16, v218
	v_lshlrev_b32_e32 v104, 16, v219
	v_lshlrev_b32_e32 v105, 16, v220
	v_lshlrev_b32_e32 v106, 16, v221
	v_lshlrev_b32_e32 v107, 16, v222
	v_lshlrev_b32_e32 v108, 16, v223
	v_lshlrev_b32_e32 v109, 16, v224
	v_lshlrev_b32_e32 v110, 16, v225
	v_lshlrev_b32_e32 v111, 16, v226
	v_lshlrev_b32_e32 v112, 16, v227
	v_lshlrev_b32_e32 v113, 16, v228
	v_lshlrev_b32_e32 v114, 16, v229
	v_lshlrev_b32_e32 v115, 16, v230
	v_lshlrev_b32_e32 v116, 16, v231
	v_lshlrev_b32_e32 v117, 16, v232
	v_lshlrev_b32_e32 v118, 16, v233
	v_lshlrev_b32_e32 v119, 16, v234
	v_lshlrev_b32_e32 v120, 16, v235
	v_lshlrev_b32_e32 v121, 16, v236
	v_lshlrev_b32_e32 v122, 16, v142
	v_lshlrev_b32_e32 v123, 16, v143
	v_lshlrev_b32_e32 v124, 16, v144
	v_mul_f32_e32 v90, v90, v202
	v_mul_f32_e32 v91, v91, v202
	v_mul_f32_e32 v124, v124, v203
	v_fma_f32 v162, v90, v65, v73
	v_fma_f32 v162, v91, v67, v162
	v_fma_f32 v162, v92, v68, v162
	v_fma_f32 v162, v93, v70, v162
	v_fma_f32 v163, v91, v65, v73
	v_fma_f32 v163, v92, v67, v163
	v_fma_f32 v163, v93, v68, v163
	v_fma_f32 v163, v94, v70, v163
	v_fma_f32 v164, v92, v65, v73
	v_fma_f32 v164, v93, v67, v164
	v_fma_f32 v164, v94, v68, v164
	v_fma_f32 v164, v95, v70, v164
	v_fma_f32 v165, v93, v65, v73
	v_fma_f32 v165, v94, v67, v165
	v_fma_f32 v165, v95, v68, v165
	v_fma_f32 v165, v96, v70, v165
	v_fma_f32 v166, v94, v65, v73
	v_fma_f32 v166, v95, v67, v166
	v_fma_f32 v166, v96, v68, v166
	v_fma_f32 v166, v97, v70, v166
	v_fma_f32 v167, v95, v65, v73
	v_fma_f32 v167, v96, v67, v167
	v_fma_f32 v167, v97, v68, v167
	v_fma_f32 v167, v98, v70, v167
	v_fma_f32 v168, v96, v65, v73
	v_fma_f32 v168, v97, v67, v168
	v_fma_f32 v168, v98, v68, v168
	v_fma_f32 v168, v99, v70, v168
	v_fma_f32 v169, v97, v65, v73
	v_fma_f32 v169, v98, v67, v169
	v_fma_f32 v169, v99, v68, v169
	v_fma_f32 v169, v100, v70, v169
	v_fma_f32 v170, v98, v65, v73
	v_fma_f32 v170, v99, v67, v170
	v_fma_f32 v170, v100, v68, v170
	v_fma_f32 v170, v101, v70, v170
	v_fma_f32 v171, v99, v65, v73
	v_fma_f32 v171, v100, v67, v171
	v_fma_f32 v171, v101, v68, v171
	v_fma_f32 v171, v102, v70, v171
	v_fma_f32 v172, v100, v65, v73
	v_fma_f32 v172, v101, v67, v172
	v_fma_f32 v172, v102, v68, v172
	v_fma_f32 v172, v103, v70, v172
	v_fma_f32 v173, v101, v65, v73
	v_fma_f32 v173, v102, v67, v173
	v_fma_f32 v173, v103, v68, v173
	v_fma_f32 v173, v104, v70, v173
	v_fma_f32 v174, v102, v65, v73
	v_fma_f32 v174, v103, v67, v174
	v_fma_f32 v174, v104, v68, v174
	v_fma_f32 v174, v105, v70, v174
	v_fma_f32 v175, v103, v65, v73
	v_fma_f32 v175, v104, v67, v175
	v_fma_f32 v175, v105, v68, v175
	v_fma_f32 v175, v106, v70, v175
	v_fma_f32 v176, v104, v65, v73
	v_fma_f32 v176, v105, v67, v176
	v_fma_f32 v176, v106, v68, v176
	v_fma_f32 v176, v107, v70, v176
	v_fma_f32 v177, v105, v65, v73
	v_fma_f32 v177, v106, v67, v177
	v_fma_f32 v177, v107, v68, v177
	v_fma_f32 v177, v108, v70, v177
	v_fma_f32 v178, v106, v65, v73
	v_fma_f32 v178, v107, v67, v178
	v_fma_f32 v178, v108, v68, v178
	v_fma_f32 v178, v109, v70, v178
	v_fma_f32 v179, v107, v65, v73
	v_fma_f32 v179, v108, v67, v179
	v_fma_f32 v179, v109, v68, v179
	v_fma_f32 v179, v110, v70, v179
	v_fma_f32 v180, v108, v65, v73
	v_fma_f32 v180, v109, v67, v180
	v_fma_f32 v180, v110, v68, v180
	v_fma_f32 v180, v111, v70, v180
	v_fma_f32 v181, v109, v65, v73
	v_fma_f32 v181, v110, v67, v181
	v_fma_f32 v181, v111, v68, v181
	v_fma_f32 v181, v112, v70, v181
	v_fma_f32 v182, v110, v65, v73
	v_fma_f32 v182, v111, v67, v182
	v_fma_f32 v182, v112, v68, v182
	v_fma_f32 v182, v113, v70, v182
	v_fma_f32 v183, v111, v65, v73
	v_fma_f32 v183, v112, v67, v183
	v_fma_f32 v183, v113, v68, v183
	v_fma_f32 v183, v114, v70, v183
	v_fma_f32 v184, v112, v65, v73
	v_fma_f32 v184, v113, v67, v184
	v_fma_f32 v184, v114, v68, v184
	v_fma_f32 v184, v115, v70, v184
	v_fma_f32 v185, v113, v65, v73
	v_fma_f32 v185, v114, v67, v185
	v_fma_f32 v185, v115, v68, v185
	v_fma_f32 v185, v116, v70, v185
	v_fma_f32 v186, v114, v65, v73
	v_fma_f32 v186, v115, v67, v186
	v_fma_f32 v186, v116, v68, v186
	v_fma_f32 v186, v117, v70, v186
	v_fma_f32 v187, v115, v65, v73
	v_fma_f32 v187, v116, v67, v187
	v_fma_f32 v187, v117, v68, v187
	v_fma_f32 v187, v118, v70, v187
	v_fma_f32 v188, v116, v65, v73
	v_fma_f32 v188, v117, v67, v188
	v_fma_f32 v188, v118, v68, v188
	v_fma_f32 v188, v119, v70, v188
	v_fma_f32 v189, v117, v65, v73
	v_fma_f32 v189, v118, v67, v189
	v_fma_f32 v189, v119, v68, v189
	v_fma_f32 v189, v120, v70, v189
	v_fma_f32 v190, v118, v65, v73
	v_fma_f32 v190, v119, v67, v190
	v_fma_f32 v190, v120, v68, v190
	v_fma_f32 v190, v121, v70, v190
	v_fma_f32 v191, v119, v65, v73
	v_fma_f32 v191, v120, v67, v191
	v_fma_f32 v191, v121, v68, v191
	v_fma_f32 v191, v122, v70, v191
	v_fma_f32 v192, v120, v65, v73
	v_fma_f32 v192, v121, v67, v192
	v_fma_f32 v192, v122, v68, v192
	v_fma_f32 v192, v123, v70, v192
	v_fma_f32 v193, v121, v65, v73
	v_fma_f32 v193, v122, v67, v193
	v_fma_f32 v193, v123, v68, v193
; __device__ __forceinline__ float bf2f(u16 h) { return __uint_as_float(((unsigned)h) << 16); }
; __device__ __forceinline__ void lru_tile(const Params& P, int chunk, int head, int pass, char* smem_raw) {
;     ...
;     const u16* zu = P.zq + gch;
;     const int r = row0 + q * 32;
;     float uv[35];
; #pragma unroll
;     for (int i = 0; i < 35; ++i) {
;       const int rr = r - 2 + i;
;       uv[i] = (rr >= seq_lo && rr < seq_hi) ? bf2f(zu[(long)rr * 1536]) : 0.f;
;     ...
;     for (int i = 0; i < 32; ++i) {
;       const float v = cb + uv[i] * w0 + uv[i + 1] * w1 + uv[i + 2] * w2 + uv[i + 3] * w3;
;       sm_uc[(q * 32 + i) * LDSS + ch] = f2bf(v);
;     }
	v_fma_f32 v193, v124, v70, v193
	v_cvt_pk_bf16_f32 v162, v162, v162
	v_cvt_pk_bf16_f32 v163, v163, v163
	v_cvt_pk_bf16_f32 v164, v164, v164
	v_cvt_pk_bf16_f32 v165, v165, v165
	v_cvt_pk_bf16_f32 v166, v166, v166
	v_cvt_pk_bf16_f32 v167, v167, v167
	v_cvt_pk_bf16_f32 v168, v168, v168
	v_cvt_pk_bf16_f32 v169, v169, v169
	v_cvt_pk_bf16_f32 v170, v170, v170
	v_cvt_pk_bf16_f32 v171, v171, v171
	v_cvt_pk_bf16_f32 v172, v172, v172
	v_cvt_pk_bf16_f32 v173, v173, v173
	v_cvt_pk_bf16_f32 v174, v174, v174
	v_cvt_pk_bf16_f32 v175, v175, v175
	v_cvt_pk_bf16_f32 v176, v176, v176
	v_cvt_pk_bf16_f32 v177, v177, v177
	v_cvt_pk_bf16_f32 v178, v178, v178
	v_cvt_pk_bf16_f32 v179, v179, v179
	v_cvt_pk_bf16_f32 v180, v180, v180
	v_cvt_pk_bf16_f32 v181, v181, v181
	v_cvt_pk_bf16_f32 v182, v182, v182
	v_cvt_pk_bf16_f32 v183, v183, v183
	v_cvt_pk_bf16_f32 v184, v184, v184
	v_cvt_pk_bf16_f32 v185, v185, v185
	v_cvt_pk_bf16_f32 v186, v186, v186
	v_cvt_pk_bf16_f32 v187, v187, v187
	v_cvt_pk_bf16_f32 v188, v188, v188
	v_cvt_pk_bf16_f32 v189, v189, v189
	v_cvt_pk_bf16_f32 v190, v190, v190
	v_cvt_pk_bf16_f32 v191, v191, v191
	v_cvt_pk_bf16_f32 v192, v192, v192
	v_cvt_pk_bf16_f32 v193, v193, v193
	ds_write_b16 v89, v162 offset:0
	ds_write_b16 v89, v163 offset:128
	ds_write_b16 v130, v164 offset:256
	ds_write_b16 v130, v165 offset:384
	ds_write_b16 v89, v166 offset:512
	ds_write_b16 v89, v167 offset:640
	ds_write_b16 v130, v168 offset:768
	ds_write_b16 v130, v169 offset:896
	ds_write_b16 v89, v170 offset:1024
	ds_write_b16 v89, v171 offset:1152
	ds_write_b16 v130, v172 offset:1280
	ds_write_b16 v130, v173 offset:1408
	ds_write_b16 v89, v174 offset:1536
	ds_write_b16 v89, v175 offset:1664
	ds_write_b16 v130, v176 offset:1792
	ds_write_b16 v130, v177 offset:1920
	ds_write_b16 v89, v178 offset:2048
	ds_write_b16 v89, v179 offset:2176
	ds_write_b16 v130, v180 offset:2304
	ds_write_b16 v130, v181 offset:2432
	ds_write_b16 v89, v182 offset:2560
	ds_write_b16 v89, v183 offset:2688
	ds_write_b16 v130, v184 offset:2816
	ds_write_b16 v130, v185 offset:2944
	ds_write_b16 v89, v186 offset:3072
	ds_write_b16 v89, v187 offset:3200
	ds_write_b16 v130, v188 offset:3328
	ds_write_b16 v130, v189 offset:3456
	ds_write_b16 v89, v190 offset:3584
	ds_write_b16 v89, v191 offset:3712
	ds_write_b16 v130, v192 offset:3840
	ds_write_b16 v130, v193 offset:3968
	v_lshlrev_b32_e32 v162, 16, v162
	v_lshlrev_b32_e32 v163, 16, v163
	v_lshlrev_b32_e32 v164, 16, v164
	v_lshlrev_b32_e32 v165, 16, v165
	v_lshlrev_b32_e32 v166, 16, v166
	v_lshlrev_b32_e32 v167, 16, v167
	v_lshlrev_b32_e32 v168, 16, v168
	v_lshlrev_b32_e32 v169, 16, v169
	v_lshlrev_b32_e32 v170, 16, v170
	v_lshlrev_b32_e32 v171, 16, v171
	v_lshlrev_b32_e32 v172, 16, v172
	v_lshlrev_b32_e32 v173, 16, v173
	v_lshlrev_b32_e32 v174, 16, v174
	v_lshlrev_b32_e32 v175, 16, v175
	v_lshlrev_b32_e32 v176, 16, v176
	v_lshlrev_b32_e32 v177, 16, v177
	v_lshlrev_b32_e32 v178, 16, v178
	v_lshlrev_b32_e32 v179, 16, v179
	v_lshlrev_b32_e32 v180, 16, v180
	v_lshlrev_b32_e32 v181, 16, v181
	v_lshlrev_b32_e32 v182, 16, v182
	v_lshlrev_b32_e32 v183, 16, v183
	v_lshlrev_b32_e32 v184, 16, v184
	v_lshlrev_b32_e32 v185, 16, v185
	v_lshlrev_b32_e32 v186, 16, v186
	v_lshlrev_b32_e32 v187, 16, v187
	v_lshlrev_b32_e32 v188, 16, v188
	v_lshlrev_b32_e32 v189, 16, v189
	v_lshlrev_b32_e32 v190, 16, v190
	v_lshlrev_b32_e32 v191, 16, v191
	v_lshlrev_b32_e32 v192, 16, v192
	v_lshlrev_b32_e32 v193, 16, v193
	s_waitcnt lgkmcnt(0)
	s_barrier
	s_add_u32 s58, s69, 1
	s_cmp_lt_u32 s58, s70
	s_cbranch_scc0 .Lmy_lrua_nopf
	s_lshl_b32 s58, s58, 9
	s_add_u32 s58, s58, s68
	s_lshr_b32 s59, s58, 3
	s_cmp_lt_u32 s59, 256
	s_cselect_b32 s60, 63, 1
	s_and_b32 s57, s59, s60
	s_cmp_eq_u32 s57, 0
	s_cselect_b64 s[0:1], s[84:85], 0
	s_cmp_eq_u32 s57, s60
	s_cselect_b64 s[4:5], s[86:87], 0
	v_mov_b32_e32 v255, 0x1800
	v_cndmask_b32_e64 v150, 0, v255, s[0:1]
	v_lshlrev_b32_e32 v136, 1, v150
	v_add_u32_e32 v136, v134, v136
	v_add_u32_e32 v150, v134, v150
	v_cndmask_b32_e64 v151, 0, v255, s[4:5]
	v_sub_u32_e32 v151, v134, v151
	s_lshl_b32 s61, s59, 7
	s_mul_i32 s0, s61, 0xc00
	s_lshl_b32 s1, s56, 1
	s_add_u32 s0, s0, s1
	s_add_u32 s4, s10, s0
	s_addc_u32 s5, s11, 0
	s_sub_u32 s4, s4, 0x1800
	s_subb_u32 s5, s5, 0
	global_load_ushort v205, v136, s[4:5]
	s_add_u32 s4, s4, 0xc00
	s_addc_u32 s5, s5, 0
	global_load_ushort v206, v150, s[4:5]
	s_add_u32 s4, s4, 0xc00
	s_addc_u32 s5, s5, 0
	global_load_ushort v207, v134, s[4:5]
	s_add_u32 s4, s4, 0xc00
	s_addc_u32 s5, s5, 0
	global_load_ushort v208, v134, s[4:5]
	s_add_u32 s4, s4, 0xc00
	s_addc_u32 s5, s5, 0
	global_load_ushort v209, v134, s[4:5]
	s_add_u32 s4, s4, 0xc00
	s_addc_u32 s5, s5, 0
	global_load_ushort v210, v134, s[4:5]
	s_add_u32 s4, s4, 0xc00
	s_addc_u32 s5, s5, 0
	global_load_ushort v211, v134, s[4:5]
	s_add_u32 s4, s4, 0xc00
	s_addc_u32 s5, s5, 0
	global_load_ushort v212, v134, s[4:5]
	s_add_u32 s4, s4, 0xc00
	s_addc_u32 s5, s5, 0
	global_load_ushort v213, v134, s[4:5]
	s_add_u32 s4, s4, 0xc00
	s_addc_u32 s5, s5, 0
	global_load_ushort v214, v134, s[4:5]
	s_add_u32 s4, s4, 0xc00
	s_addc_u32 s5, s5, 0
	global_load_ushort v215, v134, s[4:5]
	s_add_u32 s4, s4, 0xc00
	s_addc_u32 s5, s5, 0
	global_load_ushort v216, v134, s[4:5]
	s_add_u32 s4, s4, 0xc00
	s_addc_u32 s5, s5, 0
	global_load_ushort v217, v134, s[4:5]
	s_add_u32 s4, s4, 0xc00
	s_addc_u32 s5, s5, 0
	global_load_ushort v218, v134, s[4:5]
	s_add_u32 s4, s4, 0xc00
	s_addc_u32 s5, s5, 0
	global_load_ushort v219, v134, s[4:5]
	s_add_u32 s4, s4, 0xc00
	s_addc_u32 s5, s5, 0
	global_load_ushort v220, v134, s[4:5]
	s_add_u32 s4, s4, 0xc00
	s_addc_u32 s5, s5, 0
	global_load_ushort v221, v134, s[4:5]
; __device__ __forceinline__ void lru_tile(const Params& P, int chunk, int head, int pass, char* smem_raw) {
;     ...
; #pragma unroll
;       for (int t = 0; t < 8; ++t) acc[t] = f32x4{0.f, 0.f, 0.f, 0.f};
; #pragma unroll
;       for (int s = 0; s < 2; ++s) {
;         const bf16x8 af = *reinterpret_cast<const bf16x8*>(&sm_uc[(sb * 64 + wid * 16 + (lane & 15)) * LDSS + s * 32 + (lane >> 4) * 8]);
; #pragma unroll
;         for (int t = 0; t < 8; ++t) {
;           const bf16x8 bfr = *reinterpret_cast<const bf16x8*>(&sm_w[(t * 16 + (lane & 15)) * LDSS + s * 32 + (lane >> 4) * 8]);
;           acc[t] = __builtin_amdgcn_mfma_f32_16x16x32_bf16(af, bfr, acc[t], 0, 0, 0);
;         }
;       }
	s_add_u32 s4, s4, 0xc00
	s_addc_u32 s5, s5, 0
	global_load_ushort v222, v134, s[4:5]
	s_add_u32 s4, s4, 0xc00
	s_addc_u32 s5, s5, 0
	global_load_ushort v223, v134, s[4:5]
	s_add_u32 s4, s4, 0xc00
	s_addc_u32 s5, s5, 0
	global_load_ushort v224, v134, s[4:5]
	s_add_u32 s4, s4, 0xc00
	s_addc_u32 s5, s5, 0
	global_load_ushort v225, v134, s[4:5]
	s_add_u32 s4, s4, 0xc00
	s_addc_u32 s5, s5, 0
	global_load_ushort v226, v134, s[4:5]
	s_add_u32 s4, s4, 0xc00
	s_addc_u32 s5, s5, 0
	global_load_ushort v227, v134, s[4:5]
	s_add_u32 s4, s4, 0xc00
	s_addc_u32 s5, s5, 0
	global_load_ushort v228, v134, s[4:5]
	s_add_u32 s4, s4, 0xc00
	s_addc_u32 s5, s5, 0
	global_load_ushort v229, v134, s[4:5]
	s_add_u32 s4, s4, 0xc00
	s_addc_u32 s5, s5, 0
	global_load_ushort v230, v134, s[4:5]
	s_add_u32 s4, s4, 0xc00
	s_addc_u32 s5, s5, 0
	global_load_ushort v231, v134, s[4:5]
	s_add_u32 s4, s4, 0xc00
	s_addc_u32 s5, s5, 0
	global_load_ushort v232, v134, s[4:5]
	s_add_u32 s4, s4, 0xc00
	s_addc_u32 s5, s5, 0
	global_load_ushort v233, v134, s[4:5]
	s_add_u32 s4, s4, 0xc00
	s_addc_u32 s5, s5, 0
	global_load_ushort v234, v134, s[4:5]
	s_add_u32 s4, s4, 0xc00
	s_addc_u32 s5, s5, 0
	global_load_ushort v235, v134, s[4:5]
	s_add_u32 s4, s4, 0xc00
	s_addc_u32 s5, s5, 0
	global_load_ushort v236, v134, s[4:5]
	s_add_u32 s4, s4, 0xc00
	s_addc_u32 s5, s5, 0
	global_load_ushort v142, v134, s[4:5]
	s_add_u32 s4, s4, 0xc00
	s_addc_u32 s5, s5, 0
	global_load_ushort v143, v134, s[4:5]
	s_add_u32 s4, s4, 0xc00
	s_addc_u32 s5, s5, 0
	global_load_ushort v144, v151, s[4:5]
.Lmy_lrua_nopf:
	ds_read_b128 v[76:79], v131 offset:0
	ds_read_b128 v[80:83], v133 offset:0
	ds_read_b128 v[122:125], v131 offset:512
	ds_read_b128 v[126:129], v133 offset:512
	s_waitcnt lgkmcnt(3)
	v_mfma_f32_16x16x32_bf16 v[0:3], v[76:79], v[238:241], 0
	v_mfma_f32_16x16x32_bf16 v[90:93], v[76:79], v[246:249], 0
	ds_read_b128 v[76:79], v131 offset:1024
	s_waitcnt lgkmcnt(3)
	v_mfma_f32_16x16x32_bf16 v[0:3], v[80:83], v[242:245], v[0:3]
	v_mfma_f32_16x16x32_bf16 v[90:93], v[80:83], v[194:197], v[90:93]
	ds_read_b128 v[80:83], v133 offset:1024
	s_waitcnt lgkmcnt(3)
	v_mfma_f32_16x16x32_bf16 v[4:7], v[122:125], v[238:241], 0
	v_mfma_f32_16x16x32_bf16 v[94:97], v[122:125], v[246:249], 0
	ds_read_b128 v[122:125], v131 offset:1536
	s_waitcnt lgkmcnt(3)
	v_mfma_f32_16x16x32_bf16 v[4:7], v[126:129], v[242:245], v[4:7]
	v_mfma_f32_16x16x32_bf16 v[94:97], v[126:129], v[194:197], v[94:97]
	ds_read_b128 v[126:129], v133 offset:1536
	s_waitcnt lgkmcnt(3)
	v_mfma_f32_16x16x32_bf16 v[8:11], v[76:79], v[238:241], 0
	v_mfma_f32_16x16x32_bf16 v[98:101], v[76:79], v[246:249], 0
	ds_read_b128 v[76:79], v131 offset:2048
	s_waitcnt lgkmcnt(3)
	v_mfma_f32_16x16x32_bf16 v[8:11], v[80:83], v[242:245], v[8:11]
	v_mfma_f32_16x16x32_bf16 v[98:101], v[80:83], v[194:197], v[98:101]
	ds_read_b128 v[80:83], v133 offset:2048
	s_waitcnt lgkmcnt(3)
	v_mfma_f32_16x16x32_bf16 v[12:15], v[122:125], v[238:241], 0
	v_mfma_f32_16x16x32_bf16 v[102:105], v[122:125], v[246:249], 0
	ds_read_b128 v[122:125], v131 offset:2560
	s_waitcnt lgkmcnt(3)
	v_mfma_f32_16x16x32_bf16 v[12:15], v[126:129], v[242:245], v[12:15]
	v_mfma_f32_16x16x32_bf16 v[102:105], v[126:129], v[194:197], v[102:105]
	ds_read_b128 v[126:129], v133 offset:2560
	s_waitcnt lgkmcnt(3)
	v_mfma_f32_16x16x32_bf16 v[16:19], v[76:79], v[238:241], 0
	v_mfma_f32_16x16x32_bf16 v[106:109], v[76:79], v[246:249], 0
	ds_read_b128 v[76:79], v131 offset:3072
	s_waitcnt lgkmcnt(3)
	v_mfma_f32_16x16x32_bf16 v[16:19], v[80:83], v[242:245], v[16:19]
	v_mfma_f32_16x16x32_bf16 v[106:109], v[80:83], v[194:197], v[106:109]
	ds_read_b128 v[80:83], v133 offset:3072
	s_waitcnt lgkmcnt(3)
	v_mfma_f32_16x16x32_bf16 v[20:23], v[122:125], v[238:241], 0
	v_mfma_f32_16x16x32_bf16 v[110:113], v[122:125], v[246:249], 0
	ds_read_b128 v[122:125], v131 offset:3584
	s_waitcnt lgkmcnt(3)
	v_mfma_f32_16x16x32_bf16 v[20:23], v[126:129], v[242:245], v[20:23]
	v_mfma_f32_16x16x32_bf16 v[110:113], v[126:129], v[194:197], v[110:113]
	ds_read_b128 v[126:129], v133 offset:3584
	s_waitcnt lgkmcnt(3)
	v_mfma_f32_16x16x32_bf16 v[24:27], v[76:79], v[238:241], 0
	v_mfma_f32_16x16x32_bf16 v[114:117], v[76:79], v[246:249], 0
	s_waitcnt lgkmcnt(2)
	v_mfma_f32_16x16x32_bf16 v[24:27], v[80:83], v[242:245], v[24:27]
	v_mfma_f32_16x16x32_bf16 v[114:117], v[80:83], v[194:197], v[114:117]
	s_waitcnt lgkmcnt(1)
	v_mfma_f32_16x16x32_bf16 v[28:31], v[122:125], v[238:241], 0
	v_mfma_f32_16x16x32_bf16 v[118:121], v[122:125], v[246:249], 0
	s_waitcnt lgkmcnt(0)
; __device__ __forceinline__ float bf2f(u16 h) { return __uint_as_float(((unsigned)h) << 16); }
; __device__ __forceinline__ void lru_tile(const Params& P, int chunk, int head, int pass, char* smem_raw) {
;     ...
;           acc[t] = __builtin_amdgcn_mfma_f32_16x16x32_bf16(af, bfr, acc[t], 0, 0, 0);
;         }
;       }
; #pragma unroll
;       for (int tc = 0; tc < 4; ++tc)
; #pragma unroll
;         for (int reg = 0; reg < 4; ++reg) {
;           const int tl = wid * 16 + (lane >> 4) * 4 + reg;
;           const int c = 16 * tc + (lane & 15);
;           const float r = __builtin_amdgcn_rcpf(1.f + __builtin_amdgcn_exp2f(acc[tc][reg] + ba[tc]));
;           const float ii = __builtin_amdgcn_rcpf(1.f + __builtin_amdgcn_exp2f(acc[tc + 4][reg] + bi[tc]));
;           const float la = -c8[tc] * r;
;           const float a = __builtin_amdgcn_exp2f(la);
;           const float ucv = bf2f(sm_uc[(sb * 64 + tl) * LDSS + c]);
;           const float bt = __builtin_amdgcn_sqrtf(fmaxf(1.f - a * a, 0.f)) * (ii * ucv);
	v_mfma_f32_16x16x32_bf16 v[28:31], v[126:129], v[242:245], v[28:31]
	v_mfma_f32_16x16x32_bf16 v[118:121], v[126:129], v[194:197], v[118:121]
	s_lshl_b32 s0, s56, 8
	s_add_u32 s0, s0, 0x20000
	s_add_u32 s4, s20, s0
	s_addc_u32 s5, s21, 0
	global_load_dwordx4 v[238:241], v251, s[4:5]
	global_load_dwordx4 v[242:245], v251, s[4:5] offset:64
	s_add_u32 s4, s4, 0x2000
	s_addc_u32 s5, s5, 0
	global_load_dwordx4 v[246:249], v251, s[4:5]
	global_load_dwordx4 v[194:197], v251, s[4:5] offset:64
	s_nop 7
	s_nop 7
	v_add_f32_e32 v0, v0, v75
	v_add_f32_e32 v1, v1, v75
	v_add_f32_e32 v2, v2, v75
	v_add_f32_e32 v3, v3, v75
	v_add_f32_e32 v90, v90, v84
	v_add_f32_e32 v91, v91, v84
	v_add_f32_e32 v92, v92, v84
	v_add_f32_e32 v93, v93, v84
	v_exp_f32_e32 v0, v0
	v_exp_f32_e32 v1, v1
	v_exp_f32_e32 v2, v2
	v_exp_f32_e32 v3, v3
	v_exp_f32_e32 v90, v90
	v_exp_f32_e32 v91, v91
	v_exp_f32_e32 v92, v92
	v_exp_f32_e32 v93, v93
	v_add_f32_e32 v0, 1.0, v0
	v_add_f32_e32 v1, 1.0, v1
	v_add_f32_e32 v2, 1.0, v2
	v_add_f32_e32 v3, 1.0, v3
	v_add_f32_e32 v90, 1.0, v90
	v_add_f32_e32 v91, 1.0, v91
	v_add_f32_e32 v92, 1.0, v92
	v_add_f32_e32 v93, 1.0, v93
	v_rcp_f32_e32 v0, v0
	v_rcp_f32_e32 v1, v1
	v_rcp_f32_e32 v2, v2
	v_rcp_f32_e32 v3, v3
	v_rcp_f32_e32 v90, v90
	v_rcp_f32_e32 v91, v91
	v_rcp_f32_e32 v92, v92
	v_rcp_f32_e32 v93, v93
	v_mul_f32_e32 v0, v85, v0
	v_mul_f32_e32 v1, v85, v1
	v_mul_f32_e32 v2, v85, v2
	v_mul_f32_e32 v3, v85, v3
	v_mul_f32_e32 v90, v90, v162
	v_mul_f32_e32 v91, v91, v163
	v_mul_f32_e32 v92, v92, v164
	v_mul_f32_e32 v93, v93, v165
	v_exp_f32_e32 v0, v0
	v_exp_f32_e32 v1, v1
	v_exp_f32_e32 v2, v2
	v_exp_f32_e32 v3, v3
	s_nop 0
	v_fma_f32 v138, -v0, v0, 1.0
	v_fma_f32 v139, -v1, v1, 1.0
	v_fma_f32 v140, -v2, v2, 1.0
	v_fma_f32 v141, -v3, v3, 1.0
	v_max_f32_e32 v138, 0, v138
	v_max_f32_e32 v139, 0, v139
	v_max_f32_e32 v140, 0, v140
	v_max_f32_e32 v141, 0, v141
	v_sqrt_f32_e32 v138, v138
	v_sqrt_f32_e32 v139, v139
	v_sqrt_f32_e32 v140, v140
	v_sqrt_f32_e32 v141, v141
	s_nop 0
	v_mul_f32_e32 v90, v138, v90
	v_mul_f32_e32 v91, v139, v91
	v_mul_f32_e32 v92, v140, v92
	v_mul_f32_e32 v93, v141, v93
	v_add_f32_e32 v4, v4, v75
	v_add_f32_e32 v5, v5, v75
	v_add_f32_e32 v6, v6, v75
	v_add_f32_e32 v7, v7, v75
	v_add_f32_e32 v94, v94, v84
	v_add_f32_e32 v95, v95, v84
	v_add_f32_e32 v96, v96, v84
	v_add_f32_e32 v97, v97, v84
	v_exp_f32_e32 v4, v4
	v_exp_f32_e32 v5, v5
	v_exp_f32_e32 v6, v6
	v_exp_f32_e32 v7, v7
	v_exp_f32_e32 v94, v94
	v_exp_f32_e32 v95, v95
	v_exp_f32_e32 v96, v96
	v_exp_f32_e32 v97, v97
	v_add_f32_e32 v4, 1.0, v4
	v_add_f32_e32 v5, 1.0, v5
	v_add_f32_e32 v6, 1.0, v6
	v_add_f32_e32 v7, 1.0, v7
	v_add_f32_e32 v94, 1.0, v94
	v_add_f32_e32 v95, 1.0, v95
	v_add_f32_e32 v96, 1.0, v96
	v_add_f32_e32 v97, 1.0, v97
	v_rcp_f32_e32 v4, v4
	v_rcp_f32_e32 v5, v5
	v_rcp_f32_e32 v6, v6
	v_rcp_f32_e32 v7, v7
	v_rcp_f32_e32 v94, v94
	v_rcp_f32_e32 v95, v95
	v_rcp_f32_e32 v96, v96
	v_rcp_f32_e32 v97, v97
	v_mul_f32_e32 v4, v85, v4
	v_mul_f32_e32 v5, v85, v5
	v_mul_f32_e32 v6, v85, v6
	v_mul_f32_e32 v7, v85, v7
	v_mul_f32_e32 v94, v94, v166
	v_mul_f32_e32 v95, v95, v167
	v_mul_f32_e32 v96, v96, v168
	v_mul_f32_e32 v97, v97, v169
	v_exp_f32_e32 v4, v4
	v_exp_f32_e32 v5, v5
	v_exp_f32_e32 v6, v6
	v_exp_f32_e32 v7, v7
	s_nop 0
	v_fma_f32 v138, -v4, v4, 1.0
	v_fma_f32 v139, -v5, v5, 1.0
	v_fma_f32 v140, -v6, v6, 1.0
	v_fma_f32 v141, -v7, v7, 1.0
	v_max_f32_e32 v138, 0, v138
	v_max_f32_e32 v139, 0, v139
	v_max_f32_e32 v140, 0, v140
	v_max_f32_e32 v141, 0, v141
	v_sqrt_f32_e32 v138, v138
	v_sqrt_f32_e32 v139, v139
	v_sqrt_f32_e32 v140, v140
	v_sqrt_f32_e32 v141, v141
	s_nop 0
	v_mul_f32_e32 v94, v138, v94
	v_mul_f32_e32 v95, v139, v95
	v_mul_f32_e32 v96, v140, v96
	v_mul_f32_e32 v97, v141, v97
	v_add_f32_e32 v8, v8, v75
	v_add_f32_e32 v9, v9, v75
	v_add_f32_e32 v10, v10, v75
	v_add_f32_e32 v11, v11, v75
	v_add_f32_e32 v98, v98, v84
	v_add_f32_e32 v99, v99, v84
	v_add_f32_e32 v100, v100, v84
	v_add_f32_e32 v101, v101, v84
	v_exp_f32_e32 v8, v8
	v_exp_f32_e32 v9, v9
	v_exp_f32_e32 v10, v10
	v_exp_f32_e32 v11, v11
	v_exp_f32_e32 v98, v98
	v_exp_f32_e32 v99, v99
	v_exp_f32_e32 v100, v100
	v_exp_f32_e32 v101, v101
	v_add_f32_e32 v8, 1.0, v8
	v_add_f32_e32 v9, 1.0, v9
	v_add_f32_e32 v10, 1.0, v10
	v_add_f32_e32 v11, 1.0, v11
	v_add_f32_e32 v98, 1.0, v98
	v_add_f32_e32 v99, 1.0, v99
	v_add_f32_e32 v100, 1.0, v100
	v_add_f32_e32 v101, 1.0, v101
	v_rcp_f32_e32 v8, v8
	v_rcp_f32_e32 v9, v9
	v_rcp_f32_e32 v10, v10
	v_rcp_f32_e32 v11, v11
	v_rcp_f32_e32 v98, v98
	v_rcp_f32_e32 v99, v99
	v_rcp_f32_e32 v100, v100
	v_rcp_f32_e32 v101, v101
	v_mul_f32_e32 v8, v85, v8
	v_mul_f32_e32 v9, v85, v9
	v_mul_f32_e32 v10, v85, v10
	v_mul_f32_e32 v11, v85, v11
	v_mul_f32_e32 v98, v98, v170
	v_mul_f32_e32 v99, v99, v171
	v_mul_f32_e32 v100, v100, v172
	v_mul_f32_e32 v101, v101, v173
	v_exp_f32_e32 v8, v8
	v_exp_f32_e32 v9, v9
	v_exp_f32_e32 v10, v10
	v_exp_f32_e32 v11, v11
	s_nop 0
	v_fma_f32 v138, -v8, v8, 1.0
	v_fma_f32 v139, -v9, v9, 1.0
	v_fma_f32 v140, -v10, v10, 1.0
	v_fma_f32 v141, -v11, v11, 1.0
	v_max_f32_e32 v138, 0, v138
	v_max_f32_e32 v139, 0, v139
	v_max_f32_e32 v140, 0, v140
	v_max_f32_e32 v141, 0, v141
	v_sqrt_f32_e32 v138, v138
	v_sqrt_f32_e32 v139, v139
	v_sqrt_f32_e32 v140, v140
	v_sqrt_f32_e32 v141, v141
	s_nop 0
	v_mul_f32_e32 v98, v138, v98
	v_mul_f32_e32 v99, v139, v99
	v_mul_f32_e32 v100, v140, v100
	v_mul_f32_e32 v101, v141, v101
	v_add_f32_e32 v12, v12, v75
	v_add_f32_e32 v13, v13, v75
	v_add_f32_e32 v14, v14, v75
	v_add_f32_e32 v15, v15, v75
	v_add_f32_e32 v102, v102, v84
	v_add_f32_e32 v103, v103, v84
	v_add_f32_e32 v104, v104, v84
	v_add_f32_e32 v105, v105, v84
; __device__ __forceinline__ float bf2f(u16 h) { return __uint_as_float(((unsigned)h) << 16); }
; __device__ __forceinline__ void lru_tile(const Params& P, int chunk, int head, int pass, char* smem_raw) {
;     ...
;           const float r = __builtin_amdgcn_rcpf(1.f + __builtin_amdgcn_exp2f(acc[tc][reg] + ba[tc]));
;           const float ii = __builtin_amdgcn_rcpf(1.f + __builtin_amdgcn_exp2f(acc[tc + 4][reg] + bi[tc]));
;           const float la = -c8[tc] * r;
;           const float a = __builtin_amdgcn_exp2f(la);
;           const float ucv = bf2f(sm_uc[(sb * 64 + tl) * LDSS + c]);
;           const float bt = __builtin_amdgcn_sqrtf(fmaxf(1.f - a * a, 0.f)) * (ii * ucv);
	v_exp_f32_e32 v12, v12
	v_exp_f32_e32 v13, v13
	v_exp_f32_e32 v14, v14
	v_exp_f32_e32 v15, v15
	v_exp_f32_e32 v102, v102
	v_exp_f32_e32 v103, v103
	v_exp_f32_e32 v104, v104
	v_exp_f32_e32 v105, v105
	v_add_f32_e32 v12, 1.0, v12
	v_add_f32_e32 v13, 1.0, v13
	v_add_f32_e32 v14, 1.0, v14
	v_add_f32_e32 v15, 1.0, v15
	v_add_f32_e32 v102, 1.0, v102
	v_add_f32_e32 v103, 1.0, v103
	v_add_f32_e32 v104, 1.0, v104
	v_add_f32_e32 v105, 1.0, v105
	v_rcp_f32_e32 v12, v12
	v_rcp_f32_e32 v13, v13
	v_rcp_f32_e32 v14, v14
	v_rcp_f32_e32 v15, v15
	v_rcp_f32_e32 v102, v102
	v_rcp_f32_e32 v103, v103
	v_rcp_f32_e32 v104, v104
	v_rcp_f32_e32 v105, v105
	v_mul_f32_e32 v12, v85, v12
	v_mul_f32_e32 v13, v85, v13
	v_mul_f32_e32 v14, v85, v14
	v_mul_f32_e32 v15, v85, v15
	v_mul_f32_e32 v102, v102, v174
	v_mul_f32_e32 v103, v103, v175
	v_mul_f32_e32 v104, v104, v176
	v_mul_f32_e32 v105, v105, v177
	v_exp_f32_e32 v12, v12
	v_exp_f32_e32 v13, v13
	v_exp_f32_e32 v14, v14
	v_exp_f32_e32 v15, v15
	s_nop 0
	v_fma_f32 v138, -v12, v12, 1.0
	v_fma_f32 v139, -v13, v13, 1.0
	v_fma_f32 v140, -v14, v14, 1.0
	v_fma_f32 v141, -v15, v15, 1.0
	v_max_f32_e32 v138, 0, v138
	v_max_f32_e32 v139, 0, v139
	v_max_f32_e32 v140, 0, v140
	v_max_f32_e32 v141, 0, v141
	v_sqrt_f32_e32 v138, v138
	v_sqrt_f32_e32 v139, v139
	v_sqrt_f32_e32 v140, v140
	v_sqrt_f32_e32 v141, v141
	s_nop 0
	v_mul_f32_e32 v102, v138, v102
	v_mul_f32_e32 v103, v139, v103
	v_mul_f32_e32 v104, v140, v104
	v_mul_f32_e32 v105, v141, v105
	v_add_f32_e32 v16, v16, v75
	v_add_f32_e32 v17, v17, v75
	v_add_f32_e32 v18, v18, v75
	v_add_f32_e32 v19, v19, v75
	v_add_f32_e32 v106, v106, v84
	v_add_f32_e32 v107, v107, v84
	v_add_f32_e32 v108, v108, v84
	v_add_f32_e32 v109, v109, v84
	v_exp_f32_e32 v16, v16
	v_exp_f32_e32 v17, v17
	v_exp_f32_e32 v18, v18
	v_exp_f32_e32 v19, v19
	v_exp_f32_e32 v106, v106
	v_exp_f32_e32 v107, v107
	v_exp_f32_e32 v108, v108
	v_exp_f32_e32 v109, v109
	v_add_f32_e32 v16, 1.0, v16
	v_add_f32_e32 v17, 1.0, v17
	v_add_f32_e32 v18, 1.0, v18
	v_add_f32_e32 v19, 1.0, v19
	v_add_f32_e32 v106, 1.0, v106
	v_add_f32_e32 v107, 1.0, v107
	v_add_f32_e32 v108, 1.0, v108
	v_add_f32_e32 v109, 1.0, v109
	v_rcp_f32_e32 v16, v16
	v_rcp_f32_e32 v17, v17
	v_rcp_f32_e32 v18, v18
	v_rcp_f32_e32 v19, v19
	v_rcp_f32_e32 v106, v106
	v_rcp_f32_e32 v107, v107
	v_rcp_f32_e32 v108, v108
	v_rcp_f32_e32 v109, v109
	v_mul_f32_e32 v16, v85, v16
	v_mul_f32_e32 v17, v85, v17
	v_mul_f32_e32 v18, v85, v18
	v_mul_f32_e32 v19, v85, v19
	v_mul_f32_e32 v106, v106, v178
	v_mul_f32_e32 v107, v107, v179
	v_mul_f32_e32 v108, v108, v180
	v_mul_f32_e32 v109, v109, v181
	v_exp_f32_e32 v16, v16
	v_exp_f32_e32 v17, v17
	v_exp_f32_e32 v18, v18
	v_exp_f32_e32 v19, v19
	s_nop 0
	v_fma_f32 v138, -v16, v16, 1.0
	v_fma_f32 v139, -v17, v17, 1.0
	v_fma_f32 v140, -v18, v18, 1.0
	v_fma_f32 v141, -v19, v19, 1.0
	v_max_f32_e32 v138, 0, v138
	v_max_f32_e32 v139, 0, v139
	v_max_f32_e32 v140, 0, v140
	v_max_f32_e32 v141, 0, v141
	v_sqrt_f32_e32 v138, v138
	v_sqrt_f32_e32 v139, v139
	v_sqrt_f32_e32 v140, v140
	v_sqrt_f32_e32 v141, v141
	s_nop 0
	v_mul_f32_e32 v106, v138, v106
	v_mul_f32_e32 v107, v139, v107
	v_mul_f32_e32 v108, v140, v108
	v_mul_f32_e32 v109, v141, v109
	v_add_f32_e32 v20, v20, v75
	v_add_f32_e32 v21, v21, v75
	v_add_f32_e32 v22, v22, v75
	v_add_f32_e32 v23, v23, v75
	v_add_f32_e32 v110, v110, v84
	v_add_f32_e32 v111, v111, v84
	v_add_f32_e32 v112, v112, v84
	v_add_f32_e32 v113, v113, v84
	v_exp_f32_e32 v20, v20
	v_exp_f32_e32 v21, v21
	v_exp_f32_e32 v22, v22
	v_exp_f32_e32 v23, v23
	v_exp_f32_e32 v110, v110
	v_exp_f32_e32 v111, v111
	v_exp_f32_e32 v112, v112
	v_exp_f32_e32 v113, v113
	v_add_f32_e32 v20, 1.0, v20
	v_add_f32_e32 v21, 1.0, v21
	v_add_f32_e32 v22, 1.0, v22
	v_add_f32_e32 v23, 1.0, v23
	v_add_f32_e32 v110, 1.0, v110
	v_add_f32_e32 v111, 1.0, v111
	v_add_f32_e32 v112, 1.0, v112
	v_add_f32_e32 v113, 1.0, v113
	v_rcp_f32_e32 v20, v20
	v_rcp_f32_e32 v21, v21
	v_rcp_f32_e32 v22, v22
	v_rcp_f32_e32 v23, v23
	v_rcp_f32_e32 v110, v110
	v_rcp_f32_e32 v111, v111
	v_rcp_f32_e32 v112, v112
	v_rcp_f32_e32 v113, v113
	v_mul_f32_e32 v20, v85, v20
	v_mul_f32_e32 v21, v85, v21
	v_mul_f32_e32 v22, v85, v22
	v_mul_f32_e32 v23, v85, v23
	v_mul_f32_e32 v110, v110, v182
	v_mul_f32_e32 v111, v111, v183
	v_mul_f32_e32 v112, v112, v184
	v_mul_f32_e32 v113, v113, v185
	v_exp_f32_e32 v20, v20
	v_exp_f32_e32 v21, v21
	v_exp_f32_e32 v22, v22
	v_exp_f32_e32 v23, v23
	s_nop 0
	v_fma_f32 v138, -v20, v20, 1.0
	v_fma_f32 v139, -v21, v21, 1.0
	v_fma_f32 v140, -v22, v22, 1.0
	v_fma_f32 v141, -v23, v23, 1.0
	v_max_f32_e32 v138, 0, v138
	v_max_f32_e32 v139, 0, v139
	v_max_f32_e32 v140, 0, v140
	v_max_f32_e32 v141, 0, v141
	v_sqrt_f32_e32 v138, v138
	v_sqrt_f32_e32 v139, v139
	v_sqrt_f32_e32 v140, v140
	v_sqrt_f32_e32 v141, v141
	s_nop 0
	v_mul_f32_e32 v110, v138, v110
	v_mul_f32_e32 v111, v139, v111
	v_mul_f32_e32 v112, v140, v112
	v_mul_f32_e32 v113, v141, v113
	v_add_f32_e32 v24, v24, v75
	v_add_f32_e32 v25, v25, v75
	v_add_f32_e32 v26, v26, v75
	v_add_f32_e32 v27, v27, v75
	v_add_f32_e32 v114, v114, v84
	v_add_f32_e32 v115, v115, v84
	v_add_f32_e32 v116, v116, v84
	v_add_f32_e32 v117, v117, v84
	v_exp_f32_e32 v24, v24
	v_exp_f32_e32 v25, v25
	v_exp_f32_e32 v26, v26
	v_exp_f32_e32 v27, v27
	v_exp_f32_e32 v114, v114
	v_exp_f32_e32 v115, v115
	v_exp_f32_e32 v116, v116
	v_exp_f32_e32 v117, v117
	v_add_f32_e32 v24, 1.0, v24
	v_add_f32_e32 v25, 1.0, v25
	v_add_f32_e32 v26, 1.0, v26
	v_add_f32_e32 v27, 1.0, v27
	v_add_f32_e32 v114, 1.0, v114
	v_add_f32_e32 v115, 1.0, v115
	v_add_f32_e32 v116, 1.0, v116
	v_add_f32_e32 v117, 1.0, v117
	v_rcp_f32_e32 v24, v24
	v_rcp_f32_e32 v25, v25
; __device__ __forceinline__ float bf2f(u16 h) { return __uint_as_float(((unsigned)h) << 16); }
; __device__ __forceinline__ void lru_tile(const Params& P, int chunk, int head, int pass, char* smem_raw) {
;     ...
;           const float r = __builtin_amdgcn_rcpf(1.f + __builtin_amdgcn_exp2f(acc[tc][reg] + ba[tc]));
;           const float ii = __builtin_amdgcn_rcpf(1.f + __builtin_amdgcn_exp2f(acc[tc + 4][reg] + bi[tc]));
;           const float la = -c8[tc] * r;
;           const float a = __builtin_amdgcn_exp2f(la);
;           const float ucv = bf2f(sm_uc[(sb * 64 + tl) * LDSS + c]);
;           const float bt = __builtin_amdgcn_sqrtf(fmaxf(1.f - a * a, 0.f)) * (ii * ucv);
;           sm_a[tl * 64 + c] = a;
;           sm_b[tl * 64 + c] = bt;
;         }
;       __syncthreads();
;       const int pos = (d == 0) ? q : 3 - q;
;       {
;         float Pp = 1.f, H = 0.f;
; #pragma unroll 4
;         for (int i = 0; i < 16; ++i) {
;           const int tl = (d == 0) ? (q * 16 + i) : (q * 16 + 15 - i);
;           const float a = sm_a[tl * 64 + ch], b = sm_b[tl * 64 + ch];
;           H = a * H + b; Pp *= a;
;         }
;         sm_ph[pos * 64 + ch] = make_float2(Pp, H);
;       }
;       __syncthreads();
;       const float2 p0 = sm_ph[ch], p1 = sm_ph[64 + ch], p2 = sm_ph[128 + ch], p3 = sm_ph[192 + ch];
;     ...
;       cB = p0.x * cB + p0.y; cA *= p0.x;
;       cB = p1.x * cB + p1.y; cA *= p1.x;
;       cB = p2.x * cB + p2.y; cA *= p2.x;
;       cB = p3.x * cB + p3.y; cA *= p3.x;
;       __syncthreads();
;     }
;     if (pass == 1 && q == 0) P.summ[((long)d * 264 + chunk) * 512 + gch] = make_float2(cA, cB);
	v_rcp_f32_e32 v26, v26
	v_rcp_f32_e32 v27, v27
	v_rcp_f32_e32 v114, v114
	v_rcp_f32_e32 v115, v115
	v_rcp_f32_e32 v116, v116
	v_rcp_f32_e32 v117, v117
	v_mul_f32_e32 v24, v85, v24
	v_mul_f32_e32 v25, v85, v25
	v_mul_f32_e32 v26, v85, v26
	v_mul_f32_e32 v27, v85, v27
	v_mul_f32_e32 v114, v114, v186
	v_mul_f32_e32 v115, v115, v187
	v_mul_f32_e32 v116, v116, v188
	v_mul_f32_e32 v117, v117, v189
	v_exp_f32_e32 v24, v24
	v_exp_f32_e32 v25, v25
	v_exp_f32_e32 v26, v26
	v_exp_f32_e32 v27, v27
	s_nop 0
	v_fma_f32 v138, -v24, v24, 1.0
	v_fma_f32 v139, -v25, v25, 1.0
	v_fma_f32 v140, -v26, v26, 1.0
	v_fma_f32 v141, -v27, v27, 1.0
	v_max_f32_e32 v138, 0, v138
	v_max_f32_e32 v139, 0, v139
	v_max_f32_e32 v140, 0, v140
	v_max_f32_e32 v141, 0, v141
	v_sqrt_f32_e32 v138, v138
	v_sqrt_f32_e32 v139, v139
	v_sqrt_f32_e32 v140, v140
	v_sqrt_f32_e32 v141, v141
	s_nop 0
	v_mul_f32_e32 v114, v138, v114
	v_mul_f32_e32 v115, v139, v115
	v_mul_f32_e32 v116, v140, v116
	v_mul_f32_e32 v117, v141, v117
	v_add_f32_e32 v28, v28, v75
	v_add_f32_e32 v29, v29, v75
	v_add_f32_e32 v30, v30, v75
	v_add_f32_e32 v31, v31, v75
	v_add_f32_e32 v118, v118, v84
	v_add_f32_e32 v119, v119, v84
	v_add_f32_e32 v120, v120, v84
	v_add_f32_e32 v121, v121, v84
	v_exp_f32_e32 v28, v28
	v_exp_f32_e32 v29, v29
	v_exp_f32_e32 v30, v30
	v_exp_f32_e32 v31, v31
	v_exp_f32_e32 v118, v118
	v_exp_f32_e32 v119, v119
	v_exp_f32_e32 v120, v120
	v_exp_f32_e32 v121, v121
	v_add_f32_e32 v28, 1.0, v28
	v_add_f32_e32 v29, 1.0, v29
	v_add_f32_e32 v30, 1.0, v30
	v_add_f32_e32 v31, 1.0, v31
	v_add_f32_e32 v118, 1.0, v118
	v_add_f32_e32 v119, 1.0, v119
	v_add_f32_e32 v120, 1.0, v120
	v_add_f32_e32 v121, 1.0, v121
	v_rcp_f32_e32 v28, v28
	v_rcp_f32_e32 v29, v29
	v_rcp_f32_e32 v30, v30
	v_rcp_f32_e32 v31, v31
	v_rcp_f32_e32 v118, v118
	v_rcp_f32_e32 v119, v119
	v_rcp_f32_e32 v120, v120
	v_rcp_f32_e32 v121, v121
	v_mul_f32_e32 v28, v85, v28
	v_mul_f32_e32 v29, v85, v29
	v_mul_f32_e32 v30, v85, v30
	v_mul_f32_e32 v31, v85, v31
	v_mul_f32_e32 v118, v118, v190
	v_mul_f32_e32 v119, v119, v191
	v_mul_f32_e32 v120, v120, v192
	v_mul_f32_e32 v121, v121, v193
	v_exp_f32_e32 v28, v28
	v_exp_f32_e32 v29, v29
	v_exp_f32_e32 v30, v30
	v_exp_f32_e32 v31, v31
	s_nop 0
	v_fma_f32 v138, -v28, v28, 1.0
	v_fma_f32 v139, -v29, v29, 1.0
	v_fma_f32 v140, -v30, v30, 1.0
	v_fma_f32 v141, -v31, v31, 1.0
	v_max_f32_e32 v138, 0, v138
	v_max_f32_e32 v139, 0, v139
	v_max_f32_e32 v140, 0, v140
	v_max_f32_e32 v141, 0, v141
	v_sqrt_f32_e32 v138, v138
	v_sqrt_f32_e32 v139, v139
	v_sqrt_f32_e32 v140, v140
	v_sqrt_f32_e32 v141, v141
	s_nop 0
	v_mul_f32_e32 v118, v138, v118
	v_mul_f32_e32 v119, v139, v119
	v_mul_f32_e32 v120, v140, v120
	v_mul_f32_e32 v121, v141, v121
	v_mov_b32_e32 v253, v0
	v_mov_b32_e32 v254, v90
	v_fma_f32 v254, v1, v254, v91
	v_mul_f32_e32 v253, v253, v1
	v_fma_f32 v254, v2, v254, v92
	v_mul_f32_e32 v253, v253, v2
	v_fma_f32 v254, v3, v254, v93
	v_mul_f32_e32 v253, v253, v3
	v_fma_f32 v254, v4, v254, v94
	v_mul_f32_e32 v253, v253, v4
	v_fma_f32 v254, v5, v254, v95
	v_mul_f32_e32 v253, v253, v5
	v_fma_f32 v254, v6, v254, v96
	v_mul_f32_e32 v253, v253, v6
	v_fma_f32 v254, v7, v254, v97
	v_mul_f32_e32 v253, v253, v7
	v_fma_f32 v254, v8, v254, v98
	v_mul_f32_e32 v253, v253, v8
	v_fma_f32 v254, v9, v254, v99
	v_mul_f32_e32 v253, v253, v9
	v_fma_f32 v254, v10, v254, v100
	v_mul_f32_e32 v253, v253, v10
	v_fma_f32 v254, v11, v254, v101
	v_mul_f32_e32 v253, v253, v11
	v_fma_f32 v254, v12, v254, v102
	v_mul_f32_e32 v253, v253, v12
	v_fma_f32 v254, v13, v254, v103
	v_mul_f32_e32 v253, v253, v13
	v_fma_f32 v254, v14, v254, v104
	v_mul_f32_e32 v253, v253, v14
	v_fma_f32 v254, v15, v254, v105
	v_mul_f32_e32 v253, v253, v15
	v_fma_f32 v254, v16, v254, v106
	v_mul_f32_e32 v253, v253, v16
	v_fma_f32 v254, v17, v254, v107
	v_mul_f32_e32 v253, v253, v17
	v_fma_f32 v254, v18, v254, v108
	v_mul_f32_e32 v253, v253, v18
	v_fma_f32 v254, v19, v254, v109
	v_mul_f32_e32 v253, v253, v19
	v_fma_f32 v254, v20, v254, v110
	v_mul_f32_e32 v253, v253, v20
	v_fma_f32 v254, v21, v254, v111
	v_mul_f32_e32 v253, v253, v21
	v_fma_f32 v254, v22, v254, v112
	v_mul_f32_e32 v253, v253, v22
	v_fma_f32 v254, v23, v254, v113
	v_mul_f32_e32 v253, v253, v23
	v_fma_f32 v254, v24, v254, v114
	v_mul_f32_e32 v253, v253, v24
	v_fma_f32 v254, v25, v254, v115
	v_mul_f32_e32 v253, v253, v25
	v_fma_f32 v254, v26, v254, v116
	v_mul_f32_e32 v253, v253, v26
	v_fma_f32 v254, v27, v254, v117
	v_mul_f32_e32 v253, v253, v27
	v_fma_f32 v254, v28, v254, v118
	v_mul_f32_e32 v253, v253, v28
	v_fma_f32 v254, v29, v254, v119
	v_mul_f32_e32 v253, v253, v29
	v_fma_f32 v254, v30, v254, v120
	v_mul_f32_e32 v253, v253, v30
	v_fma_f32 v254, v31, v254, v121
	v_mul_f32_e32 v253, v253, v31
	v_mov_b32_e32 v138, v253
	v_mov_b32_e32 v139, v253
	s_nop 1
	v_permlane16_swap_b32_e32 v138, v139
	v_mov_b32_e32 v140, v138
	v_mov_b32_e32 v141, v139
	s_nop 1
	v_permlane32_swap_b32_e32 v138, v140
	v_permlane32_swap_b32_e32 v139, v141
	v_mov_b32_e32 v198, v254
	v_mov_b32_e32 v199, v254
	s_nop 1
	v_permlane16_swap_b32_e32 v198, v199
	v_mov_b32_e32 v200, v198
	v_mov_b32_e32 v201, v199
	s_nop 1
	v_permlane32_swap_b32_e32 v198, v200
	v_permlane32_swap_b32_e32 v199, v201
	v_mov_b32_e32 v136, 0
	v_fma_f32 v150, v138, v136, v198
	v_fma_f32 v151, v139, v150, v199
	v_fma_f32 v202, v140, v151, v200
	v_fma_f32 v254, v141, v202, v201
	v_mul_f32_e32 v253, v138, v139
	v_mul_f32_e32 v253, v253, v140
	v_mul_f32_e32 v200, v253, v141
	v_mov_b32_e32 v201, v254
	s_add_u32 s0, s71, 0
	s_lshl_b32 s0, s0, 12
	s_lshl_b32 s1, s56, 3
	s_add_u32 s0, s0, s1
	s_add_u32 s4, s18, s0
	s_addc_u32 s5, s19, 0
	global_store_dwordx2 v250, v[200:201], s[4:5]
	ds_read_b128 v[76:79], v131 offset:0
	ds_read_b128 v[80:83], v133 offset:0
	ds_read_b128 v[122:125], v131 offset:512
	ds_read_b128 v[126:129], v133 offset:512
	s_waitcnt vmcnt(1)
; __device__ __forceinline__ float bf2f(u16 h) { return __uint_as_float(((unsigned)h) << 16); }
; __device__ __forceinline__ void lru_tile(const Params& P, int chunk, int head, int pass, char* smem_raw) {
;     ...
; #pragma unroll
;       for (int t = 0; t < 8; ++t) acc[t] = f32x4{0.f, 0.f, 0.f, 0.f};
; #pragma unroll
;       for (int s = 0; s < 2; ++s) {
;         const bf16x8 af = *reinterpret_cast<const bf16x8*>(&sm_uc[(sb * 64 + wid * 16 + (lane & 15)) * LDSS + s * 32 + (lane >> 4) * 8]);
; #pragma unroll
;         for (int t = 0; t < 8; ++t) {
;           const bf16x8 bfr = *reinterpret_cast<const bf16x8*>(&sm_w[(t * 16 + (lane & 15)) * LDSS + s * 32 + (lane >> 4) * 8]);
;           acc[t] = __builtin_amdgcn_mfma_f32_16x16x32_bf16(af, bfr, acc[t], 0, 0, 0);
;         }
;       }
; #pragma unroll
;       for (int tc = 0; tc < 4; ++tc)
; #pragma unroll
;         for (int reg = 0; reg < 4; ++reg) {
;           const int tl = wid * 16 + (lane >> 4) * 4 + reg;
;           const int c = 16 * tc + (lane & 15);
;           const float r = __builtin_amdgcn_rcpf(1.f + __builtin_amdgcn_exp2f(acc[tc][reg] + ba[tc]));
;           const float ii = __builtin_amdgcn_rcpf(1.f + __builtin_amdgcn_exp2f(acc[tc + 4][reg] + bi[tc]));
;           const float la = -c8[tc] * r;
;           const float a = __builtin_amdgcn_exp2f(la);
;           const float ucv = bf2f(sm_uc[(sb * 64 + tl) * LDSS + c]);
;           const float bt = __builtin_amdgcn_sqrtf(fmaxf(1.f - a * a, 0.f)) * (ii * ucv);
	s_waitcnt lgkmcnt(3)
	v_mfma_f32_16x16x32_bf16 v[0:3], v[76:79], v[238:241], 0
	v_mfma_f32_16x16x32_bf16 v[90:93], v[76:79], v[246:249], 0
	ds_read_b128 v[76:79], v131 offset:1024
	s_waitcnt lgkmcnt(3)
	v_mfma_f32_16x16x32_bf16 v[0:3], v[80:83], v[242:245], v[0:3]
	v_mfma_f32_16x16x32_bf16 v[90:93], v[80:83], v[194:197], v[90:93]
	ds_read_b128 v[80:83], v133 offset:1024
	s_waitcnt lgkmcnt(3)
	v_mfma_f32_16x16x32_bf16 v[4:7], v[122:125], v[238:241], 0
	v_mfma_f32_16x16x32_bf16 v[94:97], v[122:125], v[246:249], 0
	ds_read_b128 v[122:125], v131 offset:1536
	s_waitcnt lgkmcnt(3)
	v_mfma_f32_16x16x32_bf16 v[4:7], v[126:129], v[242:245], v[4:7]
	v_mfma_f32_16x16x32_bf16 v[94:97], v[126:129], v[194:197], v[94:97]
	ds_read_b128 v[126:129], v133 offset:1536
	s_waitcnt lgkmcnt(3)
	v_mfma_f32_16x16x32_bf16 v[8:11], v[76:79], v[238:241], 0
	v_mfma_f32_16x16x32_bf16 v[98:101], v[76:79], v[246:249], 0
	ds_read_b128 v[76:79], v131 offset:2048
	s_waitcnt lgkmcnt(3)
	v_mfma_f32_16x16x32_bf16 v[8:11], v[80:83], v[242:245], v[8:11]
	v_mfma_f32_16x16x32_bf16 v[98:101], v[80:83], v[194:197], v[98:101]
	ds_read_b128 v[80:83], v133 offset:2048
	s_waitcnt lgkmcnt(3)
	v_mfma_f32_16x16x32_bf16 v[12:15], v[122:125], v[238:241], 0
	v_mfma_f32_16x16x32_bf16 v[102:105], v[122:125], v[246:249], 0
	ds_read_b128 v[122:125], v131 offset:2560
	s_waitcnt lgkmcnt(3)
	v_mfma_f32_16x16x32_bf16 v[12:15], v[126:129], v[242:245], v[12:15]
	v_mfma_f32_16x16x32_bf16 v[102:105], v[126:129], v[194:197], v[102:105]
	ds_read_b128 v[126:129], v133 offset:2560
	s_waitcnt lgkmcnt(3)
	v_mfma_f32_16x16x32_bf16 v[16:19], v[76:79], v[238:241], 0
	v_mfma_f32_16x16x32_bf16 v[106:109], v[76:79], v[246:249], 0
	ds_read_b128 v[76:79], v131 offset:3072
	s_waitcnt lgkmcnt(3)
	v_mfma_f32_16x16x32_bf16 v[16:19], v[80:83], v[242:245], v[16:19]
	v_mfma_f32_16x16x32_bf16 v[106:109], v[80:83], v[194:197], v[106:109]
	ds_read_b128 v[80:83], v133 offset:3072
	s_waitcnt lgkmcnt(3)
	v_mfma_f32_16x16x32_bf16 v[20:23], v[122:125], v[238:241], 0
	v_mfma_f32_16x16x32_bf16 v[110:113], v[122:125], v[246:249], 0
	ds_read_b128 v[122:125], v131 offset:3584
	s_waitcnt lgkmcnt(3)
	v_mfma_f32_16x16x32_bf16 v[20:23], v[126:129], v[242:245], v[20:23]
	v_mfma_f32_16x16x32_bf16 v[110:113], v[126:129], v[194:197], v[110:113]
	ds_read_b128 v[126:129], v133 offset:3584
	s_waitcnt lgkmcnt(3)
	v_mfma_f32_16x16x32_bf16 v[24:27], v[76:79], v[238:241], 0
	v_mfma_f32_16x16x32_bf16 v[114:117], v[76:79], v[246:249], 0
	s_waitcnt lgkmcnt(2)
	v_mfma_f32_16x16x32_bf16 v[24:27], v[80:83], v[242:245], v[24:27]
	v_mfma_f32_16x16x32_bf16 v[114:117], v[80:83], v[194:197], v[114:117]
	s_waitcnt lgkmcnt(1)
	v_mfma_f32_16x16x32_bf16 v[28:31], v[122:125], v[238:241], 0
	v_mfma_f32_16x16x32_bf16 v[118:121], v[122:125], v[246:249], 0
	s_waitcnt lgkmcnt(0)
	v_mfma_f32_16x16x32_bf16 v[28:31], v[126:129], v[242:245], v[28:31]
	v_mfma_f32_16x16x32_bf16 v[118:121], v[126:129], v[194:197], v[118:121]
	s_lshl_b32 s0, s56, 8
	s_add_u32 s0, s0, 0x0
	s_add_u32 s4, s20, s0
	s_addc_u32 s5, s21, 0
	global_load_dwordx4 v[238:241], v251, s[4:5]
	global_load_dwordx4 v[242:245], v251, s[4:5] offset:64
	s_add_u32 s4, s4, 0x2000
	s_addc_u32 s5, s5, 0
	global_load_dwordx4 v[246:249], v251, s[4:5]
	global_load_dwordx4 v[194:197], v251, s[4:5] offset:64
	s_nop 7
	s_nop 7
	v_add_f32_e32 v0, v0, v145
	v_add_f32_e32 v1, v1, v145
	v_add_f32_e32 v2, v2, v145
	v_add_f32_e32 v3, v3, v145
	v_add_f32_e32 v90, v90, v146
	v_add_f32_e32 v91, v91, v146
	v_add_f32_e32 v92, v92, v146
	v_add_f32_e32 v93, v93, v146
	v_exp_f32_e32 v0, v0
	v_exp_f32_e32 v1, v1
	v_exp_f32_e32 v2, v2
	v_exp_f32_e32 v3, v3
	v_exp_f32_e32 v90, v90
	v_exp_f32_e32 v91, v91
	v_exp_f32_e32 v92, v92
	v_exp_f32_e32 v93, v93
	v_add_f32_e32 v0, 1.0, v0
	v_add_f32_e32 v1, 1.0, v1
	v_add_f32_e32 v2, 1.0, v2
	v_add_f32_e32 v3, 1.0, v3
	v_add_f32_e32 v90, 1.0, v90
	v_add_f32_e32 v91, 1.0, v91
	v_add_f32_e32 v92, 1.0, v92
	v_add_f32_e32 v93, 1.0, v93
	v_rcp_f32_e32 v0, v0
	v_rcp_f32_e32 v1, v1
	v_rcp_f32_e32 v2, v2
	v_rcp_f32_e32 v3, v3
	v_rcp_f32_e32 v90, v90
	v_rcp_f32_e32 v91, v91
	v_rcp_f32_e32 v92, v92
	v_rcp_f32_e32 v93, v93
	v_mul_f32_e32 v0, v147, v0
	v_mul_f32_e32 v1, v147, v1
	v_mul_f32_e32 v2, v147, v2
	v_mul_f32_e32 v3, v147, v3
	v_mul_f32_e32 v90, v90, v162
	v_mul_f32_e32 v91, v91, v163
	v_mul_f32_e32 v92, v92, v164
	v_mul_f32_e32 v93, v93, v165
	v_exp_f32_e32 v0, v0
	v_exp_f32_e32 v1, v1
	v_exp_f32_e32 v2, v2
	v_exp_f32_e32 v3, v3
	s_nop 0
	v_fma_f32 v138, -v0, v0, 1.0
	v_fma_f32 v139, -v1, v1, 1.0
	v_fma_f32 v140, -v2, v2, 1.0
	v_fma_f32 v141, -v3, v3, 1.0
	v_max_f32_e32 v138, 0, v138
	v_max_f32_e32 v139, 0, v139
	v_max_f32_e32 v140, 0, v140
	v_max_f32_e32 v141, 0, v141
	v_sqrt_f32_e32 v138, v138
	v_sqrt_f32_e32 v139, v139
	v_sqrt_f32_e32 v140, v140
	v_sqrt_f32_e32 v141, v141
	s_nop 0
	v_mul_f32_e32 v90, v138, v90
	v_mul_f32_e32 v91, v139, v91
	v_mul_f32_e32 v92, v140, v92
	v_mul_f32_e32 v93, v141, v93
	v_add_f32_e32 v4, v4, v145
	v_add_f32_e32 v5, v5, v145
	v_add_f32_e32 v6, v6, v145
	v_add_f32_e32 v7, v7, v145
	v_add_f32_e32 v94, v94, v146
	v_add_f32_e32 v95, v95, v146
	v_add_f32_e32 v96, v96, v146
	v_add_f32_e32 v97, v97, v146
	v_exp_f32_e32 v4, v4
	v_exp_f32_e32 v5, v5
	v_exp_f32_e32 v6, v6
	v_exp_f32_e32 v7, v7
	v_exp_f32_e32 v94, v94
	v_exp_f32_e32 v95, v95
	v_exp_f32_e32 v96, v96
	v_exp_f32_e32 v97, v97
	v_add_f32_e32 v4, 1.0, v4
	v_add_f32_e32 v5, 1.0, v5
	v_add_f32_e32 v6, 1.0, v6
	v_add_f32_e32 v7, 1.0, v7
	v_add_f32_e32 v94, 1.0, v94
	v_add_f32_e32 v95, 1.0, v95
	v_add_f32_e32 v96, 1.0, v96
	v_add_f32_e32 v97, 1.0, v97
	v_rcp_f32_e32 v4, v4
	v_rcp_f32_e32 v5, v5
	v_rcp_f32_e32 v6, v6
; __device__ __forceinline__ float bf2f(u16 h) { return __uint_as_float(((unsigned)h) << 16); }
; __device__ __forceinline__ void lru_tile(const Params& P, int chunk, int head, int pass, char* smem_raw) {
;     ...
;           const float r = __builtin_amdgcn_rcpf(1.f + __builtin_amdgcn_exp2f(acc[tc][reg] + ba[tc]));
;           const float ii = __builtin_amdgcn_rcpf(1.f + __builtin_amdgcn_exp2f(acc[tc + 4][reg] + bi[tc]));
;           const float la = -c8[tc] * r;
;           const float a = __builtin_amdgcn_exp2f(la);
;           const float ucv = bf2f(sm_uc[(sb * 64 + tl) * LDSS + c]);
;           const float bt = __builtin_amdgcn_sqrtf(fmaxf(1.f - a * a, 0.f)) * (ii * ucv);
	v_rcp_f32_e32 v7, v7
	v_rcp_f32_e32 v94, v94
	v_rcp_f32_e32 v95, v95
	v_rcp_f32_e32 v96, v96
	v_rcp_f32_e32 v97, v97
	v_mul_f32_e32 v4, v147, v4
	v_mul_f32_e32 v5, v147, v5
	v_mul_f32_e32 v6, v147, v6
	v_mul_f32_e32 v7, v147, v7
	v_mul_f32_e32 v94, v94, v166
	v_mul_f32_e32 v95, v95, v167
	v_mul_f32_e32 v96, v96, v168
	v_mul_f32_e32 v97, v97, v169
	v_exp_f32_e32 v4, v4
	v_exp_f32_e32 v5, v5
	v_exp_f32_e32 v6, v6
	v_exp_f32_e32 v7, v7
	s_nop 0
	v_fma_f32 v138, -v4, v4, 1.0
	v_fma_f32 v139, -v5, v5, 1.0
	v_fma_f32 v140, -v6, v6, 1.0
	v_fma_f32 v141, -v7, v7, 1.0
	v_max_f32_e32 v138, 0, v138
	v_max_f32_e32 v139, 0, v139
	v_max_f32_e32 v140, 0, v140
	v_max_f32_e32 v141, 0, v141
	v_sqrt_f32_e32 v138, v138
	v_sqrt_f32_e32 v139, v139
	v_sqrt_f32_e32 v140, v140
	v_sqrt_f32_e32 v141, v141
	s_nop 0
	v_mul_f32_e32 v94, v138, v94
	v_mul_f32_e32 v95, v139, v95
	v_mul_f32_e32 v96, v140, v96
	v_mul_f32_e32 v97, v141, v97
	v_add_f32_e32 v8, v8, v145
	v_add_f32_e32 v9, v9, v145
	v_add_f32_e32 v10, v10, v145
	v_add_f32_e32 v11, v11, v145
	v_add_f32_e32 v98, v98, v146
	v_add_f32_e32 v99, v99, v146
	v_add_f32_e32 v100, v100, v146
	v_add_f32_e32 v101, v101, v146
	v_exp_f32_e32 v8, v8
	v_exp_f32_e32 v9, v9
	v_exp_f32_e32 v10, v10
	v_exp_f32_e32 v11, v11
	v_exp_f32_e32 v98, v98
	v_exp_f32_e32 v99, v99
	v_exp_f32_e32 v100, v100
	v_exp_f32_e32 v101, v101
	v_add_f32_e32 v8, 1.0, v8
	v_add_f32_e32 v9, 1.0, v9
	v_add_f32_e32 v10, 1.0, v10
	v_add_f32_e32 v11, 1.0, v11
	v_add_f32_e32 v98, 1.0, v98
	v_add_f32_e32 v99, 1.0, v99
	v_add_f32_e32 v100, 1.0, v100
	v_add_f32_e32 v101, 1.0, v101
	v_rcp_f32_e32 v8, v8
	v_rcp_f32_e32 v9, v9
	v_rcp_f32_e32 v10, v10
	v_rcp_f32_e32 v11, v11
	v_rcp_f32_e32 v98, v98
	v_rcp_f32_e32 v99, v99
	v_rcp_f32_e32 v100, v100
	v_rcp_f32_e32 v101, v101
	v_mul_f32_e32 v8, v147, v8
	v_mul_f32_e32 v9, v147, v9
	v_mul_f32_e32 v10, v147, v10
	v_mul_f32_e32 v11, v147, v11
	v_mul_f32_e32 v98, v98, v170
	v_mul_f32_e32 v99, v99, v171
	v_mul_f32_e32 v100, v100, v172
	v_mul_f32_e32 v101, v101, v173
	v_exp_f32_e32 v8, v8
	v_exp_f32_e32 v9, v9
	v_exp_f32_e32 v10, v10
	v_exp_f32_e32 v11, v11
	s_nop 0
	v_fma_f32 v138, -v8, v8, 1.0
	v_fma_f32 v139, -v9, v9, 1.0
	v_fma_f32 v140, -v10, v10, 1.0
	v_fma_f32 v141, -v11, v11, 1.0
	v_max_f32_e32 v138, 0, v138
	v_max_f32_e32 v139, 0, v139
	v_max_f32_e32 v140, 0, v140
	v_max_f32_e32 v141, 0, v141
	v_sqrt_f32_e32 v138, v138
	v_sqrt_f32_e32 v139, v139
	v_sqrt_f32_e32 v140, v140
	v_sqrt_f32_e32 v141, v141
	s_nop 0
	v_mul_f32_e32 v98, v138, v98
	v_mul_f32_e32 v99, v139, v99
	v_mul_f32_e32 v100, v140, v100
	v_mul_f32_e32 v101, v141, v101
	v_add_f32_e32 v12, v12, v145
	v_add_f32_e32 v13, v13, v145
	v_add_f32_e32 v14, v14, v145
	v_add_f32_e32 v15, v15, v145
	v_add_f32_e32 v102, v102, v146
	v_add_f32_e32 v103, v103, v146
	v_add_f32_e32 v104, v104, v146
	v_add_f32_e32 v105, v105, v146
	v_exp_f32_e32 v12, v12
	v_exp_f32_e32 v13, v13
	v_exp_f32_e32 v14, v14
	v_exp_f32_e32 v15, v15
	v_exp_f32_e32 v102, v102
	v_exp_f32_e32 v103, v103
	v_exp_f32_e32 v104, v104
	v_exp_f32_e32 v105, v105
	v_add_f32_e32 v12, 1.0, v12
	v_add_f32_e32 v13, 1.0, v13
	v_add_f32_e32 v14, 1.0, v14
	v_add_f32_e32 v15, 1.0, v15
	v_add_f32_e32 v102, 1.0, v102
	v_add_f32_e32 v103, 1.0, v103
	v_add_f32_e32 v104, 1.0, v104
	v_add_f32_e32 v105, 1.0, v105
	v_rcp_f32_e32 v12, v12
	v_rcp_f32_e32 v13, v13
	v_rcp_f32_e32 v14, v14
	v_rcp_f32_e32 v15, v15
	v_rcp_f32_e32 v102, v102
	v_rcp_f32_e32 v103, v103
	v_rcp_f32_e32 v104, v104
	v_rcp_f32_e32 v105, v105
	v_mul_f32_e32 v12, v147, v12
	v_mul_f32_e32 v13, v147, v13
	v_mul_f32_e32 v14, v147, v14
	v_mul_f32_e32 v15, v147, v15
	v_mul_f32_e32 v102, v102, v174
	v_mul_f32_e32 v103, v103, v175
	v_mul_f32_e32 v104, v104, v176
	v_mul_f32_e32 v105, v105, v177
	v_exp_f32_e32 v12, v12
	v_exp_f32_e32 v13, v13
	v_exp_f32_e32 v14, v14
	v_exp_f32_e32 v15, v15
	s_nop 0
	v_fma_f32 v138, -v12, v12, 1.0
	v_fma_f32 v139, -v13, v13, 1.0
	v_fma_f32 v140, -v14, v14, 1.0
	v_fma_f32 v141, -v15, v15, 1.0
	v_max_f32_e32 v138, 0, v138
	v_max_f32_e32 v139, 0, v139
	v_max_f32_e32 v140, 0, v140
	v_max_f32_e32 v141, 0, v141
	v_sqrt_f32_e32 v138, v138
	v_sqrt_f32_e32 v139, v139
	v_sqrt_f32_e32 v140, v140
	v_sqrt_f32_e32 v141, v141
	s_nop 0
	v_mul_f32_e32 v102, v138, v102
	v_mul_f32_e32 v103, v139, v103
	v_mul_f32_e32 v104, v140, v104
	v_mul_f32_e32 v105, v141, v105
	v_add_f32_e32 v16, v16, v145
	v_add_f32_e32 v17, v17, v145
	v_add_f32_e32 v18, v18, v145
	v_add_f32_e32 v19, v19, v145
	v_add_f32_e32 v106, v106, v146
	v_add_f32_e32 v107, v107, v146
	v_add_f32_e32 v108, v108, v146
	v_add_f32_e32 v109, v109, v146
	v_exp_f32_e32 v16, v16
	v_exp_f32_e32 v17, v17
	v_exp_f32_e32 v18, v18
	v_exp_f32_e32 v19, v19
	v_exp_f32_e32 v106, v106
	v_exp_f32_e32 v107, v107
	v_exp_f32_e32 v108, v108
	v_exp_f32_e32 v109, v109
	v_add_f32_e32 v16, 1.0, v16
	v_add_f32_e32 v17, 1.0, v17
	v_add_f32_e32 v18, 1.0, v18
	v_add_f32_e32 v19, 1.0, v19
	v_add_f32_e32 v106, 1.0, v106
	v_add_f32_e32 v107, 1.0, v107
	v_add_f32_e32 v108, 1.0, v108
	v_add_f32_e32 v109, 1.0, v109
	v_rcp_f32_e32 v16, v16
	v_rcp_f32_e32 v17, v17
	v_rcp_f32_e32 v18, v18
	v_rcp_f32_e32 v19, v19
	v_rcp_f32_e32 v106, v106
	v_rcp_f32_e32 v107, v107
	v_rcp_f32_e32 v108, v108
	v_rcp_f32_e32 v109, v109
	v_mul_f32_e32 v16, v147, v16
	v_mul_f32_e32 v17, v147, v17
	v_mul_f32_e32 v18, v147, v18
	v_mul_f32_e32 v19, v147, v19
	v_mul_f32_e32 v106, v106, v178
	v_mul_f32_e32 v107, v107, v179
	v_mul_f32_e32 v108, v108, v180
	v_mul_f32_e32 v109, v109, v181
	v_exp_f32_e32 v16, v16
	v_exp_f32_e32 v17, v17
	v_exp_f32_e32 v18, v18
	v_exp_f32_e32 v19, v19
	s_nop 0
	v_fma_f32 v138, -v16, v16, 1.0
	v_fma_f32 v139, -v17, v17, 1.0
; __device__ __forceinline__ float bf2f(u16 h) { return __uint_as_float(((unsigned)h) << 16); }
; __device__ __forceinline__ void lru_tile(const Params& P, int chunk, int head, int pass, char* smem_raw) {
;     ...
;           const float r = __builtin_amdgcn_rcpf(1.f + __builtin_amdgcn_exp2f(acc[tc][reg] + ba[tc]));
;           const float ii = __builtin_amdgcn_rcpf(1.f + __builtin_amdgcn_exp2f(acc[tc + 4][reg] + bi[tc]));
;           const float la = -c8[tc] * r;
;           const float a = __builtin_amdgcn_exp2f(la);
;           const float ucv = bf2f(sm_uc[(sb * 64 + tl) * LDSS + c]);
;           const float bt = __builtin_amdgcn_sqrtf(fmaxf(1.f - a * a, 0.f)) * (ii * ucv);
	v_fma_f32 v140, -v18, v18, 1.0
	v_fma_f32 v141, -v19, v19, 1.0
	v_max_f32_e32 v138, 0, v138
	v_max_f32_e32 v139, 0, v139
	v_max_f32_e32 v140, 0, v140
	v_max_f32_e32 v141, 0, v141
	v_sqrt_f32_e32 v138, v138
	v_sqrt_f32_e32 v139, v139
	v_sqrt_f32_e32 v140, v140
	v_sqrt_f32_e32 v141, v141
	s_nop 0
	v_mul_f32_e32 v106, v138, v106
	v_mul_f32_e32 v107, v139, v107
	v_mul_f32_e32 v108, v140, v108
	v_mul_f32_e32 v109, v141, v109
	v_add_f32_e32 v20, v20, v145
	v_add_f32_e32 v21, v21, v145
	v_add_f32_e32 v22, v22, v145
	v_add_f32_e32 v23, v23, v145
	v_add_f32_e32 v110, v110, v146
	v_add_f32_e32 v111, v111, v146
	v_add_f32_e32 v112, v112, v146
	v_add_f32_e32 v113, v113, v146
	v_exp_f32_e32 v20, v20
	v_exp_f32_e32 v21, v21
	v_exp_f32_e32 v22, v22
	v_exp_f32_e32 v23, v23
	v_exp_f32_e32 v110, v110
	v_exp_f32_e32 v111, v111
	v_exp_f32_e32 v112, v112
	v_exp_f32_e32 v113, v113
	v_add_f32_e32 v20, 1.0, v20
	v_add_f32_e32 v21, 1.0, v21
	v_add_f32_e32 v22, 1.0, v22
	v_add_f32_e32 v23, 1.0, v23
	v_add_f32_e32 v110, 1.0, v110
	v_add_f32_e32 v111, 1.0, v111
	v_add_f32_e32 v112, 1.0, v112
	v_add_f32_e32 v113, 1.0, v113
	v_rcp_f32_e32 v20, v20
	v_rcp_f32_e32 v21, v21
	v_rcp_f32_e32 v22, v22
	v_rcp_f32_e32 v23, v23
	v_rcp_f32_e32 v110, v110
	v_rcp_f32_e32 v111, v111
	v_rcp_f32_e32 v112, v112
	v_rcp_f32_e32 v113, v113
	v_mul_f32_e32 v20, v147, v20
	v_mul_f32_e32 v21, v147, v21
	v_mul_f32_e32 v22, v147, v22
	v_mul_f32_e32 v23, v147, v23
	v_mul_f32_e32 v110, v110, v182
	v_mul_f32_e32 v111, v111, v183
	v_mul_f32_e32 v112, v112, v184
	v_mul_f32_e32 v113, v113, v185
	v_exp_f32_e32 v20, v20
	v_exp_f32_e32 v21, v21
	v_exp_f32_e32 v22, v22
	v_exp_f32_e32 v23, v23
	s_nop 0
	v_fma_f32 v138, -v20, v20, 1.0
	v_fma_f32 v139, -v21, v21, 1.0
	v_fma_f32 v140, -v22, v22, 1.0
	v_fma_f32 v141, -v23, v23, 1.0
	v_max_f32_e32 v138, 0, v138
	v_max_f32_e32 v139, 0, v139
	v_max_f32_e32 v140, 0, v140
	v_max_f32_e32 v141, 0, v141
	v_sqrt_f32_e32 v138, v138
	v_sqrt_f32_e32 v139, v139
	v_sqrt_f32_e32 v140, v140
	v_sqrt_f32_e32 v141, v141
	s_nop 0
	v_mul_f32_e32 v110, v138, v110
	v_mul_f32_e32 v111, v139, v111
	v_mul_f32_e32 v112, v140, v112
	v_mul_f32_e32 v113, v141, v113
	v_add_f32_e32 v24, v24, v145
	v_add_f32_e32 v25, v25, v145
	v_add_f32_e32 v26, v26, v145
	v_add_f32_e32 v27, v27, v145
	v_add_f32_e32 v114, v114, v146
	v_add_f32_e32 v115, v115, v146
	v_add_f32_e32 v116, v116, v146
	v_add_f32_e32 v117, v117, v146
	v_exp_f32_e32 v24, v24
	v_exp_f32_e32 v25, v25
	v_exp_f32_e32 v26, v26
	v_exp_f32_e32 v27, v27
	v_exp_f32_e32 v114, v114
	v_exp_f32_e32 v115, v115
	v_exp_f32_e32 v116, v116
	v_exp_f32_e32 v117, v117
	v_add_f32_e32 v24, 1.0, v24
	v_add_f32_e32 v25, 1.0, v25
	v_add_f32_e32 v26, 1.0, v26
	v_add_f32_e32 v27, 1.0, v27
	v_add_f32_e32 v114, 1.0, v114
	v_add_f32_e32 v115, 1.0, v115
	v_add_f32_e32 v116, 1.0, v116
	v_add_f32_e32 v117, 1.0, v117
	v_rcp_f32_e32 v24, v24
	v_rcp_f32_e32 v25, v25
	v_rcp_f32_e32 v26, v26
	v_rcp_f32_e32 v27, v27
	v_rcp_f32_e32 v114, v114
	v_rcp_f32_e32 v115, v115
	v_rcp_f32_e32 v116, v116
	v_rcp_f32_e32 v117, v117
	v_mul_f32_e32 v24, v147, v24
	v_mul_f32_e32 v25, v147, v25
	v_mul_f32_e32 v26, v147, v26
	v_mul_f32_e32 v27, v147, v27
	v_mul_f32_e32 v114, v114, v186
	v_mul_f32_e32 v115, v115, v187
	v_mul_f32_e32 v116, v116, v188
	v_mul_f32_e32 v117, v117, v189
	v_exp_f32_e32 v24, v24
	v_exp_f32_e32 v25, v25
	v_exp_f32_e32 v26, v26
	v_exp_f32_e32 v27, v27
	s_nop 0
	v_fma_f32 v138, -v24, v24, 1.0
	v_fma_f32 v139, -v25, v25, 1.0
	v_fma_f32 v140, -v26, v26, 1.0
	v_fma_f32 v141, -v27, v27, 1.0
	v_max_f32_e32 v138, 0, v138
	v_max_f32_e32 v139, 0, v139
	v_max_f32_e32 v140, 0, v140
	v_max_f32_e32 v141, 0, v141
	v_sqrt_f32_e32 v138, v138
	v_sqrt_f32_e32 v139, v139
	v_sqrt_f32_e32 v140, v140
	v_sqrt_f32_e32 v141, v141
	s_nop 0
	v_mul_f32_e32 v114, v138, v114
	v_mul_f32_e32 v115, v139, v115
	v_mul_f32_e32 v116, v140, v116
	v_mul_f32_e32 v117, v141, v117
	v_add_f32_e32 v28, v28, v145
	v_add_f32_e32 v29, v29, v145
	v_add_f32_e32 v30, v30, v145
	v_add_f32_e32 v31, v31, v145
	v_add_f32_e32 v118, v118, v146
	v_add_f32_e32 v119, v119, v146
	v_add_f32_e32 v120, v120, v146
	v_add_f32_e32 v121, v121, v146
	v_exp_f32_e32 v28, v28
	v_exp_f32_e32 v29, v29
	v_exp_f32_e32 v30, v30
	v_exp_f32_e32 v31, v31
	v_exp_f32_e32 v118, v118
	v_exp_f32_e32 v119, v119
	v_exp_f32_e32 v120, v120
	v_exp_f32_e32 v121, v121
	v_add_f32_e32 v28, 1.0, v28
	v_add_f32_e32 v29, 1.0, v29
	v_add_f32_e32 v30, 1.0, v30
; __device__ __forceinline__ float bf2f(u16 h) { return __uint_as_float(((unsigned)h) << 16); }
; __device__ __forceinline__ void lru_tile(const Params& P, int chunk, int head, int pass, char* smem_raw) {
;     ...
;           const float r = __builtin_amdgcn_rcpf(1.f + __builtin_amdgcn_exp2f(acc[tc][reg] + ba[tc]));
;           const float ii = __builtin_amdgcn_rcpf(1.f + __builtin_amdgcn_exp2f(acc[tc + 4][reg] + bi[tc]));
;           const float la = -c8[tc] * r;
;           const float a = __builtin_amdgcn_exp2f(la);
;           const float ucv = bf2f(sm_uc[(sb * 64 + tl) * LDSS + c]);
;           const float bt = __builtin_amdgcn_sqrtf(fmaxf(1.f - a * a, 0.f)) * (ii * ucv);
;           sm_a[tl * 64 + c] = a;
;           sm_b[tl * 64 + c] = bt;
;         }
;       __syncthreads();
;       const int pos = (d == 0) ? q : 3 - q;
;       {
;         float Pp = 1.f, H = 0.f;
; #pragma unroll 4
;         for (int i = 0; i < 16; ++i) {
;           const int tl = (d == 0) ? (q * 16 + i) : (q * 16 + 15 - i);
;           const float a = sm_a[tl * 64 + ch], b = sm_b[tl * 64 + ch];
;           H = a * H + b; Pp *= a;
;         }
;         sm_ph[pos * 64 + ch] = make_float2(Pp, H);
;       }
;       __syncthreads();
;       const float2 p0 = sm_ph[ch], p1 = sm_ph[64 + ch], p2 = sm_ph[128 + ch], p3 = sm_ph[192 + ch];
;     ...
;       cB = p0.x * cB + p0.y; cA *= p0.x;
;       cB = p1.x * cB + p1.y; cA *= p1.x;
;       cB = p2.x * cB + p2.y; cA *= p2.x;
;       cB = p3.x * cB + p3.y; cA *= p3.x;
;       __syncthreads();
;     }
;     if (pass == 1 && q == 0) P.summ[((long)d * 264 + chunk) * 512 + gch] = make_float2(cA, cB);
	v_add_f32_e32 v31, 1.0, v31
	v_add_f32_e32 v118, 1.0, v118
	v_add_f32_e32 v119, 1.0, v119
	v_add_f32_e32 v120, 1.0, v120
	v_add_f32_e32 v121, 1.0, v121
	v_rcp_f32_e32 v28, v28
	v_rcp_f32_e32 v29, v29
	v_rcp_f32_e32 v30, v30
	v_rcp_f32_e32 v31, v31
	v_rcp_f32_e32 v118, v118
	v_rcp_f32_e32 v119, v119
	v_rcp_f32_e32 v120, v120
	v_rcp_f32_e32 v121, v121
	v_mul_f32_e32 v28, v147, v28
	v_mul_f32_e32 v29, v147, v29
	v_mul_f32_e32 v30, v147, v30
	v_mul_f32_e32 v31, v147, v31
	v_mul_f32_e32 v118, v118, v190
	v_mul_f32_e32 v119, v119, v191
	v_mul_f32_e32 v120, v120, v192
	v_mul_f32_e32 v121, v121, v193
	v_exp_f32_e32 v28, v28
	v_exp_f32_e32 v29, v29
	v_exp_f32_e32 v30, v30
	v_exp_f32_e32 v31, v31
	s_nop 0
	v_fma_f32 v138, -v28, v28, 1.0
	v_fma_f32 v139, -v29, v29, 1.0
	v_fma_f32 v140, -v30, v30, 1.0
	v_fma_f32 v141, -v31, v31, 1.0
	v_max_f32_e32 v138, 0, v138
	v_max_f32_e32 v139, 0, v139
	v_max_f32_e32 v140, 0, v140
	v_max_f32_e32 v141, 0, v141
	v_sqrt_f32_e32 v138, v138
	v_sqrt_f32_e32 v139, v139
	v_sqrt_f32_e32 v140, v140
	v_sqrt_f32_e32 v141, v141
	s_nop 0
	v_mul_f32_e32 v118, v138, v118
	v_mul_f32_e32 v119, v139, v119
	v_mul_f32_e32 v120, v140, v120
	v_mul_f32_e32 v121, v141, v121
	v_mov_b32_e32 v253, v31
	v_mov_b32_e32 v254, v121
	v_fma_f32 v254, v30, v254, v120
	v_mul_f32_e32 v253, v253, v30
	v_fma_f32 v254, v29, v254, v119
	v_mul_f32_e32 v253, v253, v29
	v_fma_f32 v254, v28, v254, v118
	v_mul_f32_e32 v253, v253, v28
	v_fma_f32 v254, v27, v254, v117
	v_mul_f32_e32 v253, v253, v27
	v_fma_f32 v254, v26, v254, v116
	v_mul_f32_e32 v253, v253, v26
	v_fma_f32 v254, v25, v254, v115
	v_mul_f32_e32 v253, v253, v25
	v_fma_f32 v254, v24, v254, v114
	v_mul_f32_e32 v253, v253, v24
	v_fma_f32 v254, v23, v254, v113
	v_mul_f32_e32 v253, v253, v23
	v_fma_f32 v254, v22, v254, v112
	v_mul_f32_e32 v253, v253, v22
	v_fma_f32 v254, v21, v254, v111
	v_mul_f32_e32 v253, v253, v21
	v_fma_f32 v254, v20, v254, v110
	v_mul_f32_e32 v253, v253, v20
	v_fma_f32 v254, v19, v254, v109
	v_mul_f32_e32 v253, v253, v19
	v_fma_f32 v254, v18, v254, v108
	v_mul_f32_e32 v253, v253, v18
	v_fma_f32 v254, v17, v254, v107
	v_mul_f32_e32 v253, v253, v17
	v_fma_f32 v254, v16, v254, v106
	v_mul_f32_e32 v253, v253, v16
	v_fma_f32 v254, v15, v254, v105
	v_mul_f32_e32 v253, v253, v15
	v_fma_f32 v254, v14, v254, v104
	v_mul_f32_e32 v253, v253, v14
	v_fma_f32 v254, v13, v254, v103
	v_mul_f32_e32 v253, v253, v13
	v_fma_f32 v254, v12, v254, v102
	v_mul_f32_e32 v253, v253, v12
	v_fma_f32 v254, v11, v254, v101
	v_mul_f32_e32 v253, v253, v11
	v_fma_f32 v254, v10, v254, v100
	v_mul_f32_e32 v253, v253, v10
	v_fma_f32 v254, v9, v254, v99
	v_mul_f32_e32 v253, v253, v9
	v_fma_f32 v254, v8, v254, v98
	v_mul_f32_e32 v253, v253, v8
	v_fma_f32 v254, v7, v254, v97
	v_mul_f32_e32 v253, v253, v7
	v_fma_f32 v254, v6, v254, v96
	v_mul_f32_e32 v253, v253, v6
	v_fma_f32 v254, v5, v254, v95
	v_mul_f32_e32 v253, v253, v5
	v_fma_f32 v254, v4, v254, v94
	v_mul_f32_e32 v253, v253, v4
	v_fma_f32 v254, v3, v254, v93
	v_mul_f32_e32 v253, v253, v3
	v_fma_f32 v254, v2, v254, v92
	v_mul_f32_e32 v253, v253, v2
	v_fma_f32 v254, v1, v254, v91
	v_mul_f32_e32 v253, v253, v1
	v_fma_f32 v254, v0, v254, v90
	v_mul_f32_e32 v253, v253, v0
	v_mov_b32_e32 v138, v253
	v_mov_b32_e32 v139, v253
	s_nop 1
	v_permlane16_swap_b32_e32 v138, v139
	v_mov_b32_e32 v140, v138
	v_mov_b32_e32 v141, v139
	s_nop 1
	v_permlane32_swap_b32_e32 v138, v140
	v_permlane32_swap_b32_e32 v139, v141
	v_mov_b32_e32 v198, v254
	v_mov_b32_e32 v199, v254
	s_nop 1
	v_permlane16_swap_b32_e32 v198, v199
	v_mov_b32_e32 v200, v198
	v_mov_b32_e32 v201, v199
	s_nop 1
	v_permlane32_swap_b32_e32 v198, v200
	v_permlane32_swap_b32_e32 v199, v201
	v_mov_b32_e32 v202, 0
	v_fma_f32 v151, v141, v202, v201
	v_fma_f32 v150, v140, v151, v200
	v_fma_f32 v136, v139, v150, v199
	v_fma_f32 v254, v138, v136, v198
	v_mul_f32_e32 v253, v138, v139
	v_mul_f32_e32 v253, v253, v140
	v_mul_f32_e32 v200, v253, v141
	v_mov_b32_e32 v201, v254
	s_add_u32 s0, s71, 264
	s_lshl_b32 s0, s0, 12
	s_lshl_b32 s1, s56, 3
	s_add_u32 s0, s0, s1
	s_add_u32 s4, s18, s0
	s_addc_u32 s5, s19, 0
	global_store_dwordx2 v250, v[200:201], s[4:5]
	v_add_u32_e32 v89, s62, v89
	v_add_u32_e32 v130, s62, v130
	v_add_u32_e32 v131, s62, v131
	v_add_u32_e32 v133, s62, v133
	s_sub_u32 s62, 0, s62
	s_add_u32 s69, s69, 1
	s_cmp_lt_u32 s69, s70
	s_cbranch_scc1 .Lmy_lrua_tile
	s_waitcnt lgkmcnt(0)
	s_barrier

; __device__ __forceinline__ void lru_tile(const Params& P, int chunk, int head, int pass, char* smem_raw) {
;     ...
;   const int tid = VTID, lane = tid & 63, wid = tid >> 6;
;   const int q = tid >> 6, ch = tid & 63;
;   const int row0 = chunk * 128;
;   int seq_lo, seq_hi;
;   if (chunk < 256) { seq_lo = (chunk >> 6) << 13; seq_hi = seq_lo + 8192; }
;   else { const int b = (chunk - 256) >> 1; seq_lo = N_X + b * 256; seq_hi = seq_lo + 256; }
;   const int gch = head * 64 + ch;
.LBB0_477:
	v_readlane_b32 s0, v252, 0
	v_readlane_b32 s1, v252, 1
	v_readfirstlane_b32 s68, v153
	s_nop 3
	s_sub_u32 s0, s0, 0x170
	s_subb_u32 s1, s1, 0
	s_load_dwordx2 s[10:11], s[0:1], 0x148
	s_load_dwordx2 s[12:13], s[0:1], 0x158
	s_load_dwordx2 s[18:19], s[0:1], 0x130
	s_load_dwordx2 s[20:21], s[0:1], 0x128
	s_load_dwordx4 s[24:27], s[0:1], 0x70
	s_load_dwordx2 s[28:29], s[0:1], 0x88
	s_load_dwordx2 s[30:31], s[0:1], 0x98
	s_load_dwordx2 s[36:37], s[0:1], 0xa0
	s_lshl_b32 s4, s2, 1
	s_add_u32 s68, s4, s68
	s_mov_b32 s69, 0
	s_mov_b32 s70, 4
	s_cmp_lt_u32 s68, 64
	s_cselect_b32 s70, 5, 4
	s_mov_b32 s72, 0xffff0000
	s_mov_b32 s73, -1
	s_mov_b32 s74, 0
	s_mov_b32 s75, -1
	s_mov_b32 s76, 0
	s_mov_b32 s77, 0xffff0000
	s_mov_b32 s78, -1
	s_mov_b32 s79, 0x0000ffff
	s_mov_b32 s80, -1
	s_mov_b32 s81, 0
	s_mov_b32 s82, 0x0000ffff
	s_mov_b32 s83, 0
	v_and_b32_e32 v138, 63, v152
	v_lshrrev_b32_e32 v139, 4, v138
	v_and_b32_e32 v140, 15, v138
	v_bfe_u32 v141, v152, 6, 2
	v_lshl_add_u32 v255, v141, 4, v140
	v_mul_u32_u24_e32 v253, 0x12000, v153
	v_add_u32_e32 v253, 16, v253
	v_mul_u32_u24_e32 v134, 0x18000, v139
	v_lshl_add_u32 v134, v255, 1, v134
	v_lshlrev_b32_e32 v237, 16, v139
	v_lshl_add_u32 v237, v255, 1, v237
	v_lshlrev_b32_e32 v250, 3, v255
	v_lshlrev_b32_e32 v251, 7, v255
	v_lshl_add_u32 v251, v139, 4, v251
	v_lshrrev_b32_e32 v254, 3, v140
	v_lshl_add_u32 v254, v141, 1, v254
	v_lshlrev_b32_e32 v202, 1, v139
	v_xor_b32_e32 v89, v254, v202
	v_xor_b32_e32 v130, 1, v89
	v_and_b32_e32 v203, 7, v140
	v_lshl_add_u32 v202, v139, 12, v253
	v_lshl_add_u32 v202, v203, 1, v202
	v_lshl_add_u32 v89, v89, 4, v202
	v_lshl_add_u32 v130, v130, 4, v202
	v_lshrrev_b32_e32 v202, 2, v140
	v_and_b32_e32 v203, 3, v140
	v_lshl_add_u32 v254, v202, 5, v203
	v_lshl_add_u32 v254, v254, 7, v253
	v_lshrrev_b32_e32 v203, 1, v203
	v_lshl_add_u32 v202, v202, 1, v203
	v_xor_b32_e32 v202, v139, v202
	v_lshl_add_u32 v131, v202, 4, v254
	v_xor_b32_e32 v202, 4, v202
	v_lshl_add_u32 v133, v202, 4, v254
	v_cmp_eq_u32_e32 vcc, 0, v139
	s_mov_b64 s[84:85], vcc
	v_cmp_eq_u32_e32 vcc, 3, v139
	s_mov_b64 s[86:87], vcc
	s_waitcnt lgkmcnt(0)
; __device__ __forceinline__ float bf2f(u16 h) { return __uint_as_float(((unsigned)h) << 16); }
; __device__ __forceinline__ void lru_tile(const Params& P, int chunk, int head, int pass, char* smem_raw) {
;     ...
;   const int q = tid >> 6, ch = tid & 63;
;   const int row0 = chunk * 128;
;   int seq_lo, seq_hi;
;   if (chunk < 256) { seq_lo = (chunk >> 6) << 13; seq_hi = seq_lo + 8192; }
;   else { const int b = (chunk - 256) >> 1; seq_lo = N_X + b * 256; seq_hi = seq_lo + 256; }
;   const int gch = head * 64 + ch;
;   const float* hfbuf = reinterpret_cast<const float*>(P.hy);
;   float* hfw = reinterpret_cast<float*>(P.hy);
;   {
;     const float w0 = P.conv_w[gch], w1 = P.conv_w[512 + gch], w2 = P.conv_w[1024 + gch], w3 = P.conv_w[1536 + gch];
;     const float cb = P.conv_b[gch];
;     const u16* zu = P.zq + gch;
;     const int r = row0 + q * 32;
;     float uv[35];
; #pragma unroll
;     for (int i = 0; i < 35; ++i) {
;       const int rr = r - 2 + i;
;       uv[i] = (rr >= seq_lo && rr < seq_hi) ? bf2f(zu[(long)rr * 1536]) : 0.f;
;     ...
;     float ba[4], bi[4], c8[4];
; #pragma unroll
;     for (int tc = 0; tc < 4; ++tc) {
;       const int cidx = d * 512 + head * 64 + 16 * tc + (lane & 15);
;       ba[tc] = P.b_a[cidx] * -1.4426950408889634f; bi[tc] = P.b_i[cidx] * -1.4426950408889634f;
;       const float nl = -P.lam[cidx];
;       const float e_ = __expf(nl);
;       const float sp = (nl > 20.f) ? nl
;                      : (e_ < 0.03f ? e_ * (1.f - e_ * (0.5f - e_ * (0.33333334f - 0.25f * e_))) : __logf(1.f + e_));
;       c8[tc] = 8.f * 1.4426950408889634f * sp;
;     }
	s_and_b32 s56, s68, 7
	s_lshl_b32 s56, s56, 6
	s_lshr_b32 s59, s68, 3
	s_cmp_lt_u32 s59, 256
	s_cselect_b32 s60, 63, 1
	s_and_b32 s57, s59, s60
	s_cmp_eq_u32 s57, 0
	s_cselect_b64 s[0:1], s[84:85], 0
	s_cmp_eq_u32 s57, s60
	s_cselect_b64 s[4:5], s[86:87], 0
	v_mov_b32_e32 v255, 0x1800
	v_cndmask_b32_e64 v150, 0, v255, s[0:1]
	v_lshlrev_b32_e32 v136, 1, v150
	v_add_u32_e32 v136, v134, v136
	v_add_u32_e32 v150, v134, v150
	v_cndmask_b32_e64 v151, 0, v255, s[4:5]
	v_sub_u32_e32 v151, v134, v151
	s_lshl_b32 s61, s59, 7
	s_mul_i32 s0, s61, 0xc00
	s_lshl_b32 s1, s56, 1
	s_add_u32 s0, s0, s1
	s_add_u32 s4, s10, s0
	s_addc_u32 s5, s11, 0
	s_sub_u32 s4, s4, 0x1800
	s_subb_u32 s5, s5, 0
	global_load_ushort v32, v136, s[4:5]
	s_add_u32 s4, s4, 0xc00
	s_addc_u32 s5, s5, 0
	global_load_ushort v33, v150, s[4:5]
	s_add_u32 s4, s4, 0xc00
	s_addc_u32 s5, s5, 0
	global_load_ushort v34, v134, s[4:5]
	s_add_u32 s4, s4, 0xc00
	s_addc_u32 s5, s5, 0
	global_load_ushort v35, v134, s[4:5]
	s_add_u32 s4, s4, 0xc00
	s_addc_u32 s5, s5, 0
	global_load_ushort v36, v134, s[4:5]
	s_add_u32 s4, s4, 0xc00
	s_addc_u32 s5, s5, 0
	global_load_ushort v37, v134, s[4:5]
	s_add_u32 s4, s4, 0xc00
	s_addc_u32 s5, s5, 0
	global_load_ushort v38, v134, s[4:5]
	s_add_u32 s4, s4, 0xc00
	s_addc_u32 s5, s5, 0
	global_load_ushort v39, v134, s[4:5]
	s_add_u32 s4, s4, 0xc00
	s_addc_u32 s5, s5, 0
	global_load_ushort v40, v134, s[4:5]
	s_add_u32 s4, s4, 0xc00
	s_addc_u32 s5, s5, 0
	global_load_ushort v41, v134, s[4:5]
	s_add_u32 s4, s4, 0xc00
	s_addc_u32 s5, s5, 0
	global_load_ushort v42, v134, s[4:5]
	s_add_u32 s4, s4, 0xc00
	s_addc_u32 s5, s5, 0
	global_load_ushort v43, v134, s[4:5]
	s_add_u32 s4, s4, 0xc00
	s_addc_u32 s5, s5, 0
	global_load_ushort v44, v134, s[4:5]
	s_add_u32 s4, s4, 0xc00
	s_addc_u32 s5, s5, 0
	global_load_ushort v45, v134, s[4:5]
	s_add_u32 s4, s4, 0xc00
	s_addc_u32 s5, s5, 0
	global_load_ushort v46, v134, s[4:5]
	s_add_u32 s4, s4, 0xc00
	s_addc_u32 s5, s5, 0
	global_load_ushort v47, v134, s[4:5]
	s_add_u32 s4, s4, 0xc00
	s_addc_u32 s5, s5, 0
	global_load_ushort v48, v134, s[4:5]
	s_add_u32 s4, s4, 0xc00
	s_addc_u32 s5, s5, 0
	global_load_ushort v49, v134, s[4:5]
	s_add_u32 s4, s4, 0xc00
	s_addc_u32 s5, s5, 0
	global_load_ushort v50, v134, s[4:5]
	s_add_u32 s4, s4, 0xc00
	s_addc_u32 s5, s5, 0
	global_load_ushort v51, v134, s[4:5]
	s_add_u32 s4, s4, 0xc00
	s_addc_u32 s5, s5, 0
	global_load_ushort v52, v134, s[4:5]
	s_add_u32 s4, s4, 0xc00
	s_addc_u32 s5, s5, 0
	global_load_ushort v53, v134, s[4:5]
	s_add_u32 s4, s4, 0xc00
	s_addc_u32 s5, s5, 0
	global_load_ushort v54, v134, s[4:5]
	s_add_u32 s4, s4, 0xc00
	s_addc_u32 s5, s5, 0
	global_load_ushort v55, v134, s[4:5]
	s_add_u32 s4, s4, 0xc00
	s_addc_u32 s5, s5, 0
	global_load_ushort v56, v134, s[4:5]
	s_add_u32 s4, s4, 0xc00
	s_addc_u32 s5, s5, 0
	global_load_ushort v57, v134, s[4:5]
	s_add_u32 s4, s4, 0xc00
	s_addc_u32 s5, s5, 0
	global_load_ushort v58, v134, s[4:5]
	s_add_u32 s4, s4, 0xc00
	s_addc_u32 s5, s5, 0
	global_load_ushort v59, v134, s[4:5]
	s_add_u32 s4, s4, 0xc00
	s_addc_u32 s5, s5, 0
	global_load_ushort v60, v134, s[4:5]
	s_add_u32 s4, s4, 0xc00
	s_addc_u32 s5, s5, 0
	global_load_ushort v61, v134, s[4:5]
	s_add_u32 s4, s4, 0xc00
	s_addc_u32 s5, s5, 0
	global_load_ushort v62, v134, s[4:5]
	s_add_u32 s4, s4, 0xc00
	s_addc_u32 s5, s5, 0
	global_load_ushort v63, v134, s[4:5]
	s_add_u32 s4, s4, 0xc00
	s_addc_u32 s5, s5, 0
	global_load_ushort v64, v134, s[4:5]
	s_add_u32 s4, s4, 0xc00
	s_addc_u32 s5, s5, 0
	global_load_ushort v66, v134, s[4:5]
	s_add_u32 s4, s4, 0xc00
	s_addc_u32 s5, s5, 0
	global_load_ushort v69, v151, s[4:5]
	v_bfe_u32 v255, v152, 6, 2
	v_and_b32_e32 v253, 15, v152
	v_lshl_add_u32 v255, v255, 4, v253
	v_add_u32_e32 v255, s56, v255
	v_lshlrev_b32_e32 v255, 2, v255
	global_load_dword v65, v255, s[24:25]
	global_load_dword v67, v255, s[24:25] offset:2048
	s_add_u32 s0, s24, 0x1000
	s_addc_u32 s1, s25, 0
	global_load_dword v68, v255, s[0:1]
	global_load_dword v70, v255, s[0:1] offset:2048
	global_load_dword v73, v255, s[26:27]
	s_add_u32 s0, s28, 0x0
	s_addc_u32 s1, s29, 0
	global_load_dword v75, v255, s[0:1]
	s_add_u32 s0, s30, 0x0
	s_addc_u32 s1, s31, 0
	global_load_dword v84, v255, s[0:1]
	s_add_u32 s0, s36, 0x0
	s_addc_u32 s1, s37, 0
	global_load_dword v85, v255, s[0:1]
	s_add_u32 s0, s28, 0x800
	s_addc_u32 s1, s29, 0
	global_load_dword v145, v255, s[0:1]
	s_add_u32 s0, s30, 0x800
	s_addc_u32 s1, s31, 0
	global_load_dword v146, v255, s[0:1]
	s_add_u32 s0, s36, 0x800
	s_addc_u32 s1, s37, 0
	global_load_dword v147, v255, s[0:1]
	s_lshl_b32 s0, s56, 8
	s_add_u32 s0, s0, 0x0
	s_add_u32 s4, s20, s0
	s_addc_u32 s5, s21, 0
	global_load_dwordx4 v[238:241], v251, s[4:5]
	global_load_dwordx4 v[242:245], v251, s[4:5] offset:64
	s_add_u32 s4, s4, 0x2000
	s_addc_u32 s5, s5, 0
	global_load_dwordx4 v[246:249], v251, s[4:5]
	global_load_dwordx4 v[194:197], v251, s[4:5] offset:64
	s_waitcnt vmcnt(0)
	v_mul_f32_e32 v75, 0xbfb8aa3b, v75
	v_mul_f32_e32 v84, 0xbfb8aa3b, v84
	v_sub_f32_e32 v138, 0, v85
	v_mul_f32_e32 v139, 0x3fb8aa3b, v138
	v_exp_f32_e32 v139, v139
	s_nop 0
	v_mul_f32_e32 v140, 0xbe800000, v139
	v_add_f32_e32 v140, 0x3eaaaaab, v140
	v_fma_f32 v140, -v139, v140, 0.5
	v_fma_f32 v140, -v139, v140, 1.0
	v_mul_f32_e32 v140, v139, v140
	v_add_f32_e32 v141, 1.0, v139
	v_log_f32_e32 v141, v141
	v_mov_b32_e32 v255, 0x3cf5c28f
	v_mul_f32_e32 v141, 0x3f317218, v141
	v_cmp_gt_f32_e32 vcc, v255, v139
	s_nop 1
	v_cndmask_b32_e32 v140, v141, v140, vcc
	v_mov_b32_e32 v255, 0x41a00000
	v_cmp_lt_f32_e32 vcc, v255, v138
	s_nop 1
	v_cndmask_b32_e32 v140, v140, v138, vcc
	v_mul_f32_e32 v85, 0xc138aa3b, v140
	v_mul_f32_e32 v145, 0xbfb8aa3b, v145
	v_mul_f32_e32 v146, 0xbfb8aa3b, v146
	v_sub_f32_e32 v138, 0, v147
	v_mul_f32_e32 v139, 0x3fb8aa3b, v138
	v_exp_f32_e32 v139, v139
	s_nop 0
	v_mul_f32_e32 v140, 0xbe800000, v139
	v_add_f32_e32 v140, 0x3eaaaaab, v140
	v_fma_f32 v140, -v139, v140, 0.5
	v_fma_f32 v140, -v139, v140, 1.0
	v_mul_f32_e32 v140, v139, v140
	v_add_f32_e32 v141, 1.0, v139
	v_log_f32_e32 v141, v141
	v_mov_b32_e32 v255, 0x3cf5c28f
	v_mul_f32_e32 v141, 0x3f317218, v141
	v_cmp_gt_f32_e32 vcc, v255, v139
	s_nop 1
	v_cndmask_b32_e32 v140, v141, v140, vcc
	v_mov_b32_e32 v255, 0x41a00000
	v_cmp_lt_f32_e32 vcc, v255, v138
	s_nop 1
	v_cndmask_b32_e32 v140, v140, v138, vcc
	v_mul_f32_e32 v147, 0xc138aa3b, v140
	s_mov_b32 s62, 0x4000

; __device__ __forceinline__ float bf2f(u16 h) { return __uint_as_float(((unsigned)h) << 16); }
; __device__ __forceinline__ void lru_tile(const Params& P, int chunk, int head, int pass, char* smem_raw) {
;     ...
;     const float w0 = P.conv_w[gch], w1 = P.conv_w[512 + gch], w2 = P.conv_w[1024 + gch], w3 = P.conv_w[1536 + gch];
;     const float cb = P.conv_b[gch];
;     const u16* zu = P.zq + gch;
;     const int r = row0 + q * 32;
;     float uv[35];
; #pragma unroll
;     for (int i = 0; i < 35; ++i) {
;       const int rr = r - 2 + i;
;       uv[i] = (rr >= seq_lo && rr < seq_hi) ? bf2f(zu[(long)rr * 1536]) : 0.f;
;     }
;     __syncthreads();
; #pragma unroll
;     for (int i = 0; i < 32; ++i) {
;       const float v = cb + uv[i] * w0 + uv[i + 1] * w1 + uv[i + 2] * w2 + uv[i + 3] * w3;
;       sm_uc[(q * 32 + i) * LDSS + ch] = f2bf(v);
;     }
.Lmy_lrub_fl:
	s_cmp_eq_u32 s57, 0
	s_cselect_b64 s[0:1], s[84:85], 0
	s_cmp_eq_u32 s57, s60
	s_cselect_b64 s[4:5], s[86:87], 0
	v_cndmask_b32_e64 v202, 1.0, 0, s[0:1]
	v_cndmask_b32_e64 v203, 1.0, 0, s[4:5]
	s_waitcnt vmcnt(32)
	v_lshlrev_b32_e32 v90, 16, v32
	v_lshlrev_b32_e32 v91, 16, v33
	v_lshlrev_b32_e32 v92, 16, v34
	v_lshlrev_b32_e32 v93, 16, v35
	v_lshlrev_b32_e32 v94, 16, v36
	v_lshlrev_b32_e32 v95, 16, v37
	v_lshlrev_b32_e32 v96, 16, v38
	v_lshlrev_b32_e32 v97, 16, v39
	v_lshlrev_b32_e32 v98, 16, v40
	v_lshlrev_b32_e32 v99, 16, v41
	v_lshlrev_b32_e32 v100, 16, v42
	v_lshlrev_b32_e32 v101, 16, v43
	v_lshlrev_b32_e32 v102, 16, v44
	v_lshlrev_b32_e32 v103, 16, v45
	v_lshlrev_b32_e32 v104, 16, v46
	v_lshlrev_b32_e32 v105, 16, v47
	v_lshlrev_b32_e32 v106, 16, v48
	v_lshlrev_b32_e32 v107, 16, v49
	v_lshlrev_b32_e32 v108, 16, v50
	v_lshlrev_b32_e32 v109, 16, v51
	v_lshlrev_b32_e32 v110, 16, v52
	v_lshlrev_b32_e32 v111, 16, v53
	v_lshlrev_b32_e32 v112, 16, v54
	v_lshlrev_b32_e32 v113, 16, v55
	v_lshlrev_b32_e32 v114, 16, v56
	v_lshlrev_b32_e32 v115, 16, v57
	v_lshlrev_b32_e32 v116, 16, v58
	v_lshlrev_b32_e32 v117, 16, v59
	v_lshlrev_b32_e32 v118, 16, v60
	v_lshlrev_b32_e32 v119, 16, v61
	v_lshlrev_b32_e32 v120, 16, v62
	v_lshlrev_b32_e32 v121, 16, v63
	v_lshlrev_b32_e32 v122, 16, v64
	v_lshlrev_b32_e32 v123, 16, v66
	v_lshlrev_b32_e32 v124, 16, v69
	v_mul_f32_e32 v90, v90, v202
	v_mul_f32_e32 v91, v91, v202
	v_mul_f32_e32 v124, v124, v203
	v_fma_f32 v162, v90, v65, v73
	v_fma_f32 v162, v91, v67, v162
	v_fma_f32 v162, v92, v68, v162
	v_fma_f32 v162, v93, v70, v162
	v_fma_f32 v163, v91, v65, v73
	v_fma_f32 v163, v92, v67, v163
	v_fma_f32 v163, v93, v68, v163
	v_fma_f32 v163, v94, v70, v163
	v_fma_f32 v164, v92, v65, v73
	v_fma_f32 v164, v93, v67, v164
	v_fma_f32 v164, v94, v68, v164
	v_fma_f32 v164, v95, v70, v164
	v_fma_f32 v165, v93, v65, v73
	v_fma_f32 v165, v94, v67, v165
	v_fma_f32 v165, v95, v68, v165
	v_fma_f32 v165, v96, v70, v165
	v_fma_f32 v166, v94, v65, v73
	v_fma_f32 v166, v95, v67, v166
	v_fma_f32 v166, v96, v68, v166
	v_fma_f32 v166, v97, v70, v166
	v_fma_f32 v167, v95, v65, v73
	v_fma_f32 v167, v96, v67, v167
	v_fma_f32 v167, v97, v68, v167
	v_fma_f32 v167, v98, v70, v167
	v_fma_f32 v168, v96, v65, v73
	v_fma_f32 v168, v97, v67, v168
	v_fma_f32 v168, v98, v68, v168
	v_fma_f32 v168, v99, v70, v168
	v_fma_f32 v169, v97, v65, v73
	v_fma_f32 v169, v98, v67, v169
	v_fma_f32 v169, v99, v68, v169
	v_fma_f32 v169, v100, v70, v169
	v_fma_f32 v170, v98, v65, v73
	v_fma_f32 v170, v99, v67, v170
	v_fma_f32 v170, v100, v68, v170
	v_fma_f32 v170, v101, v70, v170
	v_fma_f32 v171, v99, v65, v73
	v_fma_f32 v171, v100, v67, v171
	v_fma_f32 v171, v101, v68, v171
	v_fma_f32 v171, v102, v70, v171
	v_fma_f32 v172, v100, v65, v73
	v_fma_f32 v172, v101, v67, v172
	v_fma_f32 v172, v102, v68, v172
	v_fma_f32 v172, v103, v70, v172
	v_fma_f32 v173, v101, v65, v73
	v_fma_f32 v173, v102, v67, v173
	v_fma_f32 v173, v103, v68, v173
	v_fma_f32 v173, v104, v70, v173
	v_fma_f32 v174, v102, v65, v73
	v_fma_f32 v174, v103, v67, v174
	v_fma_f32 v174, v104, v68, v174
	v_fma_f32 v174, v105, v70, v174
	v_fma_f32 v175, v103, v65, v73
	v_fma_f32 v175, v104, v67, v175
	v_fma_f32 v175, v105, v68, v175
	v_fma_f32 v175, v106, v70, v175
	v_fma_f32 v176, v104, v65, v73
	v_fma_f32 v176, v105, v67, v176
	v_fma_f32 v176, v106, v68, v176
	v_fma_f32 v176, v107, v70, v176
	v_fma_f32 v177, v105, v65, v73
	v_fma_f32 v177, v106, v67, v177
	v_fma_f32 v177, v107, v68, v177
	v_fma_f32 v177, v108, v70, v177
	v_fma_f32 v178, v106, v65, v73
	v_fma_f32 v178, v107, v67, v178
	v_fma_f32 v178, v108, v68, v178
	v_fma_f32 v178, v109, v70, v178
	v_fma_f32 v179, v107, v65, v73
	v_fma_f32 v179, v108, v67, v179
	v_fma_f32 v179, v109, v68, v179
	v_fma_f32 v179, v110, v70, v179
	v_fma_f32 v180, v108, v65, v73
	v_fma_f32 v180, v109, v67, v180
	v_fma_f32 v180, v110, v68, v180
	v_fma_f32 v180, v111, v70, v180
	v_fma_f32 v181, v109, v65, v73
	v_fma_f32 v181, v110, v67, v181
	v_fma_f32 v181, v111, v68, v181
	v_fma_f32 v181, v112, v70, v181
	v_fma_f32 v182, v110, v65, v73
	v_fma_f32 v182, v111, v67, v182
	v_fma_f32 v182, v112, v68, v182
	v_fma_f32 v182, v113, v70, v182
	v_fma_f32 v183, v111, v65, v73
	v_fma_f32 v183, v112, v67, v183
	v_fma_f32 v183, v113, v68, v183
	v_fma_f32 v183, v114, v70, v183
	v_fma_f32 v184, v112, v65, v73
	v_fma_f32 v184, v113, v67, v184
	v_fma_f32 v184, v114, v68, v184
	v_fma_f32 v184, v115, v70, v184
	v_fma_f32 v185, v113, v65, v73
	v_fma_f32 v185, v114, v67, v185
	v_fma_f32 v185, v115, v68, v185
	v_fma_f32 v185, v116, v70, v185
	v_fma_f32 v186, v114, v65, v73
	v_fma_f32 v186, v115, v67, v186
	v_fma_f32 v186, v116, v68, v186
	v_fma_f32 v186, v117, v70, v186
	v_fma_f32 v187, v115, v65, v73
	v_fma_f32 v187, v116, v67, v187
	v_fma_f32 v187, v117, v68, v187
	v_fma_f32 v187, v118, v70, v187
	v_fma_f32 v188, v116, v65, v73
	v_fma_f32 v188, v117, v67, v188
	v_fma_f32 v188, v118, v68, v188
	v_fma_f32 v188, v119, v70, v188
	v_fma_f32 v189, v117, v65, v73
	v_fma_f32 v189, v118, v67, v189
	v_fma_f32 v189, v119, v68, v189
	v_fma_f32 v189, v120, v70, v189
	v_fma_f32 v190, v118, v65, v73
	v_fma_f32 v190, v119, v67, v190
	v_fma_f32 v190, v120, v68, v190
	v_fma_f32 v190, v121, v70, v190
	v_fma_f32 v191, v119, v65, v73
	v_fma_f32 v191, v120, v67, v191
	v_fma_f32 v191, v121, v68, v191
	v_fma_f32 v191, v122, v70, v191
	v_fma_f32 v192, v120, v65, v73
	v_fma_f32 v192, v121, v67, v192
	v_fma_f32 v192, v122, v68, v192
	v_fma_f32 v192, v123, v70, v192
	v_fma_f32 v193, v121, v65, v73
	v_fma_f32 v193, v122, v67, v193
	v_fma_f32 v193, v123, v68, v193
	v_fma_f32 v193, v124, v70, v193
; __device__ __forceinline__ void lru_tile(const Params& P, int chunk, int head, int pass, char* smem_raw) {
;     ...
; #pragma unroll
;     for (int i = 0; i < 32; ++i) {
;       const float v = cb + uv[i] * w0 + uv[i + 1] * w1 + uv[i + 2] * w2 + uv[i + 3] * w3;
;       sm_uc[(q * 32 + i) * LDSS + ch] = f2bf(v);
;     }
;     ...
;   if (pass == 2 && tid < 128) {
;     const int d = tid >> 6;
;     float h = 0.f;
;     const float2* S = P.summ + (long)d * 264 * 512 + gch;
;     if (chunk < 256) {
;       const int b = chunk >> 6, j = chunk & 63;
;       if (d == 0) {
;         float2 s = S[(long)(256 + 2 * b) * 512]; h = s.x * h + s.y;
	v_cvt_pk_bf16_f32 v162, v162, v162
	v_cvt_pk_bf16_f32 v163, v163, v163
	v_cvt_pk_bf16_f32 v164, v164, v164
	v_cvt_pk_bf16_f32 v165, v165, v165
	v_cvt_pk_bf16_f32 v166, v166, v166
	v_cvt_pk_bf16_f32 v167, v167, v167
	v_cvt_pk_bf16_f32 v168, v168, v168
	v_cvt_pk_bf16_f32 v169, v169, v169
	v_cvt_pk_bf16_f32 v170, v170, v170
	v_cvt_pk_bf16_f32 v171, v171, v171
	v_cvt_pk_bf16_f32 v172, v172, v172
	v_cvt_pk_bf16_f32 v173, v173, v173
	v_cvt_pk_bf16_f32 v174, v174, v174
	v_cvt_pk_bf16_f32 v175, v175, v175
	v_cvt_pk_bf16_f32 v176, v176, v176
	v_cvt_pk_bf16_f32 v177, v177, v177
	v_cvt_pk_bf16_f32 v178, v178, v178
	v_cvt_pk_bf16_f32 v179, v179, v179
	v_cvt_pk_bf16_f32 v180, v180, v180
	v_cvt_pk_bf16_f32 v181, v181, v181
	v_cvt_pk_bf16_f32 v182, v182, v182
	v_cvt_pk_bf16_f32 v183, v183, v183
	v_cvt_pk_bf16_f32 v184, v184, v184
	v_cvt_pk_bf16_f32 v185, v185, v185
	v_cvt_pk_bf16_f32 v186, v186, v186
	v_cvt_pk_bf16_f32 v187, v187, v187
	v_cvt_pk_bf16_f32 v188, v188, v188
	v_cvt_pk_bf16_f32 v189, v189, v189
	v_cvt_pk_bf16_f32 v190, v190, v190
	v_cvt_pk_bf16_f32 v191, v191, v191
	v_cvt_pk_bf16_f32 v192, v192, v192
	v_cvt_pk_bf16_f32 v193, v193, v193
	ds_write_b16 v89, v162 offset:0
	ds_write_b16 v89, v163 offset:128
	ds_write_b16 v130, v164 offset:256
	ds_write_b16 v130, v165 offset:384
	ds_write_b16 v89, v166 offset:512
	ds_write_b16 v89, v167 offset:640
	ds_write_b16 v130, v168 offset:768
	ds_write_b16 v130, v169 offset:896
	ds_write_b16 v89, v170 offset:1024
	ds_write_b16 v89, v171 offset:1152
	ds_write_b16 v130, v172 offset:1280
	ds_write_b16 v130, v173 offset:1408
	ds_write_b16 v89, v174 offset:1536
	ds_write_b16 v89, v175 offset:1664
	ds_write_b16 v130, v176 offset:1792
	ds_write_b16 v130, v177 offset:1920
	ds_write_b16 v89, v178 offset:2048
	ds_write_b16 v89, v179 offset:2176
	ds_write_b16 v130, v180 offset:2304
	ds_write_b16 v130, v181 offset:2432
	ds_write_b16 v89, v182 offset:2560
	ds_write_b16 v89, v183 offset:2688
	ds_write_b16 v130, v184 offset:2816
	ds_write_b16 v130, v185 offset:2944
	ds_write_b16 v89, v186 offset:3072
	ds_write_b16 v89, v187 offset:3200
	ds_write_b16 v130, v188 offset:3328
	ds_write_b16 v130, v189 offset:3456
	ds_write_b16 v89, v190 offset:3584
	ds_write_b16 v89, v191 offset:3712
	ds_write_b16 v130, v192 offset:3840
	ds_write_b16 v130, v193 offset:3968
	v_lshlrev_b32_e32 v162, 16, v162
	v_lshlrev_b32_e32 v163, 16, v163
	v_lshlrev_b32_e32 v164, 16, v164
	v_lshlrev_b32_e32 v165, 16, v165
	v_lshlrev_b32_e32 v166, 16, v166
	v_lshlrev_b32_e32 v167, 16, v167
	v_lshlrev_b32_e32 v168, 16, v168
	v_lshlrev_b32_e32 v169, 16, v169
	v_lshlrev_b32_e32 v170, 16, v170
	v_lshlrev_b32_e32 v171, 16, v171
	v_lshlrev_b32_e32 v172, 16, v172
	v_lshlrev_b32_e32 v173, 16, v173
	v_lshlrev_b32_e32 v174, 16, v174
	v_lshlrev_b32_e32 v175, 16, v175
	v_lshlrev_b32_e32 v176, 16, v176
	v_lshlrev_b32_e32 v177, 16, v177
	v_lshlrev_b32_e32 v178, 16, v178
	v_lshlrev_b32_e32 v179, 16, v179
	v_lshlrev_b32_e32 v180, 16, v180
	v_lshlrev_b32_e32 v181, 16, v181
	v_lshlrev_b32_e32 v182, 16, v182
	v_lshlrev_b32_e32 v183, 16, v183
	v_lshlrev_b32_e32 v184, 16, v184
	v_lshlrev_b32_e32 v185, 16, v185
	v_lshlrev_b32_e32 v186, 16, v186
	v_lshlrev_b32_e32 v187, 16, v187
	v_lshlrev_b32_e32 v188, 16, v188
	v_lshlrev_b32_e32 v189, 16, v189
	v_lshlrev_b32_e32 v190, 16, v190
	v_lshlrev_b32_e32 v191, 16, v191
	v_lshlrev_b32_e32 v192, 16, v192
	v_lshlrev_b32_e32 v193, 16, v193
	s_waitcnt lgkmcnt(0)
	s_barrier
	v_mov_b32_e32 v148, 0
	s_lshl_b32 s0, s56, 3
	s_add_u32 s0, s0, 0x0
	s_add_u32 s4, s18, s0
	s_addc_u32 s5, s19, 0
	s_cmp_lt_u32 s71, 256
	s_cbranch_scc0 .Lmy_lrub_lb0_ctx
; __device__ __forceinline__ void lru_tile(const Params& P, int chunk, int head, int pass, char* smem_raw) {
;     ...
;     const float2* S = P.summ + (long)d * 264 * 512 + gch;
;     if (chunk < 256) {
;       const int b = chunk >> 6, j = chunk & 63;
;       if (d == 0) {
;         float2 s = S[(long)(256 + 2 * b) * 512]; h = s.x * h + s.y;
;         s = S[(long)(256 + 2 * b + 1) * 512]; h = s.x * h + s.y;
;         int i = 0;
;         for (; i + 8 <= j; i += 8) {
;           float2 sv[8];
; #pragma unroll
;           for (int u = 0; u < 8; ++u) sv[u] = S[(long)(b * 64 + i + u) * 512];
; #pragma unroll
;           for (int u = 0; u < 8; ++u) h = sv[u].x * h + sv[u].y;
;         }
;         for (; i < j; ++i) { s = S[(long)(b * 64 + i) * 512]; h = s.x * h + s.y; }
	s_lshr_b32 s0, s71, 6
	s_lshl_b32 s1, s0, 1
	s_add_u32 s1, s1, 256
	s_add_u32 s60, s1, 0
	s_lshl_b32 s60, s60, 12
	s_add_u32 s60, s4, s60
	s_addc_u32 s61, s5, 0
	global_load_dwordx2 v[0:1], v250, s[60:61]
	s_add_u32 s60, s1, 1
	s_lshl_b32 s60, s60, 12
	s_add_u32 s60, s4, s60
	s_addc_u32 s61, s5, 0
	global_load_dwordx2 v[2:3], v250, s[60:61]
	s_lshl_b32 s0, s0, 6
	v_bfe_u32 v150, v152, 4, 2
	s_mov_b32 s1, s57
	v_lshl_add_u32 v136, v150, 16, v250
	s_lshl_b32 s60, s0, 12
	v_lshlrev_b32_e32 v150, 4, v150
	v_sub_u32_e32 v150, s1, v150
	s_add_u32 s60, s4, s60
	s_addc_u32 s61, s5, 0
	global_load_dwordx2 v[4:5], v136, s[60:61]
	s_add_u32 s60, s60, 0x1000
	s_addc_u32 s61, s61, 0
	global_load_dwordx2 v[6:7], v136, s[60:61]
	s_add_u32 s60, s60, 0x1000
	s_addc_u32 s61, s61, 0
	global_load_dwordx2 v[8:9], v136, s[60:61]
	s_add_u32 s60, s60, 0x1000
	s_addc_u32 s61, s61, 0
	global_load_dwordx2 v[10:11], v136, s[60:61]
	s_add_u32 s60, s60, 0x1000
	s_addc_u32 s61, s61, 0
	global_load_dwordx2 v[12:13], v136, s[60:61]
	s_add_u32 s60, s60, 0x1000
	s_addc_u32 s61, s61, 0
	global_load_dwordx2 v[14:15], v136, s[60:61]
	s_add_u32 s60, s60, 0x1000
	s_addc_u32 s61, s61, 0
	global_load_dwordx2 v[16:17], v136, s[60:61]
	s_add_u32 s60, s60, 0x1000
	s_addc_u32 s61, s61, 0
	global_load_dwordx2 v[18:19], v136, s[60:61]
	s_add_u32 s60, s60, 0x1000
	s_addc_u32 s61, s61, 0
	global_load_dwordx2 v[20:21], v136, s[60:61]
	s_add_u32 s60, s60, 0x1000
	s_addc_u32 s61, s61, 0
	global_load_dwordx2 v[22:23], v136, s[60:61]
	s_add_u32 s60, s60, 0x1000
	s_addc_u32 s61, s61, 0
	global_load_dwordx2 v[24:25], v136, s[60:61]
	s_add_u32 s60, s60, 0x1000
	s_addc_u32 s61, s61, 0
	global_load_dwordx2 v[26:27], v136, s[60:61]
	s_add_u32 s60, s60, 0x1000
	s_addc_u32 s61, s61, 0
	global_load_dwordx2 v[28:29], v136, s[60:61]
	s_add_u32 s60, s60, 0x1000
	s_addc_u32 s61, s61, 0
	global_load_dwordx2 v[30:31], v136, s[60:61]
	s_add_u32 s60, s60, 0x1000
	s_addc_u32 s61, s61, 0
	global_load_dwordx2 v[32:33], v136, s[60:61]
	s_add_u32 s60, s60, 0x1000
	s_addc_u32 s61, s61, 0
	global_load_dwordx2 v[34:35], v136, s[60:61]
	s_waitcnt vmcnt(16)
	v_fma_f32 v148, v0, v148, v1
	v_fma_f32 v148, v2, v148, v3
	v_mov_b32_e32 v253, 1.0
	v_mov_b32_e32 v254, 0
	s_waitcnt vmcnt(0)
	v_cmp_lt_i32_e32 vcc, 0, v150
	s_nop 1
	v_cndmask_b32_e32 v4, 1.0, v4, vcc
	v_cndmask_b32_e32 v5, 0, v5, vcc
	v_fma_f32 v254, v4, v254, v5
	v_mul_f32_e32 v253, v253, v4
	v_cmp_lt_i32_e32 vcc, 1, v150
	s_nop 1
	v_cndmask_b32_e32 v6, 1.0, v6, vcc
	v_cndmask_b32_e32 v7, 0, v7, vcc
	v_fma_f32 v254, v6, v254, v7
	v_mul_f32_e32 v253, v253, v6
	v_cmp_lt_i32_e32 vcc, 2, v150
	s_nop 1
	v_cndmask_b32_e32 v8, 1.0, v8, vcc
	v_cndmask_b32_e32 v9, 0, v9, vcc
	v_fma_f32 v254, v8, v254, v9
	v_mul_f32_e32 v253, v253, v8
	v_cmp_lt_i32_e32 vcc, 3, v150
	s_nop 1
	v_cndmask_b32_e32 v10, 1.0, v10, vcc
	v_cndmask_b32_e32 v11, 0, v11, vcc
	v_fma_f32 v254, v10, v254, v11
	v_mul_f32_e32 v253, v253, v10
	v_cmp_lt_i32_e32 vcc, 4, v150
	s_nop 1
	v_cndmask_b32_e32 v12, 1.0, v12, vcc
	v_cndmask_b32_e32 v13, 0, v13, vcc
	v_fma_f32 v254, v12, v254, v13
	v_mul_f32_e32 v253, v253, v12
	v_cmp_lt_i32_e32 vcc, 5, v150
	s_nop 1
	v_cndmask_b32_e32 v14, 1.0, v14, vcc
	v_cndmask_b32_e32 v15, 0, v15, vcc
	v_fma_f32 v254, v14, v254, v15
	v_mul_f32_e32 v253, v253, v14
	v_cmp_lt_i32_e32 vcc, 6, v150
	s_nop 1
	v_cndmask_b32_e32 v16, 1.0, v16, vcc
	v_cndmask_b32_e32 v17, 0, v17, vcc
	v_fma_f32 v254, v16, v254, v17
	v_mul_f32_e32 v253, v253, v16
	v_cmp_lt_i32_e32 vcc, 7, v150
	s_nop 1
	v_cndmask_b32_e32 v18, 1.0, v18, vcc
	v_cndmask_b32_e32 v19, 0, v19, vcc
	v_fma_f32 v254, v18, v254, v19
	v_mul_f32_e32 v253, v253, v18
	v_cmp_lt_i32_e32 vcc, 8, v150
	s_nop 1
	v_cndmask_b32_e32 v20, 1.0, v20, vcc
	v_cndmask_b32_e32 v21, 0, v21, vcc
	v_fma_f32 v254, v20, v254, v21
	v_mul_f32_e32 v253, v253, v20
	v_cmp_lt_i32_e32 vcc, 9, v150
	s_nop 1
	v_cndmask_b32_e32 v22, 1.0, v22, vcc
	v_cndmask_b32_e32 v23, 0, v23, vcc
	v_fma_f32 v254, v22, v254, v23
	v_mul_f32_e32 v253, v253, v22
	v_cmp_lt_i32_e32 vcc, 10, v150
	s_nop 1
	v_cndmask_b32_e32 v24, 1.0, v24, vcc
	v_cndmask_b32_e32 v25, 0, v25, vcc
	v_fma_f32 v254, v24, v254, v25
	v_mul_f32_e32 v253, v253, v24
	v_cmp_lt_i32_e32 vcc, 11, v150
	s_nop 1
	v_cndmask_b32_e32 v26, 1.0, v26, vcc
	v_cndmask_b32_e32 v27, 0, v27, vcc
	v_fma_f32 v254, v26, v254, v27
	v_mul_f32_e32 v253, v253, v26
	v_cmp_lt_i32_e32 vcc, 12, v150
	s_nop 1
	v_cndmask_b32_e32 v28, 1.0, v28, vcc
	v_cndmask_b32_e32 v29, 0, v29, vcc
	v_fma_f32 v254, v28, v254, v29
	v_mul_f32_e32 v253, v253, v28
	v_cmp_lt_i32_e32 vcc, 13, v150
	s_nop 1
	v_cndmask_b32_e32 v30, 1.0, v30, vcc
	v_cndmask_b32_e32 v31, 0, v31, vcc
	v_fma_f32 v254, v30, v254, v31
	v_mul_f32_e32 v253, v253, v30
	v_cmp_lt_i32_e32 vcc, 14, v150
	s_nop 1
	v_cndmask_b32_e32 v32, 1.0, v32, vcc
	v_cndmask_b32_e32 v33, 0, v33, vcc
	v_fma_f32 v254, v32, v254, v33
	v_mul_f32_e32 v253, v253, v32
	v_cmp_lt_i32_e32 vcc, 15, v150
	s_nop 1
	v_cndmask_b32_e32 v34, 1.0, v34, vcc
	v_cndmask_b32_e32 v35, 0, v35, vcc
	v_fma_f32 v254, v34, v254, v35
	v_mul_f32_e32 v253, v253, v34
	v_mov_b32_e32 v138, v253
	v_mov_b32_e32 v139, v253
	s_nop 1
	v_permlane16_swap_b32_e32 v138, v139
	v_mov_b32_e32 v140, v138
	v_mov_b32_e32 v141, v139
	s_nop 1
	v_permlane32_swap_b32_e32 v138, v140
	v_permlane32_swap_b32_e32 v139, v141
	v_mov_b32_e32 v198, v254
	v_mov_b32_e32 v199, v254
	s_nop 1
	v_permlane16_swap_b32_e32 v198, v199
	v_mov_b32_e32 v200, v198
	v_mov_b32_e32 v201, v199
	s_nop 1
	v_permlane32_swap_b32_e32 v198, v200
	v_permlane32_swap_b32_e32 v199, v201
	v_fma_f32 v148, v138, v148, v198
	v_fma_f32 v148, v139, v148, v199
	v_fma_f32 v148, v140, v148, v200
	v_fma_f32 v148, v141, v148, v201
	s_branch .Lmy_lrub_lb0_done

; __device__ __forceinline__ float bf2f(u16 h) { return __uint_as_float(((unsigned)h) << 16); }
; __device__ __forceinline__ void lru_tile(const Params& P, int chunk, int head, int pass, char* smem_raw) {
;     ...
; #pragma unroll
;       for (int t = 0; t < 8; ++t) acc[t] = f32x4{0.f, 0.f, 0.f, 0.f};
; #pragma unroll
;       for (int s = 0; s < 2; ++s) {
;         const bf16x8 af = *reinterpret_cast<const bf16x8*>(&sm_uc[(sb * 64 + wid * 16 + (lane & 15)) * LDSS + s * 32 + (lane >> 4) * 8]);
; #pragma unroll
;         for (int t = 0; t < 8; ++t) {
;           const bf16x8 bfr = *reinterpret_cast<const bf16x8*>(&sm_w[(t * 16 + (lane & 15)) * LDSS + s * 32 + (lane >> 4) * 8]);
;           acc[t] = __builtin_amdgcn_mfma_f32_16x16x32_bf16(af, bfr, acc[t], 0, 0, 0);
;         }
;       }
; #pragma unroll
;       for (int tc = 0; tc < 4; ++tc)
; #pragma unroll
;         for (int reg = 0; reg < 4; ++reg) {
;           const int tl = wid * 16 + (lane >> 4) * 4 + reg;
;           const int c = 16 * tc + (lane & 15);
;           const float r = __builtin_amdgcn_rcpf(1.f + __builtin_amdgcn_exp2f(acc[tc][reg] + ba[tc]));
;           const float ii = __builtin_amdgcn_rcpf(1.f + __builtin_amdgcn_exp2f(acc[tc + 4][reg] + bi[tc]));
;           const float la = -c8[tc] * r;
;           const float a = __builtin_amdgcn_exp2f(la);
;           const float ucv = bf2f(sm_uc[(sb * 64 + tl) * LDSS + c]);
;           const float bt = __builtin_amdgcn_sqrtf(fmaxf(1.f - a * a, 0.f)) * (ii * ucv);
;           sm_a[tl * 64 + c] = a;
;           sm_b[tl * 64 + c] = bt;
;         }
.Lmy_lrub_nopf:
	ds_read_b128 v[76:79], v131 offset:0
	ds_read_b128 v[80:83], v133 offset:0
	ds_read_b128 v[122:125], v131 offset:512
	ds_read_b128 v[126:129], v133 offset:512
	s_waitcnt lgkmcnt(3)
	v_mfma_f32_16x16x32_bf16 v[0:3], v[76:79], v[238:241], 0
	v_mfma_f32_16x16x32_bf16 v[90:93], v[76:79], v[246:249], 0
	ds_read_b128 v[76:79], v131 offset:1024
	s_waitcnt lgkmcnt(3)
	v_mfma_f32_16x16x32_bf16 v[0:3], v[80:83], v[242:245], v[0:3]
	v_mfma_f32_16x16x32_bf16 v[90:93], v[80:83], v[194:197], v[90:93]
	ds_read_b128 v[80:83], v133 offset:1024
	s_waitcnt lgkmcnt(3)
	v_mfma_f32_16x16x32_bf16 v[4:7], v[122:125], v[238:241], 0
	v_mfma_f32_16x16x32_bf16 v[94:97], v[122:125], v[246:249], 0
	ds_read_b128 v[122:125], v131 offset:1536
	s_waitcnt lgkmcnt(3)
	v_mfma_f32_16x16x32_bf16 v[4:7], v[126:129], v[242:245], v[4:7]
	v_mfma_f32_16x16x32_bf16 v[94:97], v[126:129], v[194:197], v[94:97]
	ds_read_b128 v[126:129], v133 offset:1536
	s_waitcnt lgkmcnt(3)
	v_mfma_f32_16x16x32_bf16 v[8:11], v[76:79], v[238:241], 0
	v_mfma_f32_16x16x32_bf16 v[98:101], v[76:79], v[246:249], 0
	ds_read_b128 v[76:79], v131 offset:2048
	s_waitcnt lgkmcnt(3)
	v_mfma_f32_16x16x32_bf16 v[8:11], v[80:83], v[242:245], v[8:11]
	v_mfma_f32_16x16x32_bf16 v[98:101], v[80:83], v[194:197], v[98:101]
	ds_read_b128 v[80:83], v133 offset:2048
	s_waitcnt lgkmcnt(3)
	v_mfma_f32_16x16x32_bf16 v[12:15], v[122:125], v[238:241], 0
	v_mfma_f32_16x16x32_bf16 v[102:105], v[122:125], v[246:249], 0
	ds_read_b128 v[122:125], v131 offset:2560
	s_waitcnt lgkmcnt(3)
	v_mfma_f32_16x16x32_bf16 v[12:15], v[126:129], v[242:245], v[12:15]
	v_mfma_f32_16x16x32_bf16 v[102:105], v[126:129], v[194:197], v[102:105]
	ds_read_b128 v[126:129], v133 offset:2560
	s_waitcnt lgkmcnt(3)
	v_mfma_f32_16x16x32_bf16 v[16:19], v[76:79], v[238:241], 0
	v_mfma_f32_16x16x32_bf16 v[106:109], v[76:79], v[246:249], 0
	ds_read_b128 v[76:79], v131 offset:3072
	s_waitcnt lgkmcnt(3)
	v_mfma_f32_16x16x32_bf16 v[16:19], v[80:83], v[242:245], v[16:19]
	v_mfma_f32_16x16x32_bf16 v[106:109], v[80:83], v[194:197], v[106:109]
	ds_read_b128 v[80:83], v133 offset:3072
	s_waitcnt lgkmcnt(3)
	v_mfma_f32_16x16x32_bf16 v[20:23], v[122:125], v[238:241], 0
	v_mfma_f32_16x16x32_bf16 v[110:113], v[122:125], v[246:249], 0
	ds_read_b128 v[122:125], v131 offset:3584
	s_waitcnt lgkmcnt(3)
	v_mfma_f32_16x16x32_bf16 v[20:23], v[126:129], v[242:245], v[20:23]
	v_mfma_f32_16x16x32_bf16 v[110:113], v[126:129], v[194:197], v[110:113]
	ds_read_b128 v[126:129], v133 offset:3584
	s_waitcnt lgkmcnt(3)
	v_mfma_f32_16x16x32_bf16 v[24:27], v[76:79], v[238:241], 0
	v_mfma_f32_16x16x32_bf16 v[114:117], v[76:79], v[246:249], 0
	s_waitcnt lgkmcnt(2)
	v_mfma_f32_16x16x32_bf16 v[24:27], v[80:83], v[242:245], v[24:27]
	v_mfma_f32_16x16x32_bf16 v[114:117], v[80:83], v[194:197], v[114:117]
	s_waitcnt lgkmcnt(1)
	v_mfma_f32_16x16x32_bf16 v[28:31], v[122:125], v[238:241], 0
	v_mfma_f32_16x16x32_bf16 v[118:121], v[122:125], v[246:249], 0
	s_waitcnt lgkmcnt(0)
	v_mfma_f32_16x16x32_bf16 v[28:31], v[126:129], v[242:245], v[28:31]
	v_mfma_f32_16x16x32_bf16 v[118:121], v[126:129], v[194:197], v[118:121]
	s_lshl_b32 s0, s56, 8
	s_add_u32 s0, s0, 0x20000
	s_add_u32 s4, s20, s0
	s_addc_u32 s5, s21, 0
	global_load_dwordx4 v[238:241], v251, s[4:5]
	global_load_dwordx4 v[242:245], v251, s[4:5] offset:64
	s_add_u32 s4, s4, 0x2000
	s_addc_u32 s5, s5, 0
	global_load_dwordx4 v[246:249], v251, s[4:5]
	global_load_dwordx4 v[194:197], v251, s[4:5] offset:64
	s_nop 7
	s_nop 7
	v_add_f32_e32 v0, v0, v75
	v_add_f32_e32 v1, v1, v75
	v_add_f32_e32 v2, v2, v75
	v_add_f32_e32 v3, v3, v75
	v_add_f32_e32 v90, v90, v84
	v_add_f32_e32 v91, v91, v84
	v_add_f32_e32 v92, v92, v84
	v_add_f32_e32 v93, v93, v84
	v_exp_f32_e32 v0, v0
	v_exp_f32_e32 v1, v1
	v_exp_f32_e32 v2, v2
	v_exp_f32_e32 v3, v3
	v_exp_f32_e32 v90, v90
	v_exp_f32_e32 v91, v91
	v_exp_f32_e32 v92, v92
	v_exp_f32_e32 v93, v93
	v_add_f32_e32 v0, 1.0, v0
	v_add_f32_e32 v1, 1.0, v1
	v_add_f32_e32 v2, 1.0, v2
	v_add_f32_e32 v3, 1.0, v3
	v_add_f32_e32 v90, 1.0, v90
	v_add_f32_e32 v91, 1.0, v91
	v_add_f32_e32 v92, 1.0, v92
	v_add_f32_e32 v93, 1.0, v93
	v_rcp_f32_e32 v0, v0
	v_rcp_f32_e32 v1, v1
	v_rcp_f32_e32 v2, v2
	v_rcp_f32_e32 v3, v3
	v_rcp_f32_e32 v90, v90
	v_rcp_f32_e32 v91, v91
	v_rcp_f32_e32 v92, v92
	v_rcp_f32_e32 v93, v93
	v_mul_f32_e32 v0, v85, v0
	v_mul_f32_e32 v1, v85, v1
	v_mul_f32_e32 v2, v85, v2
	v_mul_f32_e32 v3, v85, v3
	v_mul_f32_e32 v90, v90, v162
	v_mul_f32_e32 v91, v91, v163
	v_mul_f32_e32 v92, v92, v164
	v_mul_f32_e32 v93, v93, v165
	v_exp_f32_e32 v0, v0
	v_exp_f32_e32 v1, v1
	v_exp_f32_e32 v2, v2
	v_exp_f32_e32 v3, v3
	s_nop 0
	v_fma_f32 v138, -v0, v0, 1.0
	v_fma_f32 v139, -v1, v1, 1.0
	v_fma_f32 v140, -v2, v2, 1.0
	v_fma_f32 v141, -v3, v3, 1.0
	v_max_f32_e32 v138, 0, v138
	v_max_f32_e32 v139, 0, v139
	v_max_f32_e32 v140, 0, v140
	v_max_f32_e32 v141, 0, v141
	v_sqrt_f32_e32 v138, v138
	v_sqrt_f32_e32 v139, v139
	v_sqrt_f32_e32 v140, v140
	v_sqrt_f32_e32 v141, v141
	s_nop 0
	v_mul_f32_e32 v90, v138, v90
	v_mul_f32_e32 v91, v139, v91
	v_mul_f32_e32 v92, v140, v92
	v_mul_f32_e32 v93, v141, v93
	v_add_f32_e32 v4, v4, v75
	v_add_f32_e32 v5, v5, v75
	v_add_f32_e32 v6, v6, v75
	v_add_f32_e32 v7, v7, v75
	v_add_f32_e32 v94, v94, v84
	v_add_f32_e32 v95, v95, v84
	v_add_f32_e32 v96, v96, v84
	v_add_f32_e32 v97, v97, v84
	v_exp_f32_e32 v4, v4
	v_exp_f32_e32 v5, v5
	v_exp_f32_e32 v6, v6
	v_exp_f32_e32 v7, v7
	v_exp_f32_e32 v94, v94
	v_exp_f32_e32 v95, v95
	v_exp_f32_e32 v96, v96
	v_exp_f32_e32 v97, v97
	v_add_f32_e32 v4, 1.0, v4
	v_add_f32_e32 v5, 1.0, v5
	v_add_f32_e32 v6, 1.0, v6
	v_add_f32_e32 v7, 1.0, v7
	v_add_f32_e32 v94, 1.0, v94
; __device__ __forceinline__ float bf2f(u16 h) { return __uint_as_float(((unsigned)h) << 16); }
; __device__ __forceinline__ void lru_tile(const Params& P, int chunk, int head, int pass, char* smem_raw) {
;     ...
; #pragma unroll
;       for (int tc = 0; tc < 4; ++tc)
; #pragma unroll
;         for (int reg = 0; reg < 4; ++reg) {
;           const int tl = wid * 16 + (lane >> 4) * 4 + reg;
;           const int c = 16 * tc + (lane & 15);
;           const float r = __builtin_amdgcn_rcpf(1.f + __builtin_amdgcn_exp2f(acc[tc][reg] + ba[tc]));
;           const float ii = __builtin_amdgcn_rcpf(1.f + __builtin_amdgcn_exp2f(acc[tc + 4][reg] + bi[tc]));
;           const float la = -c8[tc] * r;
;           const float a = __builtin_amdgcn_exp2f(la);
;           const float ucv = bf2f(sm_uc[(sb * 64 + tl) * LDSS + c]);
;           const float bt = __builtin_amdgcn_sqrtf(fmaxf(1.f - a * a, 0.f)) * (ii * ucv);
;           sm_a[tl * 64 + c] = a;
;           sm_b[tl * 64 + c] = bt;
;         }
	v_add_f32_e32 v95, 1.0, v95
	v_add_f32_e32 v96, 1.0, v96
	v_add_f32_e32 v97, 1.0, v97
	v_rcp_f32_e32 v4, v4
	v_rcp_f32_e32 v5, v5
	v_rcp_f32_e32 v6, v6
	v_rcp_f32_e32 v7, v7
	v_rcp_f32_e32 v94, v94
	v_rcp_f32_e32 v95, v95
	v_rcp_f32_e32 v96, v96
	v_rcp_f32_e32 v97, v97
	v_mul_f32_e32 v4, v85, v4
	v_mul_f32_e32 v5, v85, v5
	v_mul_f32_e32 v6, v85, v6
	v_mul_f32_e32 v7, v85, v7
	v_mul_f32_e32 v94, v94, v166
	v_mul_f32_e32 v95, v95, v167
	v_mul_f32_e32 v96, v96, v168
	v_mul_f32_e32 v97, v97, v169
	v_exp_f32_e32 v4, v4
	v_exp_f32_e32 v5, v5
	v_exp_f32_e32 v6, v6
	v_exp_f32_e32 v7, v7
	s_nop 0
	v_fma_f32 v138, -v4, v4, 1.0
	v_fma_f32 v139, -v5, v5, 1.0
	v_fma_f32 v140, -v6, v6, 1.0
	v_fma_f32 v141, -v7, v7, 1.0
	v_max_f32_e32 v138, 0, v138
	v_max_f32_e32 v139, 0, v139
	v_max_f32_e32 v140, 0, v140
	v_max_f32_e32 v141, 0, v141
	v_sqrt_f32_e32 v138, v138
	v_sqrt_f32_e32 v139, v139
	v_sqrt_f32_e32 v140, v140
	v_sqrt_f32_e32 v141, v141
	s_nop 0
	v_mul_f32_e32 v94, v138, v94
	v_mul_f32_e32 v95, v139, v95
	v_mul_f32_e32 v96, v140, v96
	v_mul_f32_e32 v97, v141, v97
	v_add_f32_e32 v8, v8, v75
	v_add_f32_e32 v9, v9, v75
	v_add_f32_e32 v10, v10, v75
	v_add_f32_e32 v11, v11, v75
	v_add_f32_e32 v98, v98, v84
	v_add_f32_e32 v99, v99, v84
	v_add_f32_e32 v100, v100, v84
	v_add_f32_e32 v101, v101, v84
	v_exp_f32_e32 v8, v8
	v_exp_f32_e32 v9, v9
	v_exp_f32_e32 v10, v10
	v_exp_f32_e32 v11, v11
	v_exp_f32_e32 v98, v98
	v_exp_f32_e32 v99, v99
	v_exp_f32_e32 v100, v100
	v_exp_f32_e32 v101, v101
	v_add_f32_e32 v8, 1.0, v8
	v_add_f32_e32 v9, 1.0, v9
	v_add_f32_e32 v10, 1.0, v10
	v_add_f32_e32 v11, 1.0, v11
	v_add_f32_e32 v98, 1.0, v98
	v_add_f32_e32 v99, 1.0, v99
	v_add_f32_e32 v100, 1.0, v100
	v_add_f32_e32 v101, 1.0, v101
	v_rcp_f32_e32 v8, v8
	v_rcp_f32_e32 v9, v9
	v_rcp_f32_e32 v10, v10
	v_rcp_f32_e32 v11, v11
	v_rcp_f32_e32 v98, v98
	v_rcp_f32_e32 v99, v99
	v_rcp_f32_e32 v100, v100
	v_rcp_f32_e32 v101, v101
	v_mul_f32_e32 v8, v85, v8
	v_mul_f32_e32 v9, v85, v9
	v_mul_f32_e32 v10, v85, v10
	v_mul_f32_e32 v11, v85, v11
	v_mul_f32_e32 v98, v98, v170
	v_mul_f32_e32 v99, v99, v171
	v_mul_f32_e32 v100, v100, v172
	v_mul_f32_e32 v101, v101, v173
	v_exp_f32_e32 v8, v8
	v_exp_f32_e32 v9, v9
	v_exp_f32_e32 v10, v10
	v_exp_f32_e32 v11, v11
	s_nop 0
	v_fma_f32 v138, -v8, v8, 1.0
	v_fma_f32 v139, -v9, v9, 1.0
	v_fma_f32 v140, -v10, v10, 1.0
	v_fma_f32 v141, -v11, v11, 1.0
	v_max_f32_e32 v138, 0, v138
	v_max_f32_e32 v139, 0, v139
	v_max_f32_e32 v140, 0, v140
	v_max_f32_e32 v141, 0, v141
	v_sqrt_f32_e32 v138, v138
	v_sqrt_f32_e32 v139, v139
	v_sqrt_f32_e32 v140, v140
	v_sqrt_f32_e32 v141, v141
	s_nop 0
	v_mul_f32_e32 v98, v138, v98
	v_mul_f32_e32 v99, v139, v99
	v_mul_f32_e32 v100, v140, v100
	v_mul_f32_e32 v101, v141, v101
	v_add_f32_e32 v12, v12, v75
	v_add_f32_e32 v13, v13, v75
	v_add_f32_e32 v14, v14, v75
	v_add_f32_e32 v15, v15, v75
	v_add_f32_e32 v102, v102, v84
	v_add_f32_e32 v103, v103, v84
	v_add_f32_e32 v104, v104, v84
	v_add_f32_e32 v105, v105, v84
	v_exp_f32_e32 v12, v12
	v_exp_f32_e32 v13, v13
	v_exp_f32_e32 v14, v14
	v_exp_f32_e32 v15, v15
	v_exp_f32_e32 v102, v102
	v_exp_f32_e32 v103, v103
	v_exp_f32_e32 v104, v104
	v_exp_f32_e32 v105, v105
	v_add_f32_e32 v12, 1.0, v12
	v_add_f32_e32 v13, 1.0, v13
	v_add_f32_e32 v14, 1.0, v14
	v_add_f32_e32 v15, 1.0, v15
	v_add_f32_e32 v102, 1.0, v102
	v_add_f32_e32 v103, 1.0, v103
	v_add_f32_e32 v104, 1.0, v104
	v_add_f32_e32 v105, 1.0, v105
	v_rcp_f32_e32 v12, v12
	v_rcp_f32_e32 v13, v13
	v_rcp_f32_e32 v14, v14
	v_rcp_f32_e32 v15, v15
	v_rcp_f32_e32 v102, v102
	v_rcp_f32_e32 v103, v103
	v_rcp_f32_e32 v104, v104
	v_rcp_f32_e32 v105, v105
	v_mul_f32_e32 v12, v85, v12
	v_mul_f32_e32 v13, v85, v13
	v_mul_f32_e32 v14, v85, v14
	v_mul_f32_e32 v15, v85, v15
	v_mul_f32_e32 v102, v102, v174
	v_mul_f32_e32 v103, v103, v175
	v_mul_f32_e32 v104, v104, v176
	v_mul_f32_e32 v105, v105, v177
	v_exp_f32_e32 v12, v12
	v_exp_f32_e32 v13, v13
	v_exp_f32_e32 v14, v14
	v_exp_f32_e32 v15, v15
	s_nop 0
	v_fma_f32 v138, -v12, v12, 1.0
	v_fma_f32 v139, -v13, v13, 1.0
	v_fma_f32 v140, -v14, v14, 1.0
	v_fma_f32 v141, -v15, v15, 1.0
	v_max_f32_e32 v138, 0, v138
	v_max_f32_e32 v139, 0, v139
	v_max_f32_e32 v140, 0, v140
	v_max_f32_e32 v141, 0, v141
	v_sqrt_f32_e32 v138, v138
	v_sqrt_f32_e32 v139, v139
	v_sqrt_f32_e32 v140, v140
	v_sqrt_f32_e32 v141, v141
	s_nop 0
	v_mul_f32_e32 v102, v138, v102
	v_mul_f32_e32 v103, v139, v103
	v_mul_f32_e32 v104, v140, v104
	v_mul_f32_e32 v105, v141, v105
	v_add_f32_e32 v16, v16, v75
	v_add_f32_e32 v17, v17, v75
	v_add_f32_e32 v18, v18, v75
	v_add_f32_e32 v19, v19, v75
	v_add_f32_e32 v106, v106, v84
	v_add_f32_e32 v107, v107, v84
	v_add_f32_e32 v108, v108, v84
	v_add_f32_e32 v109, v109, v84
	v_exp_f32_e32 v16, v16
	v_exp_f32_e32 v17, v17
	v_exp_f32_e32 v18, v18
	v_exp_f32_e32 v19, v19
	v_exp_f32_e32 v106, v106
	v_exp_f32_e32 v107, v107
	v_exp_f32_e32 v108, v108
	v_exp_f32_e32 v109, v109
	v_add_f32_e32 v16, 1.0, v16
	v_add_f32_e32 v17, 1.0, v17
	v_add_f32_e32 v18, 1.0, v18
	v_add_f32_e32 v19, 1.0, v19
	v_add_f32_e32 v106, 1.0, v106
	v_add_f32_e32 v107, 1.0, v107
	v_add_f32_e32 v108, 1.0, v108
	v_add_f32_e32 v109, 1.0, v109
	v_rcp_f32_e32 v16, v16
	v_rcp_f32_e32 v17, v17
	v_rcp_f32_e32 v18, v18
	v_rcp_f32_e32 v19, v19
	v_rcp_f32_e32 v106, v106
	v_rcp_f32_e32 v107, v107
	v_rcp_f32_e32 v108, v108
	v_rcp_f32_e32 v109, v109
	v_mul_f32_e32 v16, v85, v16
	v_mul_f32_e32 v17, v85, v17
	v_mul_f32_e32 v18, v85, v18
	v_mul_f32_e32 v19, v85, v19
	v_mul_f32_e32 v106, v106, v178
	v_mul_f32_e32 v107, v107, v179
	v_mul_f32_e32 v108, v108, v180
	v_mul_f32_e32 v109, v109, v181
	v_exp_f32_e32 v16, v16
	v_exp_f32_e32 v17, v17
	v_exp_f32_e32 v18, v18
; __device__ __forceinline__ float bf2f(u16 h) { return __uint_as_float(((unsigned)h) << 16); }
; __device__ __forceinline__ void lru_tile(const Params& P, int chunk, int head, int pass, char* smem_raw) {
;     ...
; #pragma unroll
;       for (int tc = 0; tc < 4; ++tc)
; #pragma unroll
;         for (int reg = 0; reg < 4; ++reg) {
;           const int tl = wid * 16 + (lane >> 4) * 4 + reg;
;           const int c = 16 * tc + (lane & 15);
;           const float r = __builtin_amdgcn_rcpf(1.f + __builtin_amdgcn_exp2f(acc[tc][reg] + ba[tc]));
;           const float ii = __builtin_amdgcn_rcpf(1.f + __builtin_amdgcn_exp2f(acc[tc + 4][reg] + bi[tc]));
;           const float la = -c8[tc] * r;
;           const float a = __builtin_amdgcn_exp2f(la);
;           const float ucv = bf2f(sm_uc[(sb * 64 + tl) * LDSS + c]);
;           const float bt = __builtin_amdgcn_sqrtf(fmaxf(1.f - a * a, 0.f)) * (ii * ucv);
;           sm_a[tl * 64 + c] = a;
;           sm_b[tl * 64 + c] = bt;
;         }
	v_exp_f32_e32 v19, v19
	s_nop 0
	v_fma_f32 v138, -v16, v16, 1.0
	v_fma_f32 v139, -v17, v17, 1.0
	v_fma_f32 v140, -v18, v18, 1.0
	v_fma_f32 v141, -v19, v19, 1.0
	v_max_f32_e32 v138, 0, v138
	v_max_f32_e32 v139, 0, v139
	v_max_f32_e32 v140, 0, v140
	v_max_f32_e32 v141, 0, v141
	v_sqrt_f32_e32 v138, v138
	v_sqrt_f32_e32 v139, v139
	v_sqrt_f32_e32 v140, v140
	v_sqrt_f32_e32 v141, v141
	s_nop 0
	v_mul_f32_e32 v106, v138, v106
	v_mul_f32_e32 v107, v139, v107
	v_mul_f32_e32 v108, v140, v108
	v_mul_f32_e32 v109, v141, v109
	v_add_f32_e32 v20, v20, v75
	v_add_f32_e32 v21, v21, v75
	v_add_f32_e32 v22, v22, v75
	v_add_f32_e32 v23, v23, v75
	v_add_f32_e32 v110, v110, v84
	v_add_f32_e32 v111, v111, v84
	v_add_f32_e32 v112, v112, v84
	v_add_f32_e32 v113, v113, v84
	v_exp_f32_e32 v20, v20
	v_exp_f32_e32 v21, v21
	v_exp_f32_e32 v22, v22
	v_exp_f32_e32 v23, v23
	v_exp_f32_e32 v110, v110
	v_exp_f32_e32 v111, v111
	v_exp_f32_e32 v112, v112
	v_exp_f32_e32 v113, v113
	v_add_f32_e32 v20, 1.0, v20
	v_add_f32_e32 v21, 1.0, v21
	v_add_f32_e32 v22, 1.0, v22
	v_add_f32_e32 v23, 1.0, v23
	v_add_f32_e32 v110, 1.0, v110
	v_add_f32_e32 v111, 1.0, v111
	v_add_f32_e32 v112, 1.0, v112
	v_add_f32_e32 v113, 1.0, v113
	v_rcp_f32_e32 v20, v20
	v_rcp_f32_e32 v21, v21
	v_rcp_f32_e32 v22, v22
	v_rcp_f32_e32 v23, v23
	v_rcp_f32_e32 v110, v110
	v_rcp_f32_e32 v111, v111
	v_rcp_f32_e32 v112, v112
	v_rcp_f32_e32 v113, v113
	v_mul_f32_e32 v20, v85, v20
	v_mul_f32_e32 v21, v85, v21
	v_mul_f32_e32 v22, v85, v22
	v_mul_f32_e32 v23, v85, v23
	v_mul_f32_e32 v110, v110, v182
	v_mul_f32_e32 v111, v111, v183
	v_mul_f32_e32 v112, v112, v184
	v_mul_f32_e32 v113, v113, v185
	v_exp_f32_e32 v20, v20
	v_exp_f32_e32 v21, v21
	v_exp_f32_e32 v22, v22
	v_exp_f32_e32 v23, v23
	s_nop 0
	v_fma_f32 v138, -v20, v20, 1.0
	v_fma_f32 v139, -v21, v21, 1.0
	v_fma_f32 v140, -v22, v22, 1.0
	v_fma_f32 v141, -v23, v23, 1.0
	v_max_f32_e32 v138, 0, v138
	v_max_f32_e32 v139, 0, v139
	v_max_f32_e32 v140, 0, v140
	v_max_f32_e32 v141, 0, v141
	v_sqrt_f32_e32 v138, v138
	v_sqrt_f32_e32 v139, v139
	v_sqrt_f32_e32 v140, v140
	v_sqrt_f32_e32 v141, v141
	s_nop 0
	v_mul_f32_e32 v110, v138, v110
	v_mul_f32_e32 v111, v139, v111
	v_mul_f32_e32 v112, v140, v112
	v_mul_f32_e32 v113, v141, v113
	v_add_f32_e32 v24, v24, v75
	v_add_f32_e32 v25, v25, v75
	v_add_f32_e32 v26, v26, v75
	v_add_f32_e32 v27, v27, v75
	v_add_f32_e32 v114, v114, v84
	v_add_f32_e32 v115, v115, v84
	v_add_f32_e32 v116, v116, v84
	v_add_f32_e32 v117, v117, v84
	v_exp_f32_e32 v24, v24
	v_exp_f32_e32 v25, v25
	v_exp_f32_e32 v26, v26
	v_exp_f32_e32 v27, v27
	v_exp_f32_e32 v114, v114
	v_exp_f32_e32 v115, v115
	v_exp_f32_e32 v116, v116
	v_exp_f32_e32 v117, v117
	v_add_f32_e32 v24, 1.0, v24
	v_add_f32_e32 v25, 1.0, v25
	v_add_f32_e32 v26, 1.0, v26
	v_add_f32_e32 v27, 1.0, v27
	v_add_f32_e32 v114, 1.0, v114
	v_add_f32_e32 v115, 1.0, v115
	v_add_f32_e32 v116, 1.0, v116
	v_add_f32_e32 v117, 1.0, v117
	v_rcp_f32_e32 v24, v24
	v_rcp_f32_e32 v25, v25
	v_rcp_f32_e32 v26, v26
	v_rcp_f32_e32 v27, v27
	v_rcp_f32_e32 v114, v114
	v_rcp_f32_e32 v115, v115
	v_rcp_f32_e32 v116, v116
	v_rcp_f32_e32 v117, v117
	v_mul_f32_e32 v24, v85, v24
	v_mul_f32_e32 v25, v85, v25
	v_mul_f32_e32 v26, v85, v26
	v_mul_f32_e32 v27, v85, v27
	v_mul_f32_e32 v114, v114, v186
	v_mul_f32_e32 v115, v115, v187
	v_mul_f32_e32 v116, v116, v188
	v_mul_f32_e32 v117, v117, v189
	v_exp_f32_e32 v24, v24
	v_exp_f32_e32 v25, v25
	v_exp_f32_e32 v26, v26
	v_exp_f32_e32 v27, v27
	s_nop 0
	v_fma_f32 v138, -v24, v24, 1.0
	v_fma_f32 v139, -v25, v25, 1.0
	v_fma_f32 v140, -v26, v26, 1.0
	v_fma_f32 v141, -v27, v27, 1.0
	v_max_f32_e32 v138, 0, v138
	v_max_f32_e32 v139, 0, v139
	v_max_f32_e32 v140, 0, v140
	v_max_f32_e32 v141, 0, v141
	v_sqrt_f32_e32 v138, v138
	v_sqrt_f32_e32 v139, v139
	v_sqrt_f32_e32 v140, v140
	v_sqrt_f32_e32 v141, v141
	s_nop 0
	v_mul_f32_e32 v114, v138, v114
	v_mul_f32_e32 v115, v139, v115
	v_mul_f32_e32 v116, v140, v116
	v_mul_f32_e32 v117, v141, v117
	v_add_f32_e32 v28, v28, v75
	v_add_f32_e32 v29, v29, v75
	v_add_f32_e32 v30, v30, v75
	v_add_f32_e32 v31, v31, v75
	v_add_f32_e32 v118, v118, v84
	v_add_f32_e32 v119, v119, v84
	v_add_f32_e32 v120, v120, v84
	v_add_f32_e32 v121, v121, v84
	v_exp_f32_e32 v28, v28
	v_exp_f32_e32 v29, v29
	v_exp_f32_e32 v30, v30
	v_exp_f32_e32 v31, v31
	v_exp_f32_e32 v118, v118
	v_exp_f32_e32 v119, v119
	v_exp_f32_e32 v120, v120
	v_exp_f32_e32 v121, v121
	v_add_f32_e32 v28, 1.0, v28
	v_add_f32_e32 v29, 1.0, v29
	v_add_f32_e32 v30, 1.0, v30
	v_add_f32_e32 v31, 1.0, v31
	v_add_f32_e32 v118, 1.0, v118
	v_add_f32_e32 v119, 1.0, v119
	v_add_f32_e32 v120, 1.0, v120
	v_add_f32_e32 v121, 1.0, v121
	v_rcp_f32_e32 v28, v28
	v_rcp_f32_e32 v29, v29
	v_rcp_f32_e32 v30, v30
	v_rcp_f32_e32 v31, v31
	v_rcp_f32_e32 v118, v118
	v_rcp_f32_e32 v119, v119
	v_rcp_f32_e32 v120, v120
	v_rcp_f32_e32 v121, v121
	v_mul_f32_e32 v28, v85, v28
	v_mul_f32_e32 v29, v85, v29
	v_mul_f32_e32 v30, v85, v30
	v_mul_f32_e32 v31, v85, v31
	v_mul_f32_e32 v118, v118, v190
	v_mul_f32_e32 v119, v119, v191
	v_mul_f32_e32 v120, v120, v192
	v_mul_f32_e32 v121, v121, v193
	v_exp_f32_e32 v28, v28
	v_exp_f32_e32 v29, v29
	v_exp_f32_e32 v30, v30
	v_exp_f32_e32 v31, v31
	s_nop 0
	v_fma_f32 v138, -v28, v28, 1.0
	v_fma_f32 v139, -v29, v29, 1.0
	v_fma_f32 v140, -v30, v30, 1.0
	v_fma_f32 v141, -v31, v31, 1.0
	v_max_f32_e32 v138, 0, v138
	v_max_f32_e32 v139, 0, v139
	v_max_f32_e32 v140, 0, v140
	v_max_f32_e32 v141, 0, v141
	v_sqrt_f32_e32 v138, v138
	v_sqrt_f32_e32 v139, v139
	v_sqrt_f32_e32 v140, v140
	v_sqrt_f32_e32 v141, v141
	s_nop 0
	v_mul_f32_e32 v118, v138, v118
	v_mul_f32_e32 v119, v139, v119
	v_mul_f32_e32 v120, v140, v120
; __device__ __forceinline__ void lru_tile(const Params& P, int chunk, int head, int pass, char* smem_raw) {
;     ...
; #pragma unroll
;       for (int s = 0; s < 2; ++s) {
;         const bf16x8 af = *reinterpret_cast<const bf16x8*>(&sm_uc[(sb * 64 + wid * 16 + (lane & 15)) * LDSS + s * 32 + (lane >> 4) * 8]);
; #pragma unroll
;         for (int t = 0; t < 8; ++t) {
;           const bf16x8 bfr = *reinterpret_cast<const bf16x8*>(&sm_w[(t * 16 + (lane & 15)) * LDSS + s * 32 + (lane >> 4) * 8]);
;           acc[t] = __builtin_amdgcn_mfma_f32_16x16x32_bf16(af, bfr, acc[t], 0, 0, 0);
;         }
;       }
;     ...
;       const int pos = (d == 0) ? q : 3 - q;
;       {
;         float Pp = 1.f, H = 0.f;
; #pragma unroll 4
;         for (int i = 0; i < 16; ++i) {
;           const int tl = (d == 0) ? (q * 16 + i) : (q * 16 + 15 - i);
;           const float a = sm_a[tl * 64 + ch], b = sm_b[tl * 64 + ch];
;           H = a * H + b; Pp *= a;
;         }
;         sm_ph[pos * 64 + ch] = make_float2(Pp, H);
;       }
;       __syncthreads();
;       const float2 p0 = sm_ph[ch], p1 = sm_ph[64 + ch], p2 = sm_ph[128 + ch], p3 = sm_ph[192 + ch];
;       if (pass == 2) {
;         float hin = cB;
;         if (pos > 0) hin = p0.x * hin + p0.y;
;         if (pos > 1) hin = p1.x * hin + p1.y;
;         if (pos > 2) hin = p2.x * hin + p2.y;
;         float h = hin;
	v_mul_f32_e32 v121, v141, v121
	v_mov_b32_e32 v253, v0
	v_mov_b32_e32 v254, v90
	v_fma_f32 v254, v1, v254, v91
	v_mul_f32_e32 v253, v253, v1
	v_fma_f32 v254, v2, v254, v92
	v_mul_f32_e32 v253, v253, v2
	v_fma_f32 v254, v3, v254, v93
	v_mul_f32_e32 v253, v253, v3
	v_fma_f32 v254, v4, v254, v94
	v_mul_f32_e32 v253, v253, v4
	v_fma_f32 v254, v5, v254, v95
	v_mul_f32_e32 v253, v253, v5
	v_fma_f32 v254, v6, v254, v96
	v_mul_f32_e32 v253, v253, v6
	v_fma_f32 v254, v7, v254, v97
	v_mul_f32_e32 v253, v253, v7
	v_fma_f32 v254, v8, v254, v98
	v_mul_f32_e32 v253, v253, v8
	v_fma_f32 v254, v9, v254, v99
	v_mul_f32_e32 v253, v253, v9
	v_fma_f32 v254, v10, v254, v100
	v_mul_f32_e32 v253, v253, v10
	v_fma_f32 v254, v11, v254, v101
	v_mul_f32_e32 v253, v253, v11
	v_fma_f32 v254, v12, v254, v102
	v_mul_f32_e32 v253, v253, v12
	v_fma_f32 v254, v13, v254, v103
	v_mul_f32_e32 v253, v253, v13
	v_fma_f32 v254, v14, v254, v104
	v_mul_f32_e32 v253, v253, v14
	v_fma_f32 v254, v15, v254, v105
	v_mul_f32_e32 v253, v253, v15
	v_fma_f32 v254, v16, v254, v106
	v_mul_f32_e32 v253, v253, v16
	v_fma_f32 v254, v17, v254, v107
	v_mul_f32_e32 v253, v253, v17
	v_fma_f32 v254, v18, v254, v108
	v_mul_f32_e32 v253, v253, v18
	v_fma_f32 v254, v19, v254, v109
	v_mul_f32_e32 v253, v253, v19
	v_fma_f32 v254, v20, v254, v110
	v_mul_f32_e32 v253, v253, v20
	v_fma_f32 v254, v21, v254, v111
	v_mul_f32_e32 v253, v253, v21
	v_fma_f32 v254, v22, v254, v112
	v_mul_f32_e32 v253, v253, v22
	v_fma_f32 v254, v23, v254, v113
	v_mul_f32_e32 v253, v253, v23
	v_fma_f32 v254, v24, v254, v114
	v_mul_f32_e32 v253, v253, v24
	v_fma_f32 v254, v25, v254, v115
	v_mul_f32_e32 v253, v253, v25
	v_fma_f32 v254, v26, v254, v116
	v_mul_f32_e32 v253, v253, v26
	v_fma_f32 v254, v27, v254, v117
	v_mul_f32_e32 v253, v253, v27
	v_fma_f32 v254, v28, v254, v118
	v_mul_f32_e32 v253, v253, v28
	v_fma_f32 v254, v29, v254, v119
	v_mul_f32_e32 v253, v253, v29
	v_fma_f32 v254, v30, v254, v120
	v_mul_f32_e32 v253, v253, v30
	v_fma_f32 v254, v31, v254, v121
	v_mul_f32_e32 v253, v253, v31
	v_mov_b32_e32 v138, v253
	v_mov_b32_e32 v139, v253
	s_nop 1
	v_permlane16_swap_b32_e32 v138, v139
	v_mov_b32_e32 v140, v138
	v_mov_b32_e32 v141, v139
	s_nop 1
	v_permlane32_swap_b32_e32 v138, v140
	v_permlane32_swap_b32_e32 v139, v141
	v_mov_b32_e32 v198, v254
	v_mov_b32_e32 v199, v254
	s_nop 1
	v_permlane16_swap_b32_e32 v198, v199
	v_mov_b32_e32 v200, v198
	v_mov_b32_e32 v201, v199
	s_nop 1
	v_permlane32_swap_b32_e32 v198, v200
	v_permlane32_swap_b32_e32 v199, v201
	v_mov_b32_e32 v136, v148
	v_fma_f32 v150, v138, v136, v198
	v_fma_f32 v151, v139, v150, v199
	v_fma_f32 v202, v140, v151, v200
	v_mov_b32_e32 v254, v136
	v_cndmask_b32_e64 v254, v254, v150, s[72:73]
	v_cndmask_b32_e64 v254, v254, v151, s[74:75]
	v_cndmask_b32_e64 v254, v254, v202, s[76:77]
	v_fma_f32 v205, v0, v254, v90
	v_fma_f32 v206, v1, v205, v91
	v_fma_f32 v207, v2, v206, v92
	v_fma_f32 v208, v3, v207, v93
	v_fma_f32 v209, v4, v208, v94
	v_fma_f32 v210, v5, v209, v95
	v_fma_f32 v211, v6, v210, v96
	v_fma_f32 v212, v7, v211, v97
	v_fma_f32 v213, v8, v212, v98
	v_fma_f32 v214, v9, v213, v99
	v_fma_f32 v215, v10, v214, v100
	v_fma_f32 v216, v11, v215, v101
	v_fma_f32 v217, v12, v216, v102
	v_fma_f32 v218, v13, v217, v103
	v_fma_f32 v219, v14, v218, v104
	v_fma_f32 v220, v15, v219, v105
	v_fma_f32 v221, v16, v220, v106
	v_fma_f32 v222, v17, v221, v107
	v_fma_f32 v223, v18, v222, v108
	v_fma_f32 v224, v19, v223, v109
	v_fma_f32 v225, v20, v224, v110
	v_fma_f32 v226, v21, v225, v111
	v_fma_f32 v227, v22, v226, v112
	v_fma_f32 v228, v23, v227, v113
	v_fma_f32 v229, v24, v228, v114
	v_fma_f32 v230, v25, v229, v115
	v_fma_f32 v231, v26, v230, v116
	v_fma_f32 v232, v27, v231, v117
	v_fma_f32 v233, v28, v232, v118
	v_fma_f32 v234, v29, v233, v119
	v_fma_f32 v235, v30, v234, v120
	v_fma_f32 v236, v31, v235, v121
	ds_read_b128 v[76:79], v131 offset:0
	ds_read_b128 v[80:83], v133 offset:0
	ds_read_b128 v[122:125], v131 offset:512
	ds_read_b128 v[126:129], v133 offset:512
	s_waitcnt vmcnt(0)
	s_waitcnt lgkmcnt(3)
	v_mfma_f32_16x16x32_bf16 v[0:3], v[76:79], v[238:241], 0
	v_mfma_f32_16x16x32_bf16 v[90:93], v[76:79], v[246:249], 0
	ds_read_b128 v[76:79], v131 offset:1024
	s_waitcnt lgkmcnt(3)
	v_mfma_f32_16x16x32_bf16 v[0:3], v[80:83], v[242:245], v[0:3]
	v_mfma_f32_16x16x32_bf16 v[90:93], v[80:83], v[194:197], v[90:93]
	ds_read_b128 v[80:83], v133 offset:1024
	s_waitcnt lgkmcnt(3)
	v_mfma_f32_16x16x32_bf16 v[4:7], v[122:125], v[238:241], 0
	v_mfma_f32_16x16x32_bf16 v[94:97], v[122:125], v[246:249], 0
	ds_read_b128 v[122:125], v131 offset:1536
	s_waitcnt lgkmcnt(3)
	v_mfma_f32_16x16x32_bf16 v[4:7], v[126:129], v[242:245], v[4:7]
	v_mfma_f32_16x16x32_bf16 v[94:97], v[126:129], v[194:197], v[94:97]
	ds_read_b128 v[126:129], v133 offset:1536
	s_waitcnt lgkmcnt(3)
	v_mfma_f32_16x16x32_bf16 v[8:11], v[76:79], v[238:241], 0
	v_mfma_f32_16x16x32_bf16 v[98:101], v[76:79], v[246:249], 0
	ds_read_b128 v[76:79], v131 offset:2048
	s_waitcnt lgkmcnt(3)
	v_mfma_f32_16x16x32_bf16 v[8:11], v[80:83], v[242:245], v[8:11]
	v_mfma_f32_16x16x32_bf16 v[98:101], v[80:83], v[194:197], v[98:101]
	ds_read_b128 v[80:83], v133 offset:2048
	s_waitcnt lgkmcnt(3)
	v_mfma_f32_16x16x32_bf16 v[12:15], v[122:125], v[238:241], 0
	v_mfma_f32_16x16x32_bf16 v[102:105], v[122:125], v[246:249], 0
	ds_read_b128 v[122:125], v131 offset:2560
	s_waitcnt lgkmcnt(3)
	v_mfma_f32_16x16x32_bf16 v[12:15], v[126:129], v[242:245], v[12:15]
	v_mfma_f32_16x16x32_bf16 v[102:105], v[126:129], v[194:197], v[102:105]
	ds_read_b128 v[126:129], v133 offset:2560
	s_waitcnt lgkmcnt(3)
; __device__ __forceinline__ float bf2f(u16 h) { return __uint_as_float(((unsigned)h) << 16); }
; __device__ __forceinline__ void lru_tile(const Params& P, int chunk, int head, int pass, char* smem_raw) {
;     ...
; #pragma unroll
;       for (int s = 0; s < 2; ++s) {
;         const bf16x8 af = *reinterpret_cast<const bf16x8*>(&sm_uc[(sb * 64 + wid * 16 + (lane & 15)) * LDSS + s * 32 + (lane >> 4) * 8]);
; #pragma unroll
;         for (int t = 0; t < 8; ++t) {
;           const bf16x8 bfr = *reinterpret_cast<const bf16x8*>(&sm_w[(t * 16 + (lane & 15)) * LDSS + s * 32 + (lane >> 4) * 8]);
;           acc[t] = __builtin_amdgcn_mfma_f32_16x16x32_bf16(af, bfr, acc[t], 0, 0, 0);
;         }
;       }
; #pragma unroll
;       for (int tc = 0; tc < 4; ++tc)
; #pragma unroll
;         for (int reg = 0; reg < 4; ++reg) {
;           const int tl = wid * 16 + (lane >> 4) * 4 + reg;
;           const int c = 16 * tc + (lane & 15);
;           const float r = __builtin_amdgcn_rcpf(1.f + __builtin_amdgcn_exp2f(acc[tc][reg] + ba[tc]));
;           const float ii = __builtin_amdgcn_rcpf(1.f + __builtin_amdgcn_exp2f(acc[tc + 4][reg] + bi[tc]));
;           const float la = -c8[tc] * r;
;           const float a = __builtin_amdgcn_exp2f(la);
;           const float ucv = bf2f(sm_uc[(sb * 64 + tl) * LDSS + c]);
;           const float bt = __builtin_amdgcn_sqrtf(fmaxf(1.f - a * a, 0.f)) * (ii * ucv);
;           sm_a[tl * 64 + c] = a;
;           sm_b[tl * 64 + c] = bt;
;         }
	v_mfma_f32_16x16x32_bf16 v[16:19], v[76:79], v[238:241], 0
	v_mfma_f32_16x16x32_bf16 v[106:109], v[76:79], v[246:249], 0
	ds_read_b128 v[76:79], v131 offset:3072
	s_waitcnt lgkmcnt(3)
	v_mfma_f32_16x16x32_bf16 v[16:19], v[80:83], v[242:245], v[16:19]
	v_mfma_f32_16x16x32_bf16 v[106:109], v[80:83], v[194:197], v[106:109]
	ds_read_b128 v[80:83], v133 offset:3072
	s_waitcnt lgkmcnt(3)
	v_mfma_f32_16x16x32_bf16 v[20:23], v[122:125], v[238:241], 0
	v_mfma_f32_16x16x32_bf16 v[110:113], v[122:125], v[246:249], 0
	ds_read_b128 v[122:125], v131 offset:3584
	s_waitcnt lgkmcnt(3)
	v_mfma_f32_16x16x32_bf16 v[20:23], v[126:129], v[242:245], v[20:23]
	v_mfma_f32_16x16x32_bf16 v[110:113], v[126:129], v[194:197], v[110:113]
	ds_read_b128 v[126:129], v133 offset:3584
	s_waitcnt lgkmcnt(3)
	v_mfma_f32_16x16x32_bf16 v[24:27], v[76:79], v[238:241], 0
	v_mfma_f32_16x16x32_bf16 v[114:117], v[76:79], v[246:249], 0
	s_waitcnt lgkmcnt(2)
	v_mfma_f32_16x16x32_bf16 v[24:27], v[80:83], v[242:245], v[24:27]
	v_mfma_f32_16x16x32_bf16 v[114:117], v[80:83], v[194:197], v[114:117]
	s_waitcnt lgkmcnt(1)
	v_mfma_f32_16x16x32_bf16 v[28:31], v[122:125], v[238:241], 0
	v_mfma_f32_16x16x32_bf16 v[118:121], v[122:125], v[246:249], 0
	s_waitcnt lgkmcnt(0)
	v_mfma_f32_16x16x32_bf16 v[28:31], v[126:129], v[242:245], v[28:31]
	v_mfma_f32_16x16x32_bf16 v[118:121], v[126:129], v[194:197], v[118:121]
	s_lshl_b32 s0, s56, 8
	s_add_u32 s0, s0, 0x0
	s_add_u32 s4, s20, s0
	s_addc_u32 s5, s21, 0
	global_load_dwordx4 v[238:241], v251, s[4:5]
	global_load_dwordx4 v[242:245], v251, s[4:5] offset:64
	s_add_u32 s4, s4, 0x2000
	s_addc_u32 s5, s5, 0
	global_load_dwordx4 v[246:249], v251, s[4:5]
	global_load_dwordx4 v[194:197], v251, s[4:5] offset:64
	s_nop 7
	s_nop 7
	v_add_f32_e32 v0, v0, v145
	v_add_f32_e32 v1, v1, v145
	v_add_f32_e32 v2, v2, v145
	v_add_f32_e32 v3, v3, v145
	v_add_f32_e32 v90, v90, v146
	v_add_f32_e32 v91, v91, v146
	v_add_f32_e32 v92, v92, v146
	v_add_f32_e32 v93, v93, v146
	v_exp_f32_e32 v0, v0
	v_exp_f32_e32 v1, v1
	v_exp_f32_e32 v2, v2
	v_exp_f32_e32 v3, v3
	v_exp_f32_e32 v90, v90
	v_exp_f32_e32 v91, v91
	v_exp_f32_e32 v92, v92
	v_exp_f32_e32 v93, v93
	v_add_f32_e32 v0, 1.0, v0
	v_add_f32_e32 v1, 1.0, v1
	v_add_f32_e32 v2, 1.0, v2
	v_add_f32_e32 v3, 1.0, v3
	v_add_f32_e32 v90, 1.0, v90
	v_add_f32_e32 v91, 1.0, v91
	v_add_f32_e32 v92, 1.0, v92
	v_add_f32_e32 v93, 1.0, v93
	v_rcp_f32_e32 v0, v0
	v_rcp_f32_e32 v1, v1
	v_rcp_f32_e32 v2, v2
	v_rcp_f32_e32 v3, v3
	v_rcp_f32_e32 v90, v90
	v_rcp_f32_e32 v91, v91
	v_rcp_f32_e32 v92, v92
	v_rcp_f32_e32 v93, v93
	v_mul_f32_e32 v0, v147, v0
	v_mul_f32_e32 v1, v147, v1
	v_mul_f32_e32 v2, v147, v2
	v_mul_f32_e32 v3, v147, v3
	v_mul_f32_e32 v90, v90, v162
	v_mul_f32_e32 v91, v91, v163
	v_mul_f32_e32 v92, v92, v164
	v_mul_f32_e32 v93, v93, v165
	v_exp_f32_e32 v0, v0
	v_exp_f32_e32 v1, v1
	v_exp_f32_e32 v2, v2
	v_exp_f32_e32 v3, v3
	s_nop 0
	v_fma_f32 v138, -v0, v0, 1.0
	v_fma_f32 v139, -v1, v1, 1.0
	v_fma_f32 v140, -v2, v2, 1.0
	v_fma_f32 v141, -v3, v3, 1.0
	v_max_f32_e32 v138, 0, v138
	v_max_f32_e32 v139, 0, v139
	v_max_f32_e32 v140, 0, v140
	v_max_f32_e32 v141, 0, v141
	v_sqrt_f32_e32 v138, v138
	v_sqrt_f32_e32 v139, v139
	v_sqrt_f32_e32 v140, v140
	v_sqrt_f32_e32 v141, v141
	s_nop 0
	v_mul_f32_e32 v90, v138, v90
	v_mul_f32_e32 v91, v139, v91
	v_mul_f32_e32 v92, v140, v92
	v_mul_f32_e32 v93, v141, v93
	v_add_f32_e32 v4, v4, v145
	v_add_f32_e32 v5, v5, v145
	v_add_f32_e32 v6, v6, v145
	v_add_f32_e32 v7, v7, v145
	v_add_f32_e32 v94, v94, v146
	v_add_f32_e32 v95, v95, v146
	v_add_f32_e32 v96, v96, v146
	v_add_f32_e32 v97, v97, v146
	v_exp_f32_e32 v4, v4
	v_exp_f32_e32 v5, v5
	v_exp_f32_e32 v6, v6
	v_exp_f32_e32 v7, v7
	v_exp_f32_e32 v94, v94
	v_exp_f32_e32 v95, v95
	v_exp_f32_e32 v96, v96
	v_exp_f32_e32 v97, v97
	v_add_f32_e32 v4, 1.0, v4
	v_add_f32_e32 v5, 1.0, v5
	v_add_f32_e32 v6, 1.0, v6
	v_add_f32_e32 v7, 1.0, v7
	v_add_f32_e32 v94, 1.0, v94
	v_add_f32_e32 v95, 1.0, v95
	v_add_f32_e32 v96, 1.0, v96
	v_add_f32_e32 v97, 1.0, v97
	v_rcp_f32_e32 v4, v4
	v_rcp_f32_e32 v5, v5
	v_rcp_f32_e32 v6, v6
	v_rcp_f32_e32 v7, v7
	v_rcp_f32_e32 v94, v94
	v_rcp_f32_e32 v95, v95
	v_rcp_f32_e32 v96, v96
	v_rcp_f32_e32 v97, v97
	v_mul_f32_e32 v4, v147, v4
	v_mul_f32_e32 v5, v147, v5
	v_mul_f32_e32 v6, v147, v6
	v_mul_f32_e32 v7, v147, v7
	v_mul_f32_e32 v94, v94, v166
	v_mul_f32_e32 v95, v95, v167
	v_mul_f32_e32 v96, v96, v168
	v_mul_f32_e32 v97, v97, v169
	v_exp_f32_e32 v4, v4
	v_exp_f32_e32 v5, v5
	v_exp_f32_e32 v6, v6
	v_exp_f32_e32 v7, v7
	s_nop 0
	v_fma_f32 v138, -v4, v4, 1.0
	v_fma_f32 v139, -v5, v5, 1.0
	v_fma_f32 v140, -v6, v6, 1.0
	v_fma_f32 v141, -v7, v7, 1.0
	v_max_f32_e32 v138, 0, v138
	v_max_f32_e32 v139, 0, v139
	v_max_f32_e32 v140, 0, v140
	v_max_f32_e32 v141, 0, v141
	v_sqrt_f32_e32 v138, v138
	v_sqrt_f32_e32 v139, v139
	v_sqrt_f32_e32 v140, v140
	v_sqrt_f32_e32 v141, v141
	s_nop 0
	v_mul_f32_e32 v94, v138, v94
	v_mul_f32_e32 v95, v139, v95
	v_mul_f32_e32 v96, v140, v96
	v_mul_f32_e32 v97, v141, v97
	v_add_f32_e32 v8, v8, v145
	v_add_f32_e32 v9, v9, v145
	v_add_f32_e32 v10, v10, v145
	v_add_f32_e32 v11, v11, v145
	v_add_f32_e32 v98, v98, v146
	v_add_f32_e32 v99, v99, v146
	v_add_f32_e32 v100, v100, v146
	v_add_f32_e32 v101, v101, v146
	v_exp_f32_e32 v8, v8
	v_exp_f32_e32 v9, v9
	v_exp_f32_e32 v10, v10
	v_exp_f32_e32 v11, v11
	v_exp_f32_e32 v98, v98
	v_exp_f32_e32 v99, v99
	v_exp_f32_e32 v100, v100
	v_exp_f32_e32 v101, v101
	v_add_f32_e32 v8, 1.0, v8
	v_add_f32_e32 v9, 1.0, v9
	v_add_f32_e32 v10, 1.0, v10
	v_add_f32_e32 v11, 1.0, v11
	v_add_f32_e32 v98, 1.0, v98
	v_add_f32_e32 v99, 1.0, v99
	v_add_f32_e32 v100, 1.0, v100
; __device__ __forceinline__ float bf2f(u16 h) { return __uint_as_float(((unsigned)h) << 16); }
; __device__ __forceinline__ void lru_tile(const Params& P, int chunk, int head, int pass, char* smem_raw) {
;     ...
; #pragma unroll
;       for (int tc = 0; tc < 4; ++tc)
; #pragma unroll
;         for (int reg = 0; reg < 4; ++reg) {
;           const int tl = wid * 16 + (lane >> 4) * 4 + reg;
;           const int c = 16 * tc + (lane & 15);
;           const float r = __builtin_amdgcn_rcpf(1.f + __builtin_amdgcn_exp2f(acc[tc][reg] + ba[tc]));
;           const float ii = __builtin_amdgcn_rcpf(1.f + __builtin_amdgcn_exp2f(acc[tc + 4][reg] + bi[tc]));
;           const float la = -c8[tc] * r;
;           const float a = __builtin_amdgcn_exp2f(la);
;           const float ucv = bf2f(sm_uc[(sb * 64 + tl) * LDSS + c]);
;           const float bt = __builtin_amdgcn_sqrtf(fmaxf(1.f - a * a, 0.f)) * (ii * ucv);
;           sm_a[tl * 64 + c] = a;
;           sm_b[tl * 64 + c] = bt;
;         }
	v_add_f32_e32 v101, 1.0, v101
	v_rcp_f32_e32 v8, v8
	v_rcp_f32_e32 v9, v9
	v_rcp_f32_e32 v10, v10
	v_rcp_f32_e32 v11, v11
	v_rcp_f32_e32 v98, v98
	v_rcp_f32_e32 v99, v99
	v_rcp_f32_e32 v100, v100
	v_rcp_f32_e32 v101, v101
	v_mul_f32_e32 v8, v147, v8
	v_mul_f32_e32 v9, v147, v9
	v_mul_f32_e32 v10, v147, v10
	v_mul_f32_e32 v11, v147, v11
	v_mul_f32_e32 v98, v98, v170
	v_mul_f32_e32 v99, v99, v171
	v_mul_f32_e32 v100, v100, v172
	v_mul_f32_e32 v101, v101, v173
	v_exp_f32_e32 v8, v8
	v_exp_f32_e32 v9, v9
	v_exp_f32_e32 v10, v10
	v_exp_f32_e32 v11, v11
	s_nop 0
	v_fma_f32 v138, -v8, v8, 1.0
	v_fma_f32 v139, -v9, v9, 1.0
	v_fma_f32 v140, -v10, v10, 1.0
	v_fma_f32 v141, -v11, v11, 1.0
	v_max_f32_e32 v138, 0, v138
	v_max_f32_e32 v139, 0, v139
	v_max_f32_e32 v140, 0, v140
	v_max_f32_e32 v141, 0, v141
	v_sqrt_f32_e32 v138, v138
	v_sqrt_f32_e32 v139, v139
	v_sqrt_f32_e32 v140, v140
	v_sqrt_f32_e32 v141, v141
	s_nop 0
	v_mul_f32_e32 v98, v138, v98
	v_mul_f32_e32 v99, v139, v99
	v_mul_f32_e32 v100, v140, v100
	v_mul_f32_e32 v101, v141, v101
	v_add_f32_e32 v12, v12, v145
	v_add_f32_e32 v13, v13, v145
	v_add_f32_e32 v14, v14, v145
	v_add_f32_e32 v15, v15, v145
	v_add_f32_e32 v102, v102, v146
	v_add_f32_e32 v103, v103, v146
	v_add_f32_e32 v104, v104, v146
	v_add_f32_e32 v105, v105, v146
	v_exp_f32_e32 v12, v12
	v_exp_f32_e32 v13, v13
	v_exp_f32_e32 v14, v14
	v_exp_f32_e32 v15, v15
	v_exp_f32_e32 v102, v102
	v_exp_f32_e32 v103, v103
	v_exp_f32_e32 v104, v104
	v_exp_f32_e32 v105, v105
	v_add_f32_e32 v12, 1.0, v12
	v_add_f32_e32 v13, 1.0, v13
	v_add_f32_e32 v14, 1.0, v14
	v_add_f32_e32 v15, 1.0, v15
	v_add_f32_e32 v102, 1.0, v102
	v_add_f32_e32 v103, 1.0, v103
	v_add_f32_e32 v104, 1.0, v104
	v_add_f32_e32 v105, 1.0, v105
	v_rcp_f32_e32 v12, v12
	v_rcp_f32_e32 v13, v13
	v_rcp_f32_e32 v14, v14
	v_rcp_f32_e32 v15, v15
	v_rcp_f32_e32 v102, v102
	v_rcp_f32_e32 v103, v103
	v_rcp_f32_e32 v104, v104
	v_rcp_f32_e32 v105, v105
	v_mul_f32_e32 v12, v147, v12
	v_mul_f32_e32 v13, v147, v13
	v_mul_f32_e32 v14, v147, v14
	v_mul_f32_e32 v15, v147, v15
	v_mul_f32_e32 v102, v102, v174
	v_mul_f32_e32 v103, v103, v175
	v_mul_f32_e32 v104, v104, v176
	v_mul_f32_e32 v105, v105, v177
	v_exp_f32_e32 v12, v12
	v_exp_f32_e32 v13, v13
	v_exp_f32_e32 v14, v14
	v_exp_f32_e32 v15, v15
	s_nop 0
	v_fma_f32 v138, -v12, v12, 1.0
	v_fma_f32 v139, -v13, v13, 1.0
	v_fma_f32 v140, -v14, v14, 1.0
	v_fma_f32 v141, -v15, v15, 1.0
	v_max_f32_e32 v138, 0, v138
	v_max_f32_e32 v139, 0, v139
	v_max_f32_e32 v140, 0, v140
	v_max_f32_e32 v141, 0, v141
	v_sqrt_f32_e32 v138, v138
	v_sqrt_f32_e32 v139, v139
	v_sqrt_f32_e32 v140, v140
	v_sqrt_f32_e32 v141, v141
	s_nop 0
	v_mul_f32_e32 v102, v138, v102
	v_mul_f32_e32 v103, v139, v103
	v_mul_f32_e32 v104, v140, v104
	v_mul_f32_e32 v105, v141, v105
	v_add_f32_e32 v16, v16, v145
	v_add_f32_e32 v17, v17, v145
	v_add_f32_e32 v18, v18, v145
	v_add_f32_e32 v19, v19, v145
	v_add_f32_e32 v106, v106, v146
	v_add_f32_e32 v107, v107, v146
	v_add_f32_e32 v108, v108, v146
	v_add_f32_e32 v109, v109, v146
	v_exp_f32_e32 v16, v16
	v_exp_f32_e32 v17, v17
	v_exp_f32_e32 v18, v18
	v_exp_f32_e32 v19, v19
	v_exp_f32_e32 v106, v106
	v_exp_f32_e32 v107, v107
	v_exp_f32_e32 v108, v108
	v_exp_f32_e32 v109, v109
	v_add_f32_e32 v16, 1.0, v16
	v_add_f32_e32 v17, 1.0, v17
	v_add_f32_e32 v18, 1.0, v18
	v_add_f32_e32 v19, 1.0, v19
	v_add_f32_e32 v106, 1.0, v106
	v_add_f32_e32 v107, 1.0, v107
	v_add_f32_e32 v108, 1.0, v108
	v_add_f32_e32 v109, 1.0, v109
	v_rcp_f32_e32 v16, v16
	v_rcp_f32_e32 v17, v17
	v_rcp_f32_e32 v18, v18
	v_rcp_f32_e32 v19, v19
	v_rcp_f32_e32 v106, v106
	v_rcp_f32_e32 v107, v107
	v_rcp_f32_e32 v108, v108
	v_rcp_f32_e32 v109, v109
	v_mul_f32_e32 v16, v147, v16
	v_mul_f32_e32 v17, v147, v17
	v_mul_f32_e32 v18, v147, v18
	v_mul_f32_e32 v19, v147, v19
	v_mul_f32_e32 v106, v106, v178
	v_mul_f32_e32 v107, v107, v179
	v_mul_f32_e32 v108, v108, v180
	v_mul_f32_e32 v109, v109, v181
	v_exp_f32_e32 v16, v16
	v_exp_f32_e32 v17, v17
	v_exp_f32_e32 v18, v18
	v_exp_f32_e32 v19, v19
	s_nop 0
	v_fma_f32 v138, -v16, v16, 1.0
	v_fma_f32 v139, -v17, v17, 1.0
	v_fma_f32 v140, -v18, v18, 1.0
	v_fma_f32 v141, -v19, v19, 1.0
	v_max_f32_e32 v138, 0, v138
	v_max_f32_e32 v139, 0, v139
	v_max_f32_e32 v140, 0, v140
	v_max_f32_e32 v141, 0, v141
	v_sqrt_f32_e32 v138, v138
	v_sqrt_f32_e32 v139, v139
	v_sqrt_f32_e32 v140, v140
	v_sqrt_f32_e32 v141, v141
	s_nop 0
	v_mul_f32_e32 v106, v138, v106
	v_mul_f32_e32 v107, v139, v107
	v_mul_f32_e32 v108, v140, v108
	v_mul_f32_e32 v109, v141, v109
	v_add_f32_e32 v20, v20, v145
	v_add_f32_e32 v21, v21, v145
	v_add_f32_e32 v22, v22, v145
	v_add_f32_e32 v23, v23, v145
	v_add_f32_e32 v110, v110, v146
	v_add_f32_e32 v111, v111, v146
	v_add_f32_e32 v112, v112, v146
	v_add_f32_e32 v113, v113, v146
	v_exp_f32_e32 v20, v20
	v_exp_f32_e32 v21, v21
	v_exp_f32_e32 v22, v22
	v_exp_f32_e32 v23, v23
	v_exp_f32_e32 v110, v110
	v_exp_f32_e32 v111, v111
	v_exp_f32_e32 v112, v112
	v_exp_f32_e32 v113, v113
	v_add_f32_e32 v20, 1.0, v20
	v_add_f32_e32 v21, 1.0, v21
	v_add_f32_e32 v22, 1.0, v22
	v_add_f32_e32 v23, 1.0, v23
	v_add_f32_e32 v110, 1.0, v110
	v_add_f32_e32 v111, 1.0, v111
	v_add_f32_e32 v112, 1.0, v112
	v_add_f32_e32 v113, 1.0, v113
	v_rcp_f32_e32 v20, v20
	v_rcp_f32_e32 v21, v21
	v_rcp_f32_e32 v22, v22
	v_rcp_f32_e32 v23, v23
	v_rcp_f32_e32 v110, v110
	v_rcp_f32_e32 v111, v111
	v_rcp_f32_e32 v112, v112
	v_rcp_f32_e32 v113, v113
	v_mul_f32_e32 v20, v147, v20
	v_mul_f32_e32 v21, v147, v21
	v_mul_f32_e32 v22, v147, v22
	v_mul_f32_e32 v23, v147, v23
	v_mul_f32_e32 v110, v110, v182
	v_mul_f32_e32 v111, v111, v183
	v_mul_f32_e32 v112, v112, v184
	v_mul_f32_e32 v113, v113, v185
; __device__ __forceinline__ float bf2f(u16 h) { return __uint_as_float(((unsigned)h) << 16); }
; __device__ __forceinline__ void lru_tile(const Params& P, int chunk, int head, int pass, char* smem_raw) {
;     ...
; #pragma unroll
;       for (int tc = 0; tc < 4; ++tc)
; #pragma unroll
;         for (int reg = 0; reg < 4; ++reg) {
;           const int tl = wid * 16 + (lane >> 4) * 4 + reg;
;           const int c = 16 * tc + (lane & 15);
;           const float r = __builtin_amdgcn_rcpf(1.f + __builtin_amdgcn_exp2f(acc[tc][reg] + ba[tc]));
;           const float ii = __builtin_amdgcn_rcpf(1.f + __builtin_amdgcn_exp2f(acc[tc + 4][reg] + bi[tc]));
;           const float la = -c8[tc] * r;
;           const float a = __builtin_amdgcn_exp2f(la);
;           const float ucv = bf2f(sm_uc[(sb * 64 + tl) * LDSS + c]);
;           const float bt = __builtin_amdgcn_sqrtf(fmaxf(1.f - a * a, 0.f)) * (ii * ucv);
;           sm_a[tl * 64 + c] = a;
;           sm_b[tl * 64 + c] = bt;
;         }
;     ...
;             const long rowp = row0 + sb * 64 + q * 16 + 15 - i;
;             hfp[i] = hfbuf[rowp * 512 + gch];
;             gp[i] = bf2f(P.zq[rowp * 1536 + 512 + gch]);
;           }
	v_exp_f32_e32 v20, v20
	v_exp_f32_e32 v21, v21
	v_exp_f32_e32 v22, v22
	v_exp_f32_e32 v23, v23
	s_nop 0
	v_fma_f32 v138, -v20, v20, 1.0
	v_fma_f32 v139, -v21, v21, 1.0
	v_fma_f32 v140, -v22, v22, 1.0
	v_fma_f32 v141, -v23, v23, 1.0
	v_max_f32_e32 v138, 0, v138
	v_max_f32_e32 v139, 0, v139
	v_max_f32_e32 v140, 0, v140
	v_max_f32_e32 v141, 0, v141
	v_sqrt_f32_e32 v138, v138
	v_sqrt_f32_e32 v139, v139
	v_sqrt_f32_e32 v140, v140
	v_sqrt_f32_e32 v141, v141
	s_nop 0
	v_mul_f32_e32 v110, v138, v110
	v_mul_f32_e32 v111, v139, v111
	v_mul_f32_e32 v112, v140, v112
	v_mul_f32_e32 v113, v141, v113
	v_add_f32_e32 v24, v24, v145
	v_add_f32_e32 v25, v25, v145
	v_add_f32_e32 v26, v26, v145
	v_add_f32_e32 v27, v27, v145
	v_add_f32_e32 v114, v114, v146
	v_add_f32_e32 v115, v115, v146
	v_add_f32_e32 v116, v116, v146
	v_add_f32_e32 v117, v117, v146
	v_exp_f32_e32 v24, v24
	v_exp_f32_e32 v25, v25
	v_exp_f32_e32 v26, v26
	v_exp_f32_e32 v27, v27
	v_exp_f32_e32 v114, v114
	v_exp_f32_e32 v115, v115
	v_exp_f32_e32 v116, v116
	v_exp_f32_e32 v117, v117
	v_add_f32_e32 v24, 1.0, v24
	v_add_f32_e32 v25, 1.0, v25
	v_add_f32_e32 v26, 1.0, v26
	v_add_f32_e32 v27, 1.0, v27
	v_add_f32_e32 v114, 1.0, v114
	v_add_f32_e32 v115, 1.0, v115
	v_add_f32_e32 v116, 1.0, v116
	v_add_f32_e32 v117, 1.0, v117
	v_rcp_f32_e32 v24, v24
	v_rcp_f32_e32 v25, v25
	v_rcp_f32_e32 v26, v26
	v_rcp_f32_e32 v27, v27
	v_rcp_f32_e32 v114, v114
	v_rcp_f32_e32 v115, v115
	v_rcp_f32_e32 v116, v116
	v_rcp_f32_e32 v117, v117
	v_mul_f32_e32 v24, v147, v24
	v_mul_f32_e32 v25, v147, v25
	v_mul_f32_e32 v26, v147, v26
	v_mul_f32_e32 v27, v147, v27
	v_mul_f32_e32 v114, v114, v186
	v_mul_f32_e32 v115, v115, v187
	v_mul_f32_e32 v116, v116, v188
	v_mul_f32_e32 v117, v117, v189
	v_exp_f32_e32 v24, v24
	v_exp_f32_e32 v25, v25
	v_exp_f32_e32 v26, v26
	v_exp_f32_e32 v27, v27
	s_nop 0
	v_fma_f32 v138, -v24, v24, 1.0
	v_fma_f32 v139, -v25, v25, 1.0
	v_fma_f32 v140, -v26, v26, 1.0
	v_fma_f32 v141, -v27, v27, 1.0
	v_max_f32_e32 v138, 0, v138
	v_max_f32_e32 v139, 0, v139
	v_max_f32_e32 v140, 0, v140
	v_max_f32_e32 v141, 0, v141
	v_sqrt_f32_e32 v138, v138
	v_sqrt_f32_e32 v139, v139
	v_sqrt_f32_e32 v140, v140
	v_sqrt_f32_e32 v141, v141
	s_nop 0
	v_mul_f32_e32 v114, v138, v114
	v_mul_f32_e32 v115, v139, v115
	v_mul_f32_e32 v116, v140, v116
	v_mul_f32_e32 v117, v141, v117
	v_add_f32_e32 v28, v28, v145
	v_add_f32_e32 v29, v29, v145
	v_add_f32_e32 v30, v30, v145
	v_add_f32_e32 v31, v31, v145
	v_add_f32_e32 v118, v118, v146
	v_add_f32_e32 v119, v119, v146
	v_add_f32_e32 v120, v120, v146
	v_add_f32_e32 v121, v121, v146
	v_exp_f32_e32 v28, v28
	v_exp_f32_e32 v29, v29
	v_exp_f32_e32 v30, v30
	v_exp_f32_e32 v31, v31
	v_exp_f32_e32 v118, v118
	v_exp_f32_e32 v119, v119
	v_exp_f32_e32 v120, v120
	v_exp_f32_e32 v121, v121
	v_add_f32_e32 v28, 1.0, v28
	v_add_f32_e32 v29, 1.0, v29
	v_add_f32_e32 v30, 1.0, v30
	v_add_f32_e32 v31, 1.0, v31
	v_add_f32_e32 v118, 1.0, v118
	v_add_f32_e32 v119, 1.0, v119
	v_add_f32_e32 v120, 1.0, v120
	v_add_f32_e32 v121, 1.0, v121
	v_rcp_f32_e32 v28, v28
	v_rcp_f32_e32 v29, v29
	v_rcp_f32_e32 v30, v30
	v_rcp_f32_e32 v31, v31
	v_rcp_f32_e32 v118, v118
	v_rcp_f32_e32 v119, v119
	v_rcp_f32_e32 v120, v120
	v_rcp_f32_e32 v121, v121
	v_mul_f32_e32 v28, v147, v28
	v_mul_f32_e32 v29, v147, v29
	v_mul_f32_e32 v30, v147, v30
	v_mul_f32_e32 v31, v147, v31
	v_mul_f32_e32 v118, v118, v190
	v_mul_f32_e32 v119, v119, v191
	v_mul_f32_e32 v120, v120, v192
	v_mul_f32_e32 v121, v121, v193
	v_exp_f32_e32 v28, v28
	v_exp_f32_e32 v29, v29
	v_exp_f32_e32 v30, v30
	v_exp_f32_e32 v31, v31
	s_nop 0
	v_fma_f32 v138, -v28, v28, 1.0
	v_fma_f32 v139, -v29, v29, 1.0
	v_fma_f32 v140, -v30, v30, 1.0
	v_fma_f32 v141, -v31, v31, 1.0
	v_max_f32_e32 v138, 0, v138
	v_max_f32_e32 v139, 0, v139
	v_max_f32_e32 v140, 0, v140
	v_max_f32_e32 v141, 0, v141
	v_sqrt_f32_e32 v138, v138
	v_sqrt_f32_e32 v139, v139
	v_sqrt_f32_e32 v140, v140
	v_sqrt_f32_e32 v141, v141
	s_nop 0
	v_mul_f32_e32 v118, v138, v118
	v_mul_f32_e32 v119, v139, v119
	v_mul_f32_e32 v120, v140, v120
	v_mul_f32_e32 v121, v141, v121
	s_mul_i32 s0, s71, 0x60000
	s_lshl_b32 s1, s56, 1
	s_add_u32 s0, s0, s1
	s_add_u32 s0, s0, 0x400
	s_add_u32 s4, s10, s0
	s_addc_u32 s5, s11, 0
	global_load_ushort v162, v134, s[4:5]
	s_add_u32 s4, s4, 0xc00
	s_addc_u32 s5, s5, 0
	global_load_ushort v163, v134, s[4:5]
	s_add_u32 s4, s4, 0xc00
	s_addc_u32 s5, s5, 0
	global_load_ushort v164, v134, s[4:5]
	s_add_u32 s4, s4, 0xc00
	s_addc_u32 s5, s5, 0
	global_load_ushort v165, v134, s[4:5]
	s_add_u32 s4, s4, 0xc00
	s_addc_u32 s5, s5, 0
	global_load_ushort v166, v134, s[4:5]
	s_add_u32 s4, s4, 0xc00
	s_addc_u32 s5, s5, 0
	global_load_ushort v167, v134, s[4:5]
	s_add_u32 s4, s4, 0xc00
	s_addc_u32 s5, s5, 0
	global_load_ushort v168, v134, s[4:5]
	s_add_u32 s4, s4, 0xc00
	s_addc_u32 s5, s5, 0
	global_load_ushort v169, v134, s[4:5]
	s_add_u32 s4, s4, 0xc00
	s_addc_u32 s5, s5, 0
	global_load_ushort v170, v134, s[4:5]
	s_add_u32 s4, s4, 0xc00
	s_addc_u32 s5, s5, 0
	global_load_ushort v171, v134, s[4:5]
	s_add_u32 s4, s4, 0xc00
	s_addc_u32 s5, s5, 0
	global_load_ushort v172, v134, s[4:5]
	s_add_u32 s4, s4, 0xc00
	s_addc_u32 s5, s5, 0
	global_load_ushort v173, v134, s[4:5]
	s_add_u32 s4, s4, 0xc00
	s_addc_u32 s5, s5, 0
	global_load_ushort v174, v134, s[4:5]
	s_add_u32 s4, s4, 0xc00
	s_addc_u32 s5, s5, 0
	global_load_ushort v175, v134, s[4:5]
	s_add_u32 s4, s4, 0xc00
	s_addc_u32 s5, s5, 0
	global_load_ushort v176, v134, s[4:5]
	s_add_u32 s4, s4, 0xc00
	s_addc_u32 s5, s5, 0
	global_load_ushort v177, v134, s[4:5]
	s_add_u32 s4, s4, 0xc00
	s_addc_u32 s5, s5, 0
	global_load_ushort v178, v134, s[4:5]
	s_add_u32 s4, s4, 0xc00
; __device__ __forceinline__ float bf2f(u16 h) { return __uint_as_float(((unsigned)h) << 16); }
; __device__ __forceinline__ void lru_tile(const Params& P, int chunk, int head, int pass, char* smem_raw) {
;     ...
;       const int pos = (d == 0) ? q : 3 - q;
;       {
;         float Pp = 1.f, H = 0.f;
; #pragma unroll 4
;         for (int i = 0; i < 16; ++i) {
;           const int tl = (d == 0) ? (q * 16 + i) : (q * 16 + 15 - i);
;           const float a = sm_a[tl * 64 + ch], b = sm_b[tl * 64 + ch];
;           H = a * H + b; Pp *= a;
;         }
;         sm_ph[pos * 64 + ch] = make_float2(Pp, H);
;       }
;       __syncthreads();
;       const float2 p0 = sm_ph[ch], p1 = sm_ph[64 + ch], p2 = sm_ph[128 + ch], p3 = sm_ph[192 + ch];
;       if (pass == 2) {
;         float hin = cB;
;         if (pos > 0) hin = p0.x * hin + p0.y;
;         if (pos > 1) hin = p1.x * hin + p1.y;
;         if (pos > 2) hin = p2.x * hin + p2.y;
;         float h = hin;
;         float hfp[16], gp[16];
;         if (d == 1) {
; #pragma unroll
;           for (int i = 0; i < 16; ++i) {
;             const long rowp = row0 + sb * 64 + q * 16 + 15 - i;
;             hfp[i] = hfbuf[rowp * 512 + gch];
;             gp[i] = bf2f(P.zq[rowp * 1536 + 512 + gch]);
;           }
;         }
; #pragma unroll
;         for (int i = 0; i < 16; ++i) {
;           const int tl = (d == 0) ? (q * 16 + i) : (q * 16 + 15 - i);
;           const float a = sm_a[tl * 64 + ch], b = sm_b[tl * 64 + ch];
;           h = a * h + b;
	s_addc_u32 s5, s5, 0
	global_load_ushort v179, v134, s[4:5]
	s_add_u32 s4, s4, 0xc00
	s_addc_u32 s5, s5, 0
	global_load_ushort v180, v134, s[4:5]
	s_add_u32 s4, s4, 0xc00
	s_addc_u32 s5, s5, 0
	global_load_ushort v181, v134, s[4:5]
	s_add_u32 s4, s4, 0xc00
	s_addc_u32 s5, s5, 0
	global_load_ushort v182, v134, s[4:5]
	s_add_u32 s4, s4, 0xc00
	s_addc_u32 s5, s5, 0
	global_load_ushort v183, v134, s[4:5]
	s_add_u32 s4, s4, 0xc00
	s_addc_u32 s5, s5, 0
	global_load_ushort v184, v134, s[4:5]
	s_add_u32 s4, s4, 0xc00
	s_addc_u32 s5, s5, 0
	global_load_ushort v185, v134, s[4:5]
	s_add_u32 s4, s4, 0xc00
	s_addc_u32 s5, s5, 0
	global_load_ushort v186, v134, s[4:5]
	s_add_u32 s4, s4, 0xc00
	s_addc_u32 s5, s5, 0
	global_load_ushort v187, v134, s[4:5]
	s_add_u32 s4, s4, 0xc00
	s_addc_u32 s5, s5, 0
	global_load_ushort v188, v134, s[4:5]
	s_add_u32 s4, s4, 0xc00
	s_addc_u32 s5, s5, 0
	global_load_ushort v189, v134, s[4:5]
	s_add_u32 s4, s4, 0xc00
	s_addc_u32 s5, s5, 0
	global_load_ushort v190, v134, s[4:5]
	s_add_u32 s4, s4, 0xc00
	s_addc_u32 s5, s5, 0
	global_load_ushort v191, v134, s[4:5]
	s_add_u32 s4, s4, 0xc00
	s_addc_u32 s5, s5, 0
	global_load_ushort v192, v134, s[4:5]
	s_add_u32 s4, s4, 0xc00
	s_addc_u32 s5, s5, 0
	global_load_ushort v193, v134, s[4:5]
	v_mov_b32_e32 v253, v31
	v_mov_b32_e32 v254, v121
	v_fma_f32 v254, v30, v254, v120
	v_mul_f32_e32 v253, v253, v30
	v_fma_f32 v254, v29, v254, v119
	v_mul_f32_e32 v253, v253, v29
	v_fma_f32 v254, v28, v254, v118
	v_mul_f32_e32 v253, v253, v28
	v_fma_f32 v254, v27, v254, v117
	v_mul_f32_e32 v253, v253, v27
	v_fma_f32 v254, v26, v254, v116
	v_mul_f32_e32 v253, v253, v26
	v_fma_f32 v254, v25, v254, v115
	v_mul_f32_e32 v253, v253, v25
	v_fma_f32 v254, v24, v254, v114
	v_mul_f32_e32 v253, v253, v24
	v_fma_f32 v254, v23, v254, v113
	v_mul_f32_e32 v253, v253, v23
	v_fma_f32 v254, v22, v254, v112
	v_mul_f32_e32 v253, v253, v22
	v_fma_f32 v254, v21, v254, v111
	v_mul_f32_e32 v253, v253, v21
	v_fma_f32 v254, v20, v254, v110
	v_mul_f32_e32 v253, v253, v20
	v_fma_f32 v254, v19, v254, v109
	v_mul_f32_e32 v253, v253, v19
	v_fma_f32 v254, v18, v254, v108
	v_mul_f32_e32 v253, v253, v18
	v_fma_f32 v254, v17, v254, v107
	v_mul_f32_e32 v253, v253, v17
	v_fma_f32 v254, v16, v254, v106
	v_mul_f32_e32 v253, v253, v16
	v_fma_f32 v254, v15, v254, v105
	v_mul_f32_e32 v253, v253, v15
	v_fma_f32 v254, v14, v254, v104
	v_mul_f32_e32 v253, v253, v14
	v_fma_f32 v254, v13, v254, v103
	v_mul_f32_e32 v253, v253, v13
	v_fma_f32 v254, v12, v254, v102
	v_mul_f32_e32 v253, v253, v12
	v_fma_f32 v254, v11, v254, v101
	v_mul_f32_e32 v253, v253, v11
	v_fma_f32 v254, v10, v254, v100
	v_mul_f32_e32 v253, v253, v10
	v_fma_f32 v254, v9, v254, v99
	v_mul_f32_e32 v253, v253, v9
	v_fma_f32 v254, v8, v254, v98
	v_mul_f32_e32 v253, v253, v8
	v_fma_f32 v254, v7, v254, v97
	v_mul_f32_e32 v253, v253, v7
	v_fma_f32 v254, v6, v254, v96
	v_mul_f32_e32 v253, v253, v6
	v_fma_f32 v254, v5, v254, v95
	v_mul_f32_e32 v253, v253, v5
	v_fma_f32 v254, v4, v254, v94
	v_mul_f32_e32 v253, v253, v4
	v_fma_f32 v254, v3, v254, v93
	v_mul_f32_e32 v253, v253, v3
	v_fma_f32 v254, v2, v254, v92
	v_mul_f32_e32 v253, v253, v2
	v_fma_f32 v254, v1, v254, v91
	v_mul_f32_e32 v253, v253, v1
	v_fma_f32 v254, v0, v254, v90
	v_mul_f32_e32 v253, v253, v0
	v_mov_b32_e32 v138, v253
	v_mov_b32_e32 v139, v253
	s_nop 1
	v_permlane16_swap_b32_e32 v138, v139
	v_mov_b32_e32 v140, v138
	v_mov_b32_e32 v141, v139
	s_nop 1
	v_permlane32_swap_b32_e32 v138, v140
	v_permlane32_swap_b32_e32 v139, v141
	v_mov_b32_e32 v198, v254
	v_mov_b32_e32 v199, v254
	s_nop 1
	v_permlane16_swap_b32_e32 v198, v199
	v_mov_b32_e32 v200, v198
	v_mov_b32_e32 v201, v199
	s_nop 1
	v_permlane32_swap_b32_e32 v198, v200
	v_permlane32_swap_b32_e32 v199, v201
	v_mov_b32_e32 v202, v149
	v_fma_f32 v151, v141, v202, v201
	v_fma_f32 v150, v140, v151, v200
	v_fma_f32 v136, v139, v150, v199
	v_mov_b32_e32 v254, v202
	v_cndmask_b32_e64 v254, v254, v151, s[78:79]
	v_cndmask_b32_e64 v254, v254, v150, s[80:81]
	v_cndmask_b32_e64 v254, v254, v136, s[82:83]
	v_fma_f32 v121, v31, v254, v121
	v_fma_f32 v120, v30, v121, v120
	v_fma_f32 v119, v29, v120, v119
	v_fma_f32 v118, v28, v119, v118
	v_fma_f32 v117, v27, v118, v117
	v_fma_f32 v116, v26, v117, v116
	v_fma_f32 v115, v25, v116, v115
	v_fma_f32 v114, v24, v115, v114
	v_fma_f32 v113, v23, v114, v113
	v_fma_f32 v112, v22, v113, v112
	v_fma_f32 v111, v21, v112, v111
	v_fma_f32 v110, v20, v111, v110
	v_fma_f32 v109, v19, v110, v109
	v_fma_f32 v108, v18, v109, v108
	v_fma_f32 v107, v17, v108, v107
	v_fma_f32 v106, v16, v107, v106
	v_fma_f32 v105, v15, v106, v105
	v_fma_f32 v104, v14, v105, v104
	v_fma_f32 v103, v13, v104, v103
	v_fma_f32 v102, v12, v103, v102
	v_fma_f32 v101, v11, v102, v101
	v_fma_f32 v100, v10, v101, v100
	v_fma_f32 v99, v9, v100, v99
	v_fma_f32 v98, v8, v99, v98
	v_fma_f32 v97, v7, v98, v97
	v_fma_f32 v96, v6, v97, v96
	v_fma_f32 v95, v5, v96, v95
	v_fma_f32 v94, v4, v95, v94
	v_fma_f32 v93, v3, v94, v93
	v_fma_f32 v92, v2, v93, v92
	v_fma_f32 v91, v1, v92, v91
	v_fma_f32 v90, v0, v91, v90
	s_waitcnt vmcnt(0)
; __device__ __forceinline__ void lru_tile(const Params& P, int chunk, int head, int pass, char* smem_raw) {
;     ...
;           } else {
;             const float hfv = hfp[i];
;             const float g = gp[i];
;             const float tz = 0.7978845608028654f * (g + 0.044715f * g * g * g);
;             const float th = 1.f - 2.f * __builtin_amdgcn_rcpf(1.f + __expf(2.f * tz));
;             const float ge = 0.5f * g * (1.f + th);
;             P.cat[row * 1024 + gch] = f2bf((hfv + h) * ge);
	v_lshlrev_b32_e32 v162, 16, v162
	v_lshlrev_b32_e32 v163, 16, v163
	v_lshlrev_b32_e32 v164, 16, v164
	v_lshlrev_b32_e32 v165, 16, v165
	v_lshlrev_b32_e32 v166, 16, v166
	v_lshlrev_b32_e32 v167, 16, v167
	v_lshlrev_b32_e32 v168, 16, v168
	v_lshlrev_b32_e32 v169, 16, v169
	v_lshlrev_b32_e32 v170, 16, v170
	v_lshlrev_b32_e32 v171, 16, v171
	v_lshlrev_b32_e32 v172, 16, v172
	v_lshlrev_b32_e32 v173, 16, v173
	v_lshlrev_b32_e32 v174, 16, v174
	v_lshlrev_b32_e32 v175, 16, v175
	v_lshlrev_b32_e32 v176, 16, v176
	v_lshlrev_b32_e32 v177, 16, v177
	v_lshlrev_b32_e32 v178, 16, v178
	v_lshlrev_b32_e32 v179, 16, v179
	v_lshlrev_b32_e32 v180, 16, v180
	v_lshlrev_b32_e32 v181, 16, v181
	v_lshlrev_b32_e32 v182, 16, v182
	v_lshlrev_b32_e32 v183, 16, v183
	v_lshlrev_b32_e32 v184, 16, v184
	v_lshlrev_b32_e32 v185, 16, v185
	v_lshlrev_b32_e32 v186, 16, v186
	v_lshlrev_b32_e32 v187, 16, v187
	v_lshlrev_b32_e32 v188, 16, v188
	v_lshlrev_b32_e32 v189, 16, v189
	v_lshlrev_b32_e32 v190, 16, v190
	v_lshlrev_b32_e32 v191, 16, v191
	v_lshlrev_b32_e32 v192, 16, v192
	v_lshlrev_b32_e32 v193, 16, v193
	v_mov_b32_e32 v202, 0x3d372713
	v_mul_f32_e32 v138, v162, v162
	v_mul_f32_e32 v139, v163, v163
	v_mul_f32_e32 v140, v164, v164
	v_mul_f32_e32 v141, v165, v165
	v_mul_f32_e32 v138, v138, v162
	v_mul_f32_e32 v139, v139, v163
	v_mul_f32_e32 v140, v140, v164
	v_mul_f32_e32 v141, v141, v165
	v_fma_f32 v138, v202, v138, v162
	v_fma_f32 v139, v202, v139, v163
	v_fma_f32 v140, v202, v140, v164
	v_fma_f32 v141, v202, v141, v165
	v_mul_f32_e32 v138, 0x40135761, v138
	v_mul_f32_e32 v139, 0x40135761, v139
	v_mul_f32_e32 v140, 0x40135761, v140
	v_mul_f32_e32 v141, 0x40135761, v141
	v_exp_f32_e32 v138, v138
	v_exp_f32_e32 v139, v139
	v_exp_f32_e32 v140, v140
	v_exp_f32_e32 v141, v141
	s_nop 0
	v_add_f32_e32 v138, 1.0, v138
	v_add_f32_e32 v139, 1.0, v139
	v_add_f32_e32 v140, 1.0, v140
	v_add_f32_e32 v141, 1.0, v141
	v_rcp_f32_e32 v138, v138
	v_rcp_f32_e32 v139, v139
	v_rcp_f32_e32 v140, v140
	v_rcp_f32_e32 v141, v141
	s_nop 0
	v_fma_f32 v138, -2.0, v138, 1.0
	v_fma_f32 v139, -2.0, v139, 1.0
	v_fma_f32 v140, -2.0, v140, 1.0
	v_fma_f32 v141, -2.0, v141, 1.0
	v_add_f32_e32 v138, 1.0, v138
	v_add_f32_e32 v139, 1.0, v139
	v_add_f32_e32 v140, 1.0, v140
	v_add_f32_e32 v141, 1.0, v141
	v_mul_f32_e32 v162, 0.5, v162
	v_mul_f32_e32 v163, 0.5, v163
	v_mul_f32_e32 v164, 0.5, v164
	v_mul_f32_e32 v165, 0.5, v165
	v_mul_f32_e32 v162, v162, v138
	v_mul_f32_e32 v163, v163, v139
	v_mul_f32_e32 v164, v164, v140
	v_mul_f32_e32 v165, v165, v141
	v_add_f32_e32 v90, v205, v90
	v_add_f32_e32 v91, v206, v91
	v_add_f32_e32 v92, v207, v92
	v_add_f32_e32 v93, v208, v93
	v_mul_f32_e32 v90, v90, v162
	v_mul_f32_e32 v91, v91, v163
	v_mul_f32_e32 v92, v92, v164
	v_mul_f32_e32 v93, v93, v165
	v_cvt_pk_bf16_f32 v90, v90, v90
	v_cvt_pk_bf16_f32 v91, v91, v91
	v_cvt_pk_bf16_f32 v92, v92, v92
	v_cvt_pk_bf16_f32 v93, v93, v93
	v_mul_f32_e32 v138, v166, v166
	v_mul_f32_e32 v139, v167, v167
	v_mul_f32_e32 v140, v168, v168
	v_mul_f32_e32 v141, v169, v169
	v_mul_f32_e32 v138, v138, v166
	v_mul_f32_e32 v139, v139, v167
	v_mul_f32_e32 v140, v140, v168
	v_mul_f32_e32 v141, v141, v169
	v_fma_f32 v138, v202, v138, v166
	v_fma_f32 v139, v202, v139, v167
	v_fma_f32 v140, v202, v140, v168
	v_fma_f32 v141, v202, v141, v169
	v_mul_f32_e32 v138, 0x40135761, v138
	v_mul_f32_e32 v139, 0x40135761, v139
	v_mul_f32_e32 v140, 0x40135761, v140
	v_mul_f32_e32 v141, 0x40135761, v141
	v_exp_f32_e32 v138, v138
	v_exp_f32_e32 v139, v139
	v_exp_f32_e32 v140, v140
	v_exp_f32_e32 v141, v141
	s_nop 0
	v_add_f32_e32 v138, 1.0, v138
	v_add_f32_e32 v139, 1.0, v139
	v_add_f32_e32 v140, 1.0, v140
	v_add_f32_e32 v141, 1.0, v141
	v_rcp_f32_e32 v138, v138
	v_rcp_f32_e32 v139, v139
	v_rcp_f32_e32 v140, v140
	v_rcp_f32_e32 v141, v141
	s_nop 0
	v_fma_f32 v138, -2.0, v138, 1.0
	v_fma_f32 v139, -2.0, v139, 1.0
	v_fma_f32 v140, -2.0, v140, 1.0
	v_fma_f32 v141, -2.0, v141, 1.0
	v_add_f32_e32 v138, 1.0, v138
	v_add_f32_e32 v139, 1.0, v139
	v_add_f32_e32 v140, 1.0, v140
	v_add_f32_e32 v141, 1.0, v141
	v_mul_f32_e32 v166, 0.5, v166
	v_mul_f32_e32 v167, 0.5, v167
	v_mul_f32_e32 v168, 0.5, v168
	v_mul_f32_e32 v169, 0.5, v169
	v_mul_f32_e32 v166, v166, v138
	v_mul_f32_e32 v167, v167, v139
	v_mul_f32_e32 v168, v168, v140
	v_mul_f32_e32 v169, v169, v141
	v_add_f32_e32 v94, v209, v94
	v_add_f32_e32 v95, v210, v95
	v_add_f32_e32 v96, v211, v96
	v_add_f32_e32 v97, v212, v97
	v_mul_f32_e32 v94, v94, v166
	v_mul_f32_e32 v95, v95, v167
	v_mul_f32_e32 v96, v96, v168
	v_mul_f32_e32 v97, v97, v169
	v_cvt_pk_bf16_f32 v94, v94, v94
	v_cvt_pk_bf16_f32 v95, v95, v95
	v_cvt_pk_bf16_f32 v96, v96, v96
	v_cvt_pk_bf16_f32 v97, v97, v97
	v_mul_f32_e32 v138, v170, v170
	v_mul_f32_e32 v139, v171, v171
	v_mul_f32_e32 v140, v172, v172
	v_mul_f32_e32 v141, v173, v173
	v_mul_f32_e32 v138, v138, v170
	v_mul_f32_e32 v139, v139, v171
	v_mul_f32_e32 v140, v140, v172
	v_mul_f32_e32 v141, v141, v173
	v_fma_f32 v138, v202, v138, v170
	v_fma_f32 v139, v202, v139, v171
	v_fma_f32 v140, v202, v140, v172
	v_fma_f32 v141, v202, v141, v173
	v_mul_f32_e32 v138, 0x40135761, v138
	v_mul_f32_e32 v139, 0x40135761, v139
	v_mul_f32_e32 v140, 0x40135761, v140
	v_mul_f32_e32 v141, 0x40135761, v141
	v_exp_f32_e32 v138, v138
	v_exp_f32_e32 v139, v139
	v_exp_f32_e32 v140, v140
	v_exp_f32_e32 v141, v141
	s_nop 0
	v_add_f32_e32 v138, 1.0, v138
	v_add_f32_e32 v139, 1.0, v139
	v_add_f32_e32 v140, 1.0, v140
	v_add_f32_e32 v141, 1.0, v141
	v_rcp_f32_e32 v138, v138
	v_rcp_f32_e32 v139, v139
	v_rcp_f32_e32 v140, v140
	v_rcp_f32_e32 v141, v141
	s_nop 0
	v_fma_f32 v138, -2.0, v138, 1.0
	v_fma_f32 v139, -2.0, v139, 1.0
; __device__ __forceinline__ void lru_tile(const Params& P, int chunk, int head, int pass, char* smem_raw) {
;     ...
;           } else {
;             const float hfv = hfp[i];
;             const float g = gp[i];
;             const float tz = 0.7978845608028654f * (g + 0.044715f * g * g * g);
;             const float th = 1.f - 2.f * __builtin_amdgcn_rcpf(1.f + __expf(2.f * tz));
;             const float ge = 0.5f * g * (1.f + th);
;             P.cat[row * 1024 + gch] = f2bf((hfv + h) * ge);
	v_fma_f32 v140, -2.0, v140, 1.0
	v_fma_f32 v141, -2.0, v141, 1.0
	v_add_f32_e32 v138, 1.0, v138
	v_add_f32_e32 v139, 1.0, v139
	v_add_f32_e32 v140, 1.0, v140
	v_add_f32_e32 v141, 1.0, v141
	v_mul_f32_e32 v170, 0.5, v170
	v_mul_f32_e32 v171, 0.5, v171
	v_mul_f32_e32 v172, 0.5, v172
	v_mul_f32_e32 v173, 0.5, v173
	v_mul_f32_e32 v170, v170, v138
	v_mul_f32_e32 v171, v171, v139
	v_mul_f32_e32 v172, v172, v140
	v_mul_f32_e32 v173, v173, v141
	v_add_f32_e32 v98, v213, v98
	v_add_f32_e32 v99, v214, v99
	v_add_f32_e32 v100, v215, v100
	v_add_f32_e32 v101, v216, v101
	v_mul_f32_e32 v98, v98, v170
	v_mul_f32_e32 v99, v99, v171
	v_mul_f32_e32 v100, v100, v172
	v_mul_f32_e32 v101, v101, v173
	v_cvt_pk_bf16_f32 v98, v98, v98
	v_cvt_pk_bf16_f32 v99, v99, v99
	v_cvt_pk_bf16_f32 v100, v100, v100
	v_cvt_pk_bf16_f32 v101, v101, v101
	v_mul_f32_e32 v138, v174, v174
	v_mul_f32_e32 v139, v175, v175
	v_mul_f32_e32 v140, v176, v176
	v_mul_f32_e32 v141, v177, v177
	v_mul_f32_e32 v138, v138, v174
	v_mul_f32_e32 v139, v139, v175
	v_mul_f32_e32 v140, v140, v176
	v_mul_f32_e32 v141, v141, v177
	v_fma_f32 v138, v202, v138, v174
	v_fma_f32 v139, v202, v139, v175
	v_fma_f32 v140, v202, v140, v176
	v_fma_f32 v141, v202, v141, v177
	v_mul_f32_e32 v138, 0x40135761, v138
	v_mul_f32_e32 v139, 0x40135761, v139
	v_mul_f32_e32 v140, 0x40135761, v140
	v_mul_f32_e32 v141, 0x40135761, v141
	v_exp_f32_e32 v138, v138
	v_exp_f32_e32 v139, v139
	v_exp_f32_e32 v140, v140
	v_exp_f32_e32 v141, v141
	s_nop 0
	v_add_f32_e32 v138, 1.0, v138
	v_add_f32_e32 v139, 1.0, v139
	v_add_f32_e32 v140, 1.0, v140
	v_add_f32_e32 v141, 1.0, v141
	v_rcp_f32_e32 v138, v138
	v_rcp_f32_e32 v139, v139
	v_rcp_f32_e32 v140, v140
	v_rcp_f32_e32 v141, v141
	s_nop 0
	v_fma_f32 v138, -2.0, v138, 1.0
	v_fma_f32 v139, -2.0, v139, 1.0
	v_fma_f32 v140, -2.0, v140, 1.0
	v_fma_f32 v141, -2.0, v141, 1.0
	v_add_f32_e32 v138, 1.0, v138
	v_add_f32_e32 v139, 1.0, v139
	v_add_f32_e32 v140, 1.0, v140
	v_add_f32_e32 v141, 1.0, v141
	v_mul_f32_e32 v174, 0.5, v174
	v_mul_f32_e32 v175, 0.5, v175
	v_mul_f32_e32 v176, 0.5, v176
	v_mul_f32_e32 v177, 0.5, v177
	v_mul_f32_e32 v174, v174, v138
	v_mul_f32_e32 v175, v175, v139
	v_mul_f32_e32 v176, v176, v140
	v_mul_f32_e32 v177, v177, v141
	v_add_f32_e32 v102, v217, v102
	v_add_f32_e32 v103, v218, v103
	v_add_f32_e32 v104, v219, v104
	v_add_f32_e32 v105, v220, v105
	v_mul_f32_e32 v102, v102, v174
	v_mul_f32_e32 v103, v103, v175
	v_mul_f32_e32 v104, v104, v176
	v_mul_f32_e32 v105, v105, v177
	v_cvt_pk_bf16_f32 v102, v102, v102
	v_cvt_pk_bf16_f32 v103, v103, v103
	v_cvt_pk_bf16_f32 v104, v104, v104
	v_cvt_pk_bf16_f32 v105, v105, v105
	v_mul_f32_e32 v138, v178, v178
	v_mul_f32_e32 v139, v179, v179
	v_mul_f32_e32 v140, v180, v180
	v_mul_f32_e32 v141, v181, v181
	v_mul_f32_e32 v138, v138, v178
	v_mul_f32_e32 v139, v139, v179
	v_mul_f32_e32 v140, v140, v180
	v_mul_f32_e32 v141, v141, v181
	v_fma_f32 v138, v202, v138, v178
	v_fma_f32 v139, v202, v139, v179
	v_fma_f32 v140, v202, v140, v180
	v_fma_f32 v141, v202, v141, v181
	v_mul_f32_e32 v138, 0x40135761, v138
	v_mul_f32_e32 v139, 0x40135761, v139
	v_mul_f32_e32 v140, 0x40135761, v140
	v_mul_f32_e32 v141, 0x40135761, v141
	v_exp_f32_e32 v138, v138
	v_exp_f32_e32 v139, v139
	v_exp_f32_e32 v140, v140
	v_exp_f32_e32 v141, v141
	s_nop 0
	v_add_f32_e32 v138, 1.0, v138
	v_add_f32_e32 v139, 1.0, v139
	v_add_f32_e32 v140, 1.0, v140
	v_add_f32_e32 v141, 1.0, v141
	v_rcp_f32_e32 v138, v138
	v_rcp_f32_e32 v139, v139
	v_rcp_f32_e32 v140, v140
	v_rcp_f32_e32 v141, v141
	s_nop 0
	v_fma_f32 v138, -2.0, v138, 1.0
	v_fma_f32 v139, -2.0, v139, 1.0
	v_fma_f32 v140, -2.0, v140, 1.0
	v_fma_f32 v141, -2.0, v141, 1.0
	v_add_f32_e32 v138, 1.0, v138
	v_add_f32_e32 v139, 1.0, v139
	v_add_f32_e32 v140, 1.0, v140
	v_add_f32_e32 v141, 1.0, v141
	v_mul_f32_e32 v178, 0.5, v178
	v_mul_f32_e32 v179, 0.5, v179
	v_mul_f32_e32 v180, 0.5, v180
	v_mul_f32_e32 v181, 0.5, v181
	v_mul_f32_e32 v178, v178, v138
	v_mul_f32_e32 v179, v179, v139
	v_mul_f32_e32 v180, v180, v140
	v_mul_f32_e32 v181, v181, v141
	v_add_f32_e32 v106, v221, v106
	v_add_f32_e32 v107, v222, v107
	v_add_f32_e32 v108, v223, v108
	v_add_f32_e32 v109, v224, v109
	v_mul_f32_e32 v106, v106, v178
	v_mul_f32_e32 v107, v107, v179
	v_mul_f32_e32 v108, v108, v180
	v_mul_f32_e32 v109, v109, v181
	v_cvt_pk_bf16_f32 v106, v106, v106
	v_cvt_pk_bf16_f32 v107, v107, v107
	v_cvt_pk_bf16_f32 v108, v108, v108
	v_cvt_pk_bf16_f32 v109, v109, v109
	v_mul_f32_e32 v138, v182, v182
	v_mul_f32_e32 v139, v183, v183
	v_mul_f32_e32 v140, v184, v184
	v_mul_f32_e32 v141, v185, v185
	v_mul_f32_e32 v138, v138, v182
	v_mul_f32_e32 v139, v139, v183
	v_mul_f32_e32 v140, v140, v184
	v_mul_f32_e32 v141, v141, v185
	v_fma_f32 v138, v202, v138, v182
	v_fma_f32 v139, v202, v139, v183
	v_fma_f32 v140, v202, v140, v184
	v_fma_f32 v141, v202, v141, v185
	v_mul_f32_e32 v138, 0x40135761, v138
	v_mul_f32_e32 v139, 0x40135761, v139
	v_mul_f32_e32 v140, 0x40135761, v140
	v_mul_f32_e32 v141, 0x40135761, v141
	v_exp_f32_e32 v138, v138
	v_exp_f32_e32 v139, v139
	v_exp_f32_e32 v140, v140
	v_exp_f32_e32 v141, v141
	s_nop 0
	v_add_f32_e32 v138, 1.0, v138
	v_add_f32_e32 v139, 1.0, v139
	v_add_f32_e32 v140, 1.0, v140
	v_add_f32_e32 v141, 1.0, v141
	v_rcp_f32_e32 v138, v138
	v_rcp_f32_e32 v139, v139
	v_rcp_f32_e32 v140, v140
	v_rcp_f32_e32 v141, v141
	s_nop 0
	v_fma_f32 v138, -2.0, v138, 1.0
	v_fma_f32 v139, -2.0, v139, 1.0
	v_fma_f32 v140, -2.0, v140, 1.0
	v_fma_f32 v141, -2.0, v141, 1.0
	v_add_f32_e32 v138, 1.0, v138
	v_add_f32_e32 v139, 1.0, v139
	v_add_f32_e32 v140, 1.0, v140
	v_add_f32_e32 v141, 1.0, v141
	v_mul_f32_e32 v182, 0.5, v182
	v_mul_f32_e32 v183, 0.5, v183
; __device__ __forceinline__ void lru_tile(const Params& P, int chunk, int head, int pass, char* smem_raw) {
;     ...
;           } else {
;             const float hfv = hfp[i];
;             const float g = gp[i];
;             const float tz = 0.7978845608028654f * (g + 0.044715f * g * g * g);
;             const float th = 1.f - 2.f * __builtin_amdgcn_rcpf(1.f + __expf(2.f * tz));
;             const float ge = 0.5f * g * (1.f + th);
;             P.cat[row * 1024 + gch] = f2bf((hfv + h) * ge);
	v_mul_f32_e32 v184, 0.5, v184
	v_mul_f32_e32 v185, 0.5, v185
	v_mul_f32_e32 v182, v182, v138
	v_mul_f32_e32 v183, v183, v139
	v_mul_f32_e32 v184, v184, v140
	v_mul_f32_e32 v185, v185, v141
	v_add_f32_e32 v110, v225, v110
	v_add_f32_e32 v111, v226, v111
	v_add_f32_e32 v112, v227, v112
	v_add_f32_e32 v113, v228, v113
	v_mul_f32_e32 v110, v110, v182
	v_mul_f32_e32 v111, v111, v183
	v_mul_f32_e32 v112, v112, v184
	v_mul_f32_e32 v113, v113, v185
	v_cvt_pk_bf16_f32 v110, v110, v110
	v_cvt_pk_bf16_f32 v111, v111, v111
	v_cvt_pk_bf16_f32 v112, v112, v112
	v_cvt_pk_bf16_f32 v113, v113, v113
	v_mul_f32_e32 v138, v186, v186
	v_mul_f32_e32 v139, v187, v187
	v_mul_f32_e32 v140, v188, v188
	v_mul_f32_e32 v141, v189, v189
	v_mul_f32_e32 v138, v138, v186
	v_mul_f32_e32 v139, v139, v187
	v_mul_f32_e32 v140, v140, v188
	v_mul_f32_e32 v141, v141, v189
	v_fma_f32 v138, v202, v138, v186
	v_fma_f32 v139, v202, v139, v187
	v_fma_f32 v140, v202, v140, v188
	v_fma_f32 v141, v202, v141, v189
	v_mul_f32_e32 v138, 0x40135761, v138
	v_mul_f32_e32 v139, 0x40135761, v139
	v_mul_f32_e32 v140, 0x40135761, v140
	v_mul_f32_e32 v141, 0x40135761, v141
	v_exp_f32_e32 v138, v138
	v_exp_f32_e32 v139, v139
	v_exp_f32_e32 v140, v140
	v_exp_f32_e32 v141, v141
	s_nop 0
	v_add_f32_e32 v138, 1.0, v138
	v_add_f32_e32 v139, 1.0, v139
	v_add_f32_e32 v140, 1.0, v140
	v_add_f32_e32 v141, 1.0, v141
	v_rcp_f32_e32 v138, v138
	v_rcp_f32_e32 v139, v139
	v_rcp_f32_e32 v140, v140
	v_rcp_f32_e32 v141, v141
	s_nop 0
	v_fma_f32 v138, -2.0, v138, 1.0
	v_fma_f32 v139, -2.0, v139, 1.0
	v_fma_f32 v140, -2.0, v140, 1.0
	v_fma_f32 v141, -2.0, v141, 1.0
	v_add_f32_e32 v138, 1.0, v138
	v_add_f32_e32 v139, 1.0, v139
	v_add_f32_e32 v140, 1.0, v140
	v_add_f32_e32 v141, 1.0, v141
	v_mul_f32_e32 v186, 0.5, v186
	v_mul_f32_e32 v187, 0.5, v187
	v_mul_f32_e32 v188, 0.5, v188
	v_mul_f32_e32 v189, 0.5, v189
	v_mul_f32_e32 v186, v186, v138
	v_mul_f32_e32 v187, v187, v139
	v_mul_f32_e32 v188, v188, v140
	v_mul_f32_e32 v189, v189, v141
	v_add_f32_e32 v114, v229, v114
	v_add_f32_e32 v115, v230, v115
	v_add_f32_e32 v116, v231, v116
	v_add_f32_e32 v117, v232, v117
	v_mul_f32_e32 v114, v114, v186
	v_mul_f32_e32 v115, v115, v187
	v_mul_f32_e32 v116, v116, v188
	v_mul_f32_e32 v117, v117, v189
	v_cvt_pk_bf16_f32 v114, v114, v114
	v_cvt_pk_bf16_f32 v115, v115, v115
	v_cvt_pk_bf16_f32 v116, v116, v116
	v_cvt_pk_bf16_f32 v117, v117, v117
	v_mul_f32_e32 v138, v190, v190
	v_mul_f32_e32 v139, v191, v191
	v_mul_f32_e32 v140, v192, v192
	v_mul_f32_e32 v141, v193, v193
	v_mul_f32_e32 v138, v138, v190
	v_mul_f32_e32 v139, v139, v191
	v_mul_f32_e32 v140, v140, v192
	v_mul_f32_e32 v141, v141, v193
	v_fma_f32 v138, v202, v138, v190
	v_fma_f32 v139, v202, v139, v191
	v_fma_f32 v140, v202, v140, v192
	v_fma_f32 v141, v202, v141, v193
	v_mul_f32_e32 v138, 0x40135761, v138
	v_mul_f32_e32 v139, 0x40135761, v139
	v_mul_f32_e32 v140, 0x40135761, v140
	v_mul_f32_e32 v141, 0x40135761, v141
	v_exp_f32_e32 v138, v138
	v_exp_f32_e32 v139, v139
	v_exp_f32_e32 v140, v140
	v_exp_f32_e32 v141, v141
	s_nop 0
	v_add_f32_e32 v138, 1.0, v138
	v_add_f32_e32 v139, 1.0, v139
	v_add_f32_e32 v140, 1.0, v140
	v_add_f32_e32 v141, 1.0, v141
	v_rcp_f32_e32 v138, v138
	v_rcp_f32_e32 v139, v139
	v_rcp_f32_e32 v140, v140
	v_rcp_f32_e32 v141, v141
	s_nop 0
	v_fma_f32 v138, -2.0, v138, 1.0
	v_fma_f32 v139, -2.0, v139, 1.0
	v_fma_f32 v140, -2.0, v140, 1.0
	v_fma_f32 v141, -2.0, v141, 1.0
	v_add_f32_e32 v138, 1.0, v138
	v_add_f32_e32 v139, 1.0, v139
	v_add_f32_e32 v140, 1.0, v140
	v_add_f32_e32 v141, 1.0, v141
	v_mul_f32_e32 v190, 0.5, v190
	v_mul_f32_e32 v191, 0.5, v191
	v_mul_f32_e32 v192, 0.5, v192
; __device__ __forceinline__ void lru_tile(const Params& P, int chunk, int head, int pass, char* smem_raw) {
;     ...
;         for (int i = 0; i < 16; ++i) {
;           const int tl = (d == 0) ? (q * 16 + i) : (q * 16 + 15 - i);
;           const float a = sm_a[tl * 64 + ch], b = sm_b[tl * 64 + ch];
;           h = a * h + b;
;           const long row = row0 + sb * 64 + tl;
;           if (d == 0) {
;             hfw[row * 512 + gch] = h;
;           } else {
;             const float hfv = hfp[i];
;             const float g = gp[i];
;             const float tz = 0.7978845608028654f * (g + 0.044715f * g * g * g);
;             const float th = 1.f - 2.f * __builtin_amdgcn_rcpf(1.f + __expf(2.f * tz));
;             const float ge = 0.5f * g * (1.f + th);
;             P.cat[row * 1024 + gch] = f2bf((hfv + h) * ge);
;           }
;         }
	v_mul_f32_e32 v193, 0.5, v193
	v_mul_f32_e32 v190, v190, v138
	v_mul_f32_e32 v191, v191, v139
	v_mul_f32_e32 v192, v192, v140
	v_mul_f32_e32 v193, v193, v141
	v_add_f32_e32 v118, v233, v118
	v_add_f32_e32 v119, v234, v119
	v_add_f32_e32 v120, v235, v120
	v_add_f32_e32 v121, v236, v121
	v_mul_f32_e32 v118, v118, v190
	v_mul_f32_e32 v119, v119, v191
	v_mul_f32_e32 v120, v120, v192
	v_mul_f32_e32 v121, v121, v193
	v_cvt_pk_bf16_f32 v118, v118, v118
	v_cvt_pk_bf16_f32 v119, v119, v119
	v_cvt_pk_bf16_f32 v120, v120, v120
	v_cvt_pk_bf16_f32 v121, v121, v121
	s_lshl_b32 s0, s71, 18
	s_lshl_b32 s1, s56, 1
	s_add_u32 s0, s0, s1
	s_add_u32 s4, s12, s0
	s_addc_u32 s5, s13, 0
	global_store_short v237, v90, s[4:5]
	s_add_u32 s4, s4, 0x800
	s_addc_u32 s5, s5, 0
	global_store_short v237, v91, s[4:5]
	s_add_u32 s4, s4, 0x800
	s_addc_u32 s5, s5, 0
	global_store_short v237, v92, s[4:5]
	s_add_u32 s4, s4, 0x800
	s_addc_u32 s5, s5, 0
	global_store_short v237, v93, s[4:5]
	s_add_u32 s4, s4, 0x800
	s_addc_u32 s5, s5, 0
	global_store_short v237, v94, s[4:5]
	s_add_u32 s4, s4, 0x800
	s_addc_u32 s5, s5, 0
	global_store_short v237, v95, s[4:5]
	s_add_u32 s4, s4, 0x800
	s_addc_u32 s5, s5, 0
	global_store_short v237, v96, s[4:5]
	s_add_u32 s4, s4, 0x800
	s_addc_u32 s5, s5, 0
	global_store_short v237, v97, s[4:5]
	s_add_u32 s4, s4, 0x800
	s_addc_u32 s5, s5, 0
	global_store_short v237, v98, s[4:5]
	s_add_u32 s4, s4, 0x800
	s_addc_u32 s5, s5, 0
	global_store_short v237, v99, s[4:5]
	s_add_u32 s4, s4, 0x800
	s_addc_u32 s5, s5, 0
	global_store_short v237, v100, s[4:5]
	s_add_u32 s4, s4, 0x800
	s_addc_u32 s5, s5, 0
	global_store_short v237, v101, s[4:5]
	s_add_u32 s4, s4, 0x800
	s_addc_u32 s5, s5, 0
	global_store_short v237, v102, s[4:5]
	s_add_u32 s4, s4, 0x800
	s_addc_u32 s5, s5, 0
	global_store_short v237, v103, s[4:5]
	s_add_u32 s4, s4, 0x800
	s_addc_u32 s5, s5, 0
	global_store_short v237, v104, s[4:5]
	s_add_u32 s4, s4, 0x800
	s_addc_u32 s5, s5, 0
	global_store_short v237, v105, s[4:5]
	s_add_u32 s4, s4, 0x800
	s_addc_u32 s5, s5, 0
	global_store_short v237, v106, s[4:5]
	s_add_u32 s4, s4, 0x800
	s_addc_u32 s5, s5, 0
	global_store_short v237, v107, s[4:5]
	s_add_u32 s4, s4, 0x800
	s_addc_u32 s5, s5, 0
	global_store_short v237, v108, s[4:5]
	s_add_u32 s4, s4, 0x800
	s_addc_u32 s5, s5, 0
	global_store_short v237, v109, s[4:5]
	s_add_u32 s4, s4, 0x800
	s_addc_u32 s5, s5, 0
	global_store_short v237, v110, s[4:5]
	s_add_u32 s4, s4, 0x800
	s_addc_u32 s5, s5, 0
	global_store_short v237, v111, s[4:5]
	s_add_u32 s4, s4, 0x800
	s_addc_u32 s5, s5, 0
	global_store_short v237, v112, s[4:5]
	s_add_u32 s4, s4, 0x800
	s_addc_u32 s5, s5, 0
	global_store_short v237, v113, s[4:5]
	s_add_u32 s4, s4, 0x800
	s_addc_u32 s5, s5, 0
	global_store_short v237, v114, s[4:5]
	s_add_u32 s4, s4, 0x800
	s_addc_u32 s5, s5, 0
	global_store_short v237, v115, s[4:5]
	s_add_u32 s4, s4, 0x800
	s_addc_u32 s5, s5, 0
	global_store_short v237, v116, s[4:5]
	s_add_u32 s4, s4, 0x800
	s_addc_u32 s5, s5, 0
	global_store_short v237, v117, s[4:5]
	s_add_u32 s4, s4, 0x800
	s_addc_u32 s5, s5, 0
	global_store_short v237, v118, s[4:5]
	s_add_u32 s4, s4, 0x800
	s_addc_u32 s5, s5, 0
	global_store_short v237, v119, s[4:5]
	s_add_u32 s4, s4, 0x800
	s_addc_u32 s5, s5, 0
	global_store_short v237, v120, s[4:5]
	s_add_u32 s4, s4, 0x800
	s_addc_u32 s5, s5, 0
	global_store_short v237, v121, s[4:5]
	v_add_u32_e32 v89, s62, v89
	v_add_u32_e32 v130, s62, v130
	v_add_u32_e32 v131, s62, v131
	v_add_u32_e32 v133, s62, v133
	s_sub_u32 s62, 0, s62
	s_add_u32 s69, s69, 1
	s_cmp_lt_u32 s69, s70
	s_cbranch_scc1 .Lmy_lrub_tile
	s_waitcnt lgkmcnt(0)
	s_barrier
	s_branch .LBB0_680
